# GEMM K-loops: all per-segment s_setprio toggles removed (both halves run at priority 0); on top of all42
# speedup vs baseline: 1.0055x; 1.0024x over previous
; template <class Epi, class Sched, bool ALIGN_EPI = false, bool SP2 = false>
; __device__ __forceinline__ void gemm_phase(PG8_LAS unsigned char* lds, const Gemm g, const Sched& S, const Epi& E, const int wid) {
;     ...
;         const bool has_next = S.next(ui + 1, nxt);
;         const char* nA = has_next ? (const char*)g.A + (size_t)nxt.pm * tstep : cA; const char* nB = has_next ? (const char*)g.Bt + (size_t)nxt.pn * tstep : cB;
;         for (int t = 0; t < nt; t += 2) {
;             const bool last = (t == nt - 2);
;             const char* a1 = cA + (size_t)(t + 1) * kstep;
;             const char* a2 = last ? nA : cA + (size_t)(t + 2) * kstep; const char* b2 = last ? nB : cB + (size_t)(t + 2) * kstep;
;             const char* a3 = a2 + kstep; const char* b3 = b2 + kstep;
.LBB0_268:
	s_ashr_i32 s15, s14, 31
	s_lshl_b64 s[16:17], s[14:15], 19
	s_add_u32 s16, s80, s16
	s_addc_u32 s17, s81, s17
	s_and_b64 s[18:19], s[4:5], exec
	s_cselect_b32 s15, s17, s23
	s_cselect_b32 s44, s16, s22
	s_ashr_i32 s13, s12, 31
	s_lshl_b64 s[18:19], s[12:13], 19
	s_add_u32 s18, s10, s18
	s_addc_u32 s19, s11, s19
	s_and_b64 s[26:27], s[4:5], exec
	s_cselect_b32 s13, s19, s25
	s_cselect_b32 s45, s18, s24
	s_add_u32 s22, s22, 0x40080
	s_addc_u32 s23, s23, 0
	s_add_u32 s46, s24, 0x100

; template <class Epi, class Sched, bool ALIGN_EPI = false, bool SP2 = false>
; __device__ __forceinline__ void gemm_phase(PG8_LAS unsigned char* lds, const Gemm g, const Sched& S, const Epi& E, const int wid) {
;     ...
;         const bool has_next = S.next(ui + 1, nxt);
;         const char* nA = has_next ? (const char*)g.A + (size_t)nxt.pm * tstep : cA; const char* nB = has_next ? (const char*)g.Bt + (size_t)nxt.pn * tstep : cB;
;         for (int t = 0; t < nt; t += 2) {
;             const bool last = (t == nt - 2);
;             const char* a1 = cA + (size_t)(t + 1) * kstep;
;             const char* a2 = last ? nA : cA + (size_t)(t + 2) * kstep; const char* b2 = last ? nB : cB + (size_t)(t + 2) * kstep;
;             const char* a3 = a2 + kstep; const char* b3 = b2 + kstep;
	s_addc_u32 s47, s25, 0
	s_mov_b32 s48, -2


; #define PG8_STAGE(bufoff, gbase, voff) do { _Pragma("unroll") for (int _i = 0; _i < 2; ++_i) \
;         __builtin_amdgcn_global_load_lds((const unsigned*)((const char*)(gbase) + (voff)[_i]), (PG8_LAS unsigned*)(lds + (bufoff) + ldsw + _i * 8192), 16, 0, 0); } while (0)
; #define PG8_LDA(dst, b, h) do { _Pragma("unroll") for (int m = 0; m < 4; ++m) _Pragma("unroll") for (int k = 0; k < 2; ++k) dst[m][k] = *(const PG8_LAS bf16x8*)(lds + PG8_SA(b, h) + aoff + m * 2048 + k * 1024); } while (0)
; #define PG8_LDB(dst, b, h) do { _Pragma("unroll") for (int n = 0; n < 2; ++n) _Pragma("unroll") for (int k = 0; k < 2; ++k) dst[n][k] = *(const PG8_LAS bf16x8*)(lds + PG8_SB(b, h) + boff + n * 2048 + k * 1024); } while (0)
; #define PG8_MMA(ai, bj, At, Bt) do { __builtin_amdgcn_s_setprio(1); _Pragma("unroll") for (int m = 0; m < 4; ++m) _Pragma("unroll") for (int n = 0; n < 2; ++n) _Pragma("unroll") for (int k = 0; k < 2; ++k) \
;         acc[ai][bj][m][n] = __builtin_amdgcn_mfma_f32_16x16x32_bf16(Bt[n][k], At[m][k], acc[ai][bj][m][n], 0, 0, 0); __builtin_amdgcn_s_setprio(0); } while (0)
; #define PG8_WAIT_V(n) asm volatile("s_waitcnt vmcnt(" #n ")" ::: "memory")
; #define PG8_WAIT_L(n) asm volatile("s_waitcnt lgkmcnt(" #n ")" ::: "memory")
; #define PG8_BAR __builtin_amdgcn_s_barrier()
; #define PG8_SCHED __builtin_amdgcn_sched_barrier(0)
; template <class Epi, class Sched, bool ALIGN_EPI = false, bool SP2 = false>
; __device__ __forceinline__ void gemm_phase(PG8_LAS unsigned char* lds, const Gemm g, const Sched& S, const Epi& E, const int wid) {
;     ...
;             PG8_LDB(B0, 0, 0); PG8_LDB(B1, 0, 1); PG8_SCHED; PG8_LDA(At, 0, 0); PG8_STAGE(PG8_SA(1, 1), a1 + hstep, voffA);
;             PG8_WAIT_V(8); PG8_WAIT_L(0); PG8_BAR; PG8_MMA(0, 0, At, B0); PG8_MMA(0, 1, At, B1); PG8_BAR; PG8_SCHED;
;             PG8_LDA(At, 0, 1); PG8_STAGE(PG8_SB(0, 0), b2, voffB); PG8_STAGE(PG8_SB(0, 1), b2 + hstep, voffB); PG8_STAGE(PG8_SA(0, 0), a2, voffA);
;             PG8_WAIT_V(8); PG8_WAIT_L(0); PG8_BAR; PG8_MMA(1, 0, At, B0); PG8_MMA(1, 1, At, B1); PG8_BAR; PG8_SCHED;
	ds_read_b128 v[144:147], v151
	ds_read_b128 v[154:157], v151 offset:1024
	ds_read_b128 v[158:161], v151 offset:2048
	ds_read_b128 v[162:165], v151 offset:3072
	ds_read_b128 v[166:169], v152
	ds_read_b128 v[170:173], v152 offset:1024
	ds_read_b128 v[174:177], v152 offset:2048
	ds_read_b128 v[178:181], v152 offset:3072
	s_add_u32 s24, s22, 0xfffc0080
	s_addc_u32 s25, s23, -1
	s_cmp_eq_u32 s48, 12
	s_cselect_b32 s27, s15, s25
	s_cselect_b32 s26, s44, s24
	s_cselect_b32 s25, s13, s47
	s_cselect_b32 s24, s45, s46
	v_lshl_add_u64 v[206:207], s[22:23], 0, v[136:137]
	s_add_i32 m0, s21, 0xc000
	ds_read_b128 v[182:185], v153
	ds_read_b128 v[186:189], v153 offset:1024
	ds_read_b128 v[190:193], v153 offset:2048
	ds_read_b128 v[194:197], v153 offset:3072
	ds_read_b128 v[198:201], v153 offset:4096
	ds_read_b128 v[202:205], v153 offset:5120
	ds_read_b128 v[212:215], v153 offset:6144
	ds_read_b128 v[216:219], v153 offset:7168
	global_load_lds_dwordx4 v[206:207], off
	v_lshl_add_u64 v[206:207], s[22:23], 0, v[138:139]
	s_add_i32 m0, s21, 0xe000
	s_nop 0
	global_load_lds_dwordx4 v[206:207], off
	s_waitcnt vmcnt(8)
	s_waitcnt lgkmcnt(0)
	s_barrier
	s_waitcnt lgkmcnt(0)
	v_mfma_f32_16x16x32_bf16 v[124:127], v[144:147], v[182:185], 0
	v_mfma_f32_16x16x32_bf16 v[116:119], v[158:161], v[182:185], 0
	v_mfma_f32_16x16x32_bf16 v[108:111], v[144:147], v[190:193], 0
	v_mfma_f32_16x16x32_bf16 v[100:103], v[158:161], v[190:193], 0
	v_mfma_f32_16x16x32_bf16 v[92:95], v[144:147], v[198:201], 0
	v_mfma_f32_16x16x32_bf16 v[84:87], v[158:161], v[198:201], 0
	v_mfma_f32_16x16x32_bf16 v[76:79], v[144:147], v[212:215], 0
	v_mfma_f32_16x16x32_bf16 v[68:71], v[158:161], v[212:215], 0
	v_mfma_f32_16x16x32_bf16 v[124:127], v[154:157], v[186:189], v[124:127]
	v_mfma_f32_16x16x32_bf16 v[116:119], v[162:165], v[186:189], v[116:119]
	v_mfma_f32_16x16x32_bf16 v[108:111], v[154:157], v[194:197], v[108:111]
	v_mfma_f32_16x16x32_bf16 v[100:103], v[162:165], v[194:197], v[100:103]
	v_mfma_f32_16x16x32_bf16 v[92:95], v[154:157], v[202:205], v[92:95]
	v_mfma_f32_16x16x32_bf16 v[84:87], v[162:165], v[202:205], v[84:87]
	v_mfma_f32_16x16x32_bf16 v[76:79], v[154:157], v[216:219], v[76:79]
	v_mfma_f32_16x16x32_bf16 v[68:71], v[162:165], v[216:219], v[68:71]
	v_mfma_f32_16x16x32_bf16 v[120:123], v[166:169], v[182:185], 0
	v_mfma_f32_16x16x32_bf16 v[112:115], v[174:177], v[182:185], 0
	v_mfma_f32_16x16x32_bf16 v[104:107], v[166:169], v[190:193], 0
	v_mfma_f32_16x16x32_bf16 v[96:99], v[174:177], v[190:193], 0
	v_mfma_f32_16x16x32_bf16 v[88:91], v[166:169], v[198:201], 0
	v_mfma_f32_16x16x32_bf16 v[80:83], v[174:177], v[198:201], 0
	v_mfma_f32_16x16x32_bf16 v[72:75], v[166:169], v[212:215], 0
	v_mfma_f32_16x16x32_bf16 v[64:67], v[174:177], v[212:215], 0
	v_mfma_f32_16x16x32_bf16 v[120:123], v[170:173], v[186:189], v[120:123]
	v_mfma_f32_16x16x32_bf16 v[112:115], v[178:181], v[186:189], v[112:115]
	v_mfma_f32_16x16x32_bf16 v[104:107], v[170:173], v[194:197], v[104:107]
	v_mfma_f32_16x16x32_bf16 v[96:99], v[178:181], v[194:197], v[96:99]
	v_mfma_f32_16x16x32_bf16 v[88:91], v[170:173], v[202:205], v[88:91]
	v_mfma_f32_16x16x32_bf16 v[80:83], v[178:181], v[202:205], v[80:83]
	v_mfma_f32_16x16x32_bf16 v[72:75], v[170:173], v[216:219], v[72:75]
	v_mfma_f32_16x16x32_bf16 v[64:67], v[178:181], v[216:219], v[64:67]
	s_barrier
	s_add_i32 s49, s40, s9
	v_lshl_add_u64 v[206:207], s[24:25], 0, v[132:133]
	s_mov_b32 m0, s49
	ds_read_b128 v[182:185], v153 offset:16384
	ds_read_b128 v[186:189], v153 offset:17408
	ds_read_b128 v[190:193], v153 offset:18432
	ds_read_b128 v[194:197], v153 offset:19456
	ds_read_b128 v[198:201], v153 offset:20480
	ds_read_b128 v[202:205], v153 offset:21504
	ds_read_b128 v[212:215], v153 offset:22528
	ds_read_b128 v[216:219], v153 offset:23552
	global_load_lds_dwordx4 v[206:207], off
	s_add_i32 m0, s49, 0x2000
	s_add_u32 s50, s24, 0x40000
	v_lshl_add_u64 v[220:221], s[24:25], 0, v[128:129]
	s_addc_u32 s51, s25, 0
	s_add_i32 s49, s41, s9
	global_load_lds_dwordx4 v[220:221], off
	v_lshl_add_u64 v[222:223], s[50:51], 0, v[132:133]
	s_mov_b32 m0, s49
	v_lshl_add_u64 v[224:225], s[26:27], 0, v[130:131]
	global_load_lds_dwordx4 v[222:223], off
	v_lshl_add_u64 v[222:223], s[50:51], 0, v[128:129]
	s_add_i32 m0, s49, 0x2000
	s_nop 0
	global_load_lds_dwordx4 v[222:223], off
	v_lshl_add_u64 v[222:223], s[26:27], 0, v[134:135]
	s_mov_b32 m0, s21
	s_nop 0
	global_load_lds_dwordx4 v[222:223], off
	s_mov_b32 m0, s30
	s_nop 0
	global_load_lds_dwordx4 v[224:225], off
	s_waitcnt vmcnt(8)
	s_waitcnt lgkmcnt(0)
	s_barrier
	s_waitcnt lgkmcnt(0)
	v_mfma_f32_16x16x32_bf16 v[60:63], v[144:147], v[182:185], 0
	v_mfma_f32_16x16x32_bf16 v[52:55], v[158:161], v[182:185], 0
	v_mfma_f32_16x16x32_bf16 v[44:47], v[144:147], v[190:193], 0
	v_mfma_f32_16x16x32_bf16 v[36:39], v[158:161], v[190:193], 0
	v_mfma_f32_16x16x32_bf16 v[28:31], v[144:147], v[198:201], 0
	v_mfma_f32_16x16x32_bf16 v[20:23], v[158:161], v[198:201], 0
	v_mfma_f32_16x16x32_bf16 v[12:15], v[144:147], v[212:215], 0
	v_mfma_f32_16x16x32_bf16 v[4:7], v[158:161], v[212:215], 0
	v_mfma_f32_16x16x32_bf16 v[60:63], v[154:157], v[186:189], v[60:63]
	v_mfma_f32_16x16x32_bf16 v[52:55], v[162:165], v[186:189], v[52:55]
	v_mfma_f32_16x16x32_bf16 v[44:47], v[154:157], v[194:197], v[44:47]
	v_mfma_f32_16x16x32_bf16 v[36:39], v[162:165], v[194:197], v[36:39]
	v_mfma_f32_16x16x32_bf16 v[28:31], v[154:157], v[202:205], v[28:31]
	v_mfma_f32_16x16x32_bf16 v[20:23], v[162:165], v[202:205], v[20:23]
	v_mfma_f32_16x16x32_bf16 v[12:15], v[154:157], v[216:219], v[12:15]
	v_mfma_f32_16x16x32_bf16 v[4:7], v[162:165], v[216:219], v[4:7]
	v_mfma_f32_16x16x32_bf16 v[56:59], v[166:169], v[182:185], 0
	v_mfma_f32_16x16x32_bf16 v[48:51], v[174:177], v[182:185], 0
	v_mfma_f32_16x16x32_bf16 v[40:43], v[166:169], v[190:193], 0
	v_mfma_f32_16x16x32_bf16 v[32:35], v[174:177], v[190:193], 0
	v_mfma_f32_16x16x32_bf16 v[24:27], v[166:169], v[198:201], 0
	v_mfma_f32_16x16x32_bf16 v[16:19], v[174:177], v[198:201], 0
	v_mfma_f32_16x16x32_bf16 v[8:11], v[166:169], v[212:215], 0
	v_mfma_f32_16x16x32_bf16 v[0:3], v[174:177], v[212:215], 0
	v_mfma_f32_16x16x32_bf16 v[56:59], v[170:173], v[186:189], v[56:59]
	v_mfma_f32_16x16x32_bf16 v[48:51], v[178:181], v[186:189], v[48:51]
	v_mfma_f32_16x16x32_bf16 v[40:43], v[170:173], v[194:197], v[40:43]
	v_mfma_f32_16x16x32_bf16 v[32:35], v[178:181], v[194:197], v[32:35]
	v_mfma_f32_16x16x32_bf16 v[24:27], v[170:173], v[202:205], v[24:27]
	v_mfma_f32_16x16x32_bf16 v[16:19], v[178:181], v[202:205], v[16:19]
	v_mfma_f32_16x16x32_bf16 v[8:11], v[170:173], v[216:219], v[8:11]
	v_mfma_f32_16x16x32_bf16 v[0:3], v[178:181], v[216:219], v[0:3]
	s_barrier
; #define PG8_STAGE(bufoff, gbase, voff) do { _Pragma("unroll") for (int _i = 0; _i < 2; ++_i) \
;         __builtin_amdgcn_global_load_lds((const unsigned*)((const char*)(gbase) + (voff)[_i]), (PG8_LAS unsigned*)(lds + (bufoff) + ldsw + _i * 8192), 16, 0, 0); } while (0)
; #define PG8_LDA(dst, b, h) do { _Pragma("unroll") for (int m = 0; m < 4; ++m) _Pragma("unroll") for (int k = 0; k < 2; ++k) dst[m][k] = *(const PG8_LAS bf16x8*)(lds + PG8_SA(b, h) + aoff + m * 2048 + k * 1024); } while (0)
; #define PG8_LDB(dst, b, h) do { _Pragma("unroll") for (int n = 0; n < 2; ++n) _Pragma("unroll") for (int k = 0; k < 2; ++k) dst[n][k] = *(const PG8_LAS bf16x8*)(lds + PG8_SB(b, h) + boff + n * 2048 + k * 1024); } while (0)
; #define PG8_MMA(ai, bj, At, Bt) do { __builtin_amdgcn_s_setprio(1); _Pragma("unroll") for (int m = 0; m < 4; ++m) _Pragma("unroll") for (int n = 0; n < 2; ++n) _Pragma("unroll") for (int k = 0; k < 2; ++k) \
;         acc[ai][bj][m][n] = __builtin_amdgcn_mfma_f32_16x16x32_bf16(Bt[n][k], At[m][k], acc[ai][bj][m][n], 0, 0, 0); __builtin_amdgcn_s_setprio(0); } while (0)
; #define PG8_WAIT_V(n) asm volatile("s_waitcnt vmcnt(" #n ")" ::: "memory")
; #define PG8_WAIT_L(n) asm volatile("s_waitcnt lgkmcnt(" #n ")" ::: "memory")
; #define PG8_BAR __builtin_amdgcn_s_barrier()
; #define PG8_SCHED __builtin_amdgcn_sched_barrier(0)
; template <class Epi, class Sched, bool ALIGN_EPI = false, bool SP2 = false>
; __device__ __forceinline__ void gemm_phase(PG8_LAS unsigned char* lds, const Gemm g, const Sched& S, const Epi& E, const int wid) {
;     ...
;             PG8_LDB(B0, 1, 0); PG8_LDB(B1, 1, 1); PG8_SCHED; PG8_LDA(At, 1, 0); PG8_STAGE(PG8_SA(0, 1), a2 + hstep, voffA);
;             PG8_WAIT_V(8); PG8_WAIT_L(0); PG8_BAR; PG8_MMA(0, 0, At, B0); PG8_MMA(0, 1, At, B1); PG8_BAR; PG8_SCHED;
;             PG8_LDA(At, 1, 1); PG8_STAGE(PG8_SB(1, 0), b3, voffB); PG8_STAGE(PG8_SB(1, 1), b3 + hstep, voffB); PG8_STAGE(PG8_SA(1, 0), a3, voffA);
;             PG8_WAIT_V(8); PG8_WAIT_L(0); PG8_BAR; PG8_MMA(1, 0, At, B0); PG8_MMA(1, 1, At, B1); PG8_BAR; PG8_SCHED;
	s_add_i32 s49, 0, 0x18000
	s_add_i32 s50, 0, 0x1c000
	v_add_u32_e32 v162, s49, v149
	v_add_u32_e32 v178, s50, v149
	ds_read_b128 v[144:147], v162
	ds_read_b128 v[154:157], v162 offset:1024
	ds_read_b128 v[158:161], v162 offset:2048
	ds_read_b128 v[162:165], v162 offset:3072
	ds_read_b128 v[166:169], v178
	ds_read_b128 v[170:173], v178 offset:1024
	ds_read_b128 v[174:177], v178 offset:2048
	ds_read_b128 v[178:181], v178 offset:3072
	s_add_u32 s26, s26, 0x40000
	s_addc_u32 s27, s27, 0
	s_mov_b32 m0, s31
	v_lshl_add_u64 v[226:227], s[26:27], 0, v[134:135]
	ds_read_b128 v[182:185], v153 offset:32768
	ds_read_b128 v[186:189], v153 offset:33792
	ds_read_b128 v[190:193], v153 offset:34816
	ds_read_b128 v[194:197], v153 offset:35840
	ds_read_b128 v[198:201], v153 offset:36864
	ds_read_b128 v[202:205], v153 offset:37888
	ds_read_b128 v[212:215], v153 offset:38912
	ds_read_b128 v[216:219], v153 offset:39936
	global_load_lds_dwordx4 v[226:227], off
	v_lshl_add_u64 v[226:227], s[26:27], 0, v[130:131]
	s_mov_b32 m0, s33
	s_nop 0
	global_load_lds_dwordx4 v[226:227], off
	s_waitcnt vmcnt(8)
	s_waitcnt lgkmcnt(0)
	s_barrier
	s_waitcnt lgkmcnt(0)
	v_mfma_f32_16x16x32_bf16 v[124:127], v[144:147], v[182:185], v[124:127]
	v_mfma_f32_16x16x32_bf16 v[116:119], v[158:161], v[182:185], v[116:119]
	v_mfma_f32_16x16x32_bf16 v[108:111], v[144:147], v[190:193], v[108:111]
	v_mfma_f32_16x16x32_bf16 v[100:103], v[158:161], v[190:193], v[100:103]
	v_mfma_f32_16x16x32_bf16 v[92:95], v[144:147], v[198:201], v[92:95]
	v_mfma_f32_16x16x32_bf16 v[84:87], v[158:161], v[198:201], v[84:87]
	v_mfma_f32_16x16x32_bf16 v[76:79], v[144:147], v[212:215], v[76:79]
	v_mfma_f32_16x16x32_bf16 v[68:71], v[158:161], v[212:215], v[68:71]
	v_mfma_f32_16x16x32_bf16 v[124:127], v[154:157], v[186:189], v[124:127]
	v_mfma_f32_16x16x32_bf16 v[116:119], v[162:165], v[186:189], v[116:119]
	v_mfma_f32_16x16x32_bf16 v[108:111], v[154:157], v[194:197], v[108:111]
	v_mfma_f32_16x16x32_bf16 v[100:103], v[162:165], v[194:197], v[100:103]
	v_mfma_f32_16x16x32_bf16 v[92:95], v[154:157], v[202:205], v[92:95]
	v_mfma_f32_16x16x32_bf16 v[84:87], v[162:165], v[202:205], v[84:87]
	v_mfma_f32_16x16x32_bf16 v[76:79], v[154:157], v[216:219], v[76:79]
	v_mfma_f32_16x16x32_bf16 v[68:71], v[162:165], v[216:219], v[68:71]
	v_mfma_f32_16x16x32_bf16 v[120:123], v[166:169], v[182:185], v[120:123]
	v_mfma_f32_16x16x32_bf16 v[112:115], v[174:177], v[182:185], v[112:115]
	v_mfma_f32_16x16x32_bf16 v[104:107], v[166:169], v[190:193], v[104:107]
	v_mfma_f32_16x16x32_bf16 v[96:99], v[174:177], v[190:193], v[96:99]
	v_mfma_f32_16x16x32_bf16 v[88:91], v[166:169], v[198:201], v[88:91]
	v_mfma_f32_16x16x32_bf16 v[80:83], v[174:177], v[198:201], v[80:83]
	v_mfma_f32_16x16x32_bf16 v[72:75], v[166:169], v[212:215], v[72:75]
	v_mfma_f32_16x16x32_bf16 v[64:67], v[174:177], v[212:215], v[64:67]
	v_mfma_f32_16x16x32_bf16 v[120:123], v[170:173], v[186:189], v[120:123]
	v_mfma_f32_16x16x32_bf16 v[112:115], v[178:181], v[186:189], v[112:115]
	v_mfma_f32_16x16x32_bf16 v[104:107], v[170:173], v[194:197], v[104:107]
	v_mfma_f32_16x16x32_bf16 v[96:99], v[178:181], v[194:197], v[96:99]
	v_mfma_f32_16x16x32_bf16 v[88:91], v[170:173], v[202:205], v[88:91]
	v_mfma_f32_16x16x32_bf16 v[80:83], v[178:181], v[202:205], v[80:83]
	v_mfma_f32_16x16x32_bf16 v[72:75], v[170:173], v[216:219], v[72:75]
	v_mfma_f32_16x16x32_bf16 v[64:67], v[178:181], v[216:219], v[64:67]
	s_barrier
	s_add_i32 s26, s49, s9
	v_lshl_add_u64 v[206:207], v[206:207], 0, s[6:7]
	s_mov_b32 m0, s26
	ds_read_b128 v[182:185], v153 offset:49152
	ds_read_b128 v[186:189], v153 offset:50176
	ds_read_b128 v[190:193], v153 offset:51200
	ds_read_b128 v[194:197], v153 offset:52224
	ds_read_b128 v[198:201], v153 offset:53248
	ds_read_b128 v[202:205], v153 offset:54272
	ds_read_b128 v[212:215], v153 offset:55296
	ds_read_b128 v[216:219], v153 offset:56320
	global_load_lds_dwordx4 v[206:207], off
	s_add_i32 m0, s26, 0x2000
	s_add_u32 s24, s24, 0x40080
	v_lshl_add_u64 v[206:207], v[220:221], 0, s[6:7]
	s_addc_u32 s25, s25, 0
	s_add_i32 s26, s50, s9
	global_load_lds_dwordx4 v[206:207], off
	v_lshl_add_u64 v[206:207], s[24:25], 0, v[132:133]
	s_mov_b32 m0, s26
	s_nop 0
	global_load_lds_dwordx4 v[206:207], off
	v_lshl_add_u64 v[206:207], s[24:25], 0, v[128:129]
	s_add_i32 m0, s26, 0x2000
	s_nop 0
	global_load_lds_dwordx4 v[206:207], off
	v_lshl_add_u64 v[206:207], v[222:223], 0, s[6:7]
	s_mov_b32 m0, s38
	s_nop 0
	global_load_lds_dwordx4 v[206:207], off
	v_lshl_add_u64 v[206:207], v[224:225], 0, s[6:7]
	s_mov_b32 m0, s39
	s_nop 0
	global_load_lds_dwordx4 v[206:207], off
	s_waitcnt vmcnt(8)
	s_waitcnt lgkmcnt(0)
	s_barrier
; #define PG8_STAGE(bufoff, gbase, voff) do { _Pragma("unroll") for (int _i = 0; _i < 2; ++_i) \
;         __builtin_amdgcn_global_load_lds((const unsigned*)((const char*)(gbase) + (voff)[_i]), (PG8_LAS unsigned*)(lds + (bufoff) + ldsw + _i * 8192), 16, 0, 0); } while (0)
; #define PG8_LDA(dst, b, h) do { _Pragma("unroll") for (int m = 0; m < 4; ++m) _Pragma("unroll") for (int k = 0; k < 2; ++k) dst[m][k] = *(const PG8_LAS bf16x8*)(lds + PG8_SA(b, h) + aoff + m * 2048 + k * 1024); } while (0)
; #define PG8_LDB(dst, b, h) do { _Pragma("unroll") for (int n = 0; n < 2; ++n) _Pragma("unroll") for (int k = 0; k < 2; ++k) dst[n][k] = *(const PG8_LAS bf16x8*)(lds + PG8_SB(b, h) + boff + n * 2048 + k * 1024); } while (0)
; #define PG8_MMA(ai, bj, At, Bt) do { __builtin_amdgcn_s_setprio(1); _Pragma("unroll") for (int m = 0; m < 4; ++m) _Pragma("unroll") for (int n = 0; n < 2; ++n) _Pragma("unroll") for (int k = 0; k < 2; ++k) \
;         acc[ai][bj][m][n] = __builtin_amdgcn_mfma_f32_16x16x32_bf16(Bt[n][k], At[m][k], acc[ai][bj][m][n], 0, 0, 0); __builtin_amdgcn_s_setprio(0); } while (0)
; #define PG8_BAR __builtin_amdgcn_s_barrier()
; template <class Epi, class Sched, bool ALIGN_EPI = false, bool SP2 = false>
; __device__ __forceinline__ void gemm_phase(PG8_LAS unsigned char* lds, const Gemm g, const Sched& S, const Epi& E, const int wid) {
;     ...
;             PG8_LDB(B0, 0, 0); PG8_LDB(B1, 0, 1); PG8_SCHED; PG8_LDA(At, 0, 0); PG8_STAGE(PG8_SA(1, 1), a1 + hstep, voffA);
;             PG8_WAIT_V(8); PG8_WAIT_L(0); PG8_BAR; PG8_MMA(0, 0, At, B0); PG8_MMA(0, 1, At, B1); PG8_BAR; PG8_SCHED;
;             PG8_LDA(At, 0, 1); PG8_STAGE(PG8_SB(0, 0), b2, voffB); PG8_STAGE(PG8_SB(0, 1), b2 + hstep, voffB); PG8_STAGE(PG8_SA(0, 0), a2, voffA);
;             PG8_WAIT_V(8); PG8_WAIT_L(0); PG8_BAR; PG8_MMA(1, 0, At, B0); PG8_MMA(1, 1, At, B1); PG8_BAR; PG8_SCHED;
;             PG8_LDB(B0, 1, 0); PG8_LDB(B1, 1, 1); PG8_SCHED; PG8_LDA(At, 1, 0); PG8_STAGE(PG8_SA(0, 1), a2 + hstep, voffA);
;             PG8_WAIT_V(8); PG8_WAIT_L(0); PG8_BAR; PG8_MMA(0, 0, At, B0); PG8_MMA(0, 1, At, B1); PG8_BAR; PG8_SCHED;
;             PG8_LDA(At, 1, 1); PG8_STAGE(PG8_SB(1, 0), b3, voffB); PG8_STAGE(PG8_SB(1, 1), b3 + hstep, voffB); PG8_STAGE(PG8_SA(1, 0), a3, voffA);
;             PG8_WAIT_V(8); PG8_WAIT_L(0); PG8_BAR; PG8_MMA(1, 0, At, B0); PG8_MMA(1, 1, At, B1); PG8_BAR; PG8_SCHED;
	s_waitcnt lgkmcnt(0)
	v_mfma_f32_16x16x32_bf16 v[60:63], v[144:147], v[182:185], v[60:63]
	v_mfma_f32_16x16x32_bf16 v[52:55], v[158:161], v[182:185], v[52:55]
	v_mfma_f32_16x16x32_bf16 v[44:47], v[144:147], v[190:193], v[44:47]
	v_mfma_f32_16x16x32_bf16 v[36:39], v[158:161], v[190:193], v[36:39]
	v_mfma_f32_16x16x32_bf16 v[28:31], v[144:147], v[198:201], v[28:31]
	v_mfma_f32_16x16x32_bf16 v[20:23], v[158:161], v[198:201], v[20:23]
	v_mfma_f32_16x16x32_bf16 v[12:15], v[144:147], v[212:215], v[12:15]
	v_mfma_f32_16x16x32_bf16 v[4:7], v[158:161], v[212:215], v[4:7]
	v_mfma_f32_16x16x32_bf16 v[60:63], v[154:157], v[186:189], v[60:63]
	v_mfma_f32_16x16x32_bf16 v[52:55], v[162:165], v[186:189], v[52:55]
	v_mfma_f32_16x16x32_bf16 v[44:47], v[154:157], v[194:197], v[44:47]
	v_mfma_f32_16x16x32_bf16 v[36:39], v[162:165], v[194:197], v[36:39]
	v_mfma_f32_16x16x32_bf16 v[28:31], v[154:157], v[202:205], v[28:31]
	v_mfma_f32_16x16x32_bf16 v[20:23], v[162:165], v[202:205], v[20:23]
	v_mfma_f32_16x16x32_bf16 v[12:15], v[154:157], v[216:219], v[12:15]
	v_mfma_f32_16x16x32_bf16 v[4:7], v[162:165], v[216:219], v[4:7]
	v_mfma_f32_16x16x32_bf16 v[56:59], v[166:169], v[182:185], v[56:59]
	v_mfma_f32_16x16x32_bf16 v[48:51], v[174:177], v[182:185], v[48:51]
	v_mfma_f32_16x16x32_bf16 v[40:43], v[166:169], v[190:193], v[40:43]
	v_mfma_f32_16x16x32_bf16 v[32:35], v[174:177], v[190:193], v[32:35]
	v_mfma_f32_16x16x32_bf16 v[24:27], v[166:169], v[198:201], v[24:27]
	v_mfma_f32_16x16x32_bf16 v[16:19], v[174:177], v[198:201], v[16:19]
	v_mfma_f32_16x16x32_bf16 v[8:11], v[166:169], v[212:215], v[8:11]
	v_mfma_f32_16x16x32_bf16 v[0:3], v[174:177], v[212:215], v[0:3]
	v_mfma_f32_16x16x32_bf16 v[56:59], v[170:173], v[186:189], v[56:59]
	v_mfma_f32_16x16x32_bf16 v[48:51], v[178:181], v[186:189], v[48:51]
	v_mfma_f32_16x16x32_bf16 v[40:43], v[170:173], v[194:197], v[40:43]
	v_mfma_f32_16x16x32_bf16 v[32:35], v[178:181], v[194:197], v[32:35]
	v_mfma_f32_16x16x32_bf16 v[24:27], v[170:173], v[202:205], v[24:27]
	v_mfma_f32_16x16x32_bf16 v[16:19], v[178:181], v[202:205], v[16:19]
	v_mfma_f32_16x16x32_bf16 v[8:11], v[170:173], v[216:219], v[8:11]
	v_mfma_f32_16x16x32_bf16 v[0:3], v[178:181], v[216:219], v[0:3]
	s_barrier
	s_add_i32 s48, s48, 2
	s_add_u32 s22, s22, 0x100
	s_addc_u32 s23, s23, 0
	s_add_u32 s46, s46, 0x100
	s_addc_u32 s47, s47, 0
	s_cmp_gt_u32 s48, 13
	s_cbranch_scc0 .LBB0_269
	s_branch .Lkp_exit_0
.LBB0_269:
	ds_read_b128 v[144:147], v151
	ds_read_b128 v[154:157], v151 offset:1024
	ds_read_b128 v[158:161], v151 offset:2048
	ds_read_b128 v[162:165], v151 offset:3072
	ds_read_b128 v[166:169], v152
	ds_read_b128 v[170:173], v152 offset:1024
	ds_read_b128 v[174:177], v152 offset:2048
	ds_read_b128 v[178:181], v152 offset:3072
	s_add_u32 s24, s22, 0xfffc0080
	s_addc_u32 s25, s23, -1
	s_cmp_eq_u32 s48, 12
	s_cselect_b32 s27, s15, s25
	s_cselect_b32 s26, s44, s24
	s_cselect_b32 s25, s13, s47
	s_cselect_b32 s24, s45, s46
	v_lshl_add_u64 v[206:207], s[22:23], 0, v[136:137]
	s_add_i32 m0, s21, 0xc000
	ds_read_b128 v[182:185], v153
	ds_read_b128 v[186:189], v153 offset:1024
	ds_read_b128 v[190:193], v153 offset:2048
	ds_read_b128 v[194:197], v153 offset:3072
	ds_read_b128 v[198:201], v153 offset:4096
	ds_read_b128 v[202:205], v153 offset:5120
	ds_read_b128 v[212:215], v153 offset:6144
	ds_read_b128 v[216:219], v153 offset:7168
	global_load_lds_dwordx4 v[206:207], off
	v_lshl_add_u64 v[206:207], s[22:23], 0, v[138:139]
	s_add_i32 m0, s21, 0xe000
	s_nop 0
	global_load_lds_dwordx4 v[206:207], off
	s_waitcnt vmcnt(8)
	s_waitcnt lgkmcnt(0)
	s_barrier
	s_waitcnt lgkmcnt(0)
	v_mfma_f32_16x16x32_bf16 v[124:127], v[144:147], v[182:185], v[124:127]
	v_mfma_f32_16x16x32_bf16 v[116:119], v[158:161], v[182:185], v[116:119]
	v_mfma_f32_16x16x32_bf16 v[108:111], v[144:147], v[190:193], v[108:111]
	v_mfma_f32_16x16x32_bf16 v[100:103], v[158:161], v[190:193], v[100:103]
	v_mfma_f32_16x16x32_bf16 v[92:95], v[144:147], v[198:201], v[92:95]
	v_mfma_f32_16x16x32_bf16 v[84:87], v[158:161], v[198:201], v[84:87]
	v_mfma_f32_16x16x32_bf16 v[76:79], v[144:147], v[212:215], v[76:79]
	v_mfma_f32_16x16x32_bf16 v[68:71], v[158:161], v[212:215], v[68:71]
	v_mfma_f32_16x16x32_bf16 v[124:127], v[154:157], v[186:189], v[124:127]
	v_mfma_f32_16x16x32_bf16 v[116:119], v[162:165], v[186:189], v[116:119]
	v_mfma_f32_16x16x32_bf16 v[108:111], v[154:157], v[194:197], v[108:111]
	v_mfma_f32_16x16x32_bf16 v[100:103], v[162:165], v[194:197], v[100:103]
	v_mfma_f32_16x16x32_bf16 v[92:95], v[154:157], v[202:205], v[92:95]
	v_mfma_f32_16x16x32_bf16 v[84:87], v[162:165], v[202:205], v[84:87]
	v_mfma_f32_16x16x32_bf16 v[76:79], v[154:157], v[216:219], v[76:79]
	v_mfma_f32_16x16x32_bf16 v[68:71], v[162:165], v[216:219], v[68:71]
	v_mfma_f32_16x16x32_bf16 v[120:123], v[166:169], v[182:185], v[120:123]
	v_mfma_f32_16x16x32_bf16 v[112:115], v[174:177], v[182:185], v[112:115]
	v_mfma_f32_16x16x32_bf16 v[104:107], v[166:169], v[190:193], v[104:107]
	v_mfma_f32_16x16x32_bf16 v[96:99], v[174:177], v[190:193], v[96:99]
	v_mfma_f32_16x16x32_bf16 v[88:91], v[166:169], v[198:201], v[88:91]
	v_mfma_f32_16x16x32_bf16 v[80:83], v[174:177], v[198:201], v[80:83]
	v_mfma_f32_16x16x32_bf16 v[72:75], v[166:169], v[212:215], v[72:75]
	v_mfma_f32_16x16x32_bf16 v[64:67], v[174:177], v[212:215], v[64:67]
	v_mfma_f32_16x16x32_bf16 v[120:123], v[170:173], v[186:189], v[120:123]
	v_mfma_f32_16x16x32_bf16 v[112:115], v[178:181], v[186:189], v[112:115]
	v_mfma_f32_16x16x32_bf16 v[104:107], v[170:173], v[194:197], v[104:107]
	v_mfma_f32_16x16x32_bf16 v[96:99], v[178:181], v[194:197], v[96:99]
	v_mfma_f32_16x16x32_bf16 v[88:91], v[170:173], v[202:205], v[88:91]
	v_mfma_f32_16x16x32_bf16 v[80:83], v[178:181], v[202:205], v[80:83]
	v_mfma_f32_16x16x32_bf16 v[72:75], v[170:173], v[216:219], v[72:75]
	v_mfma_f32_16x16x32_bf16 v[64:67], v[178:181], v[216:219], v[64:67]
	s_barrier
; #define PG8_STAGE(bufoff, gbase, voff) do { _Pragma("unroll") for (int _i = 0; _i < 2; ++_i) \
;         __builtin_amdgcn_global_load_lds((const unsigned*)((const char*)(gbase) + (voff)[_i]), (PG8_LAS unsigned*)(lds + (bufoff) + ldsw + _i * 8192), 16, 0, 0); } while (0)
; #define PG8_LDA(dst, b, h) do { _Pragma("unroll") for (int m = 0; m < 4; ++m) _Pragma("unroll") for (int k = 0; k < 2; ++k) dst[m][k] = *(const PG8_LAS bf16x8*)(lds + PG8_SA(b, h) + aoff + m * 2048 + k * 1024); } while (0)
; #define PG8_LDB(dst, b, h) do { _Pragma("unroll") for (int n = 0; n < 2; ++n) _Pragma("unroll") for (int k = 0; k < 2; ++k) dst[n][k] = *(const PG8_LAS bf16x8*)(lds + PG8_SB(b, h) + boff + n * 2048 + k * 1024); } while (0)
; #define PG8_MMA(ai, bj, At, Bt) do { __builtin_amdgcn_s_setprio(1); _Pragma("unroll") for (int m = 0; m < 4; ++m) _Pragma("unroll") for (int n = 0; n < 2; ++n) _Pragma("unroll") for (int k = 0; k < 2; ++k) \
;         acc[ai][bj][m][n] = __builtin_amdgcn_mfma_f32_16x16x32_bf16(Bt[n][k], At[m][k], acc[ai][bj][m][n], 0, 0, 0); __builtin_amdgcn_s_setprio(0); } while (0)
; #define PG8_WAIT_V(n) asm volatile("s_waitcnt vmcnt(" #n ")" ::: "memory")
; #define PG8_WAIT_L(n) asm volatile("s_waitcnt lgkmcnt(" #n ")" ::: "memory")
; #define PG8_BAR __builtin_amdgcn_s_barrier()
; #define PG8_SCHED __builtin_amdgcn_sched_barrier(0)
; template <class Epi, class Sched, bool ALIGN_EPI = false, bool SP2 = false>
; __device__ __forceinline__ void gemm_phase(PG8_LAS unsigned char* lds, const Gemm g, const Sched& S, const Epi& E, const int wid) {
;     ...
;             PG8_LDA(At, 0, 1); PG8_STAGE(PG8_SB(0, 0), b2, voffB); PG8_STAGE(PG8_SB(0, 1), b2 + hstep, voffB); PG8_STAGE(PG8_SA(0, 0), a2, voffA);
;             PG8_WAIT_V(8); PG8_WAIT_L(0); PG8_BAR; PG8_MMA(1, 0, At, B0); PG8_MMA(1, 1, At, B1); PG8_BAR; PG8_SCHED;
;             PG8_LDB(B0, 1, 0); PG8_LDB(B1, 1, 1); PG8_SCHED; PG8_LDA(At, 1, 0); PG8_STAGE(PG8_SA(0, 1), a2 + hstep, voffA);
;             PG8_WAIT_V(8); PG8_WAIT_L(0); PG8_BAR; PG8_MMA(0, 0, At, B0); PG8_MMA(0, 1, At, B1); PG8_BAR; PG8_SCHED;
	s_add_i32 s49, s40, s9
	v_lshl_add_u64 v[206:207], s[24:25], 0, v[132:133]
	s_mov_b32 m0, s49
	ds_read_b128 v[182:185], v153 offset:16384
	ds_read_b128 v[186:189], v153 offset:17408
	ds_read_b128 v[190:193], v153 offset:18432
	ds_read_b128 v[194:197], v153 offset:19456
	ds_read_b128 v[198:201], v153 offset:20480
	ds_read_b128 v[202:205], v153 offset:21504
	ds_read_b128 v[212:215], v153 offset:22528
	ds_read_b128 v[216:219], v153 offset:23552
	global_load_lds_dwordx4 v[206:207], off
	s_add_i32 m0, s49, 0x2000
	s_add_u32 s50, s24, 0x40000
	v_lshl_add_u64 v[220:221], s[24:25], 0, v[128:129]
	s_addc_u32 s51, s25, 0
	s_add_i32 s49, s41, s9
	global_load_lds_dwordx4 v[220:221], off
	v_lshl_add_u64 v[222:223], s[50:51], 0, v[132:133]
	s_mov_b32 m0, s49
	v_lshl_add_u64 v[224:225], s[26:27], 0, v[130:131]
	global_load_lds_dwordx4 v[222:223], off
	v_lshl_add_u64 v[222:223], s[50:51], 0, v[128:129]
	s_add_i32 m0, s49, 0x2000
	s_nop 0
	global_load_lds_dwordx4 v[222:223], off
	v_lshl_add_u64 v[222:223], s[26:27], 0, v[134:135]
	s_mov_b32 m0, s21
	s_nop 0
	global_load_lds_dwordx4 v[222:223], off
	s_mov_b32 m0, s30
	s_nop 0
	global_load_lds_dwordx4 v[224:225], off
	s_waitcnt vmcnt(8)
	s_waitcnt lgkmcnt(0)
	s_barrier
	s_waitcnt lgkmcnt(0)
	v_mfma_f32_16x16x32_bf16 v[60:63], v[144:147], v[182:185], v[60:63]
	v_mfma_f32_16x16x32_bf16 v[52:55], v[158:161], v[182:185], v[52:55]
	v_mfma_f32_16x16x32_bf16 v[44:47], v[144:147], v[190:193], v[44:47]
	v_mfma_f32_16x16x32_bf16 v[36:39], v[158:161], v[190:193], v[36:39]
	v_mfma_f32_16x16x32_bf16 v[28:31], v[144:147], v[198:201], v[28:31]
	v_mfma_f32_16x16x32_bf16 v[20:23], v[158:161], v[198:201], v[20:23]
	v_mfma_f32_16x16x32_bf16 v[12:15], v[144:147], v[212:215], v[12:15]
	v_mfma_f32_16x16x32_bf16 v[4:7], v[158:161], v[212:215], v[4:7]
	v_mfma_f32_16x16x32_bf16 v[60:63], v[154:157], v[186:189], v[60:63]
	v_mfma_f32_16x16x32_bf16 v[52:55], v[162:165], v[186:189], v[52:55]
	v_mfma_f32_16x16x32_bf16 v[44:47], v[154:157], v[194:197], v[44:47]
	v_mfma_f32_16x16x32_bf16 v[36:39], v[162:165], v[194:197], v[36:39]
	v_mfma_f32_16x16x32_bf16 v[28:31], v[154:157], v[202:205], v[28:31]
	v_mfma_f32_16x16x32_bf16 v[20:23], v[162:165], v[202:205], v[20:23]
	v_mfma_f32_16x16x32_bf16 v[12:15], v[154:157], v[216:219], v[12:15]
	v_mfma_f32_16x16x32_bf16 v[4:7], v[162:165], v[216:219], v[4:7]
	v_mfma_f32_16x16x32_bf16 v[56:59], v[166:169], v[182:185], v[56:59]
	v_mfma_f32_16x16x32_bf16 v[48:51], v[174:177], v[182:185], v[48:51]
	v_mfma_f32_16x16x32_bf16 v[40:43], v[166:169], v[190:193], v[40:43]
	v_mfma_f32_16x16x32_bf16 v[32:35], v[174:177], v[190:193], v[32:35]
	v_mfma_f32_16x16x32_bf16 v[24:27], v[166:169], v[198:201], v[24:27]
	v_mfma_f32_16x16x32_bf16 v[16:19], v[174:177], v[198:201], v[16:19]
	v_mfma_f32_16x16x32_bf16 v[8:11], v[166:169], v[212:215], v[8:11]
	v_mfma_f32_16x16x32_bf16 v[0:3], v[174:177], v[212:215], v[0:3]
	v_mfma_f32_16x16x32_bf16 v[56:59], v[170:173], v[186:189], v[56:59]
	v_mfma_f32_16x16x32_bf16 v[48:51], v[178:181], v[186:189], v[48:51]
	v_mfma_f32_16x16x32_bf16 v[40:43], v[170:173], v[194:197], v[40:43]
	v_mfma_f32_16x16x32_bf16 v[32:35], v[178:181], v[194:197], v[32:35]
	v_mfma_f32_16x16x32_bf16 v[24:27], v[170:173], v[202:205], v[24:27]
	v_mfma_f32_16x16x32_bf16 v[16:19], v[178:181], v[202:205], v[16:19]
	v_mfma_f32_16x16x32_bf16 v[8:11], v[170:173], v[216:219], v[8:11]
	v_mfma_f32_16x16x32_bf16 v[0:3], v[178:181], v[216:219], v[0:3]
	s_barrier
	s_add_i32 s49, 0, 0x18000
	s_add_i32 s50, 0, 0x1c000
	v_add_u32_e32 v162, s49, v149
	v_add_u32_e32 v178, s50, v149
	ds_read_b128 v[144:147], v162
	ds_read_b128 v[154:157], v162 offset:1024
	ds_read_b128 v[158:161], v162 offset:2048
	ds_read_b128 v[162:165], v162 offset:3072
	ds_read_b128 v[166:169], v178
	ds_read_b128 v[170:173], v178 offset:1024
	ds_read_b128 v[174:177], v178 offset:2048
	ds_read_b128 v[178:181], v178 offset:3072
	s_add_u32 s26, s26, 0x40000
	s_addc_u32 s27, s27, 0
	s_mov_b32 m0, s31
	v_lshl_add_u64 v[226:227], s[26:27], 0, v[134:135]
	ds_read_b128 v[182:185], v153 offset:32768
	ds_read_b128 v[186:189], v153 offset:33792
	ds_read_b128 v[190:193], v153 offset:34816
	ds_read_b128 v[194:197], v153 offset:35840
	ds_read_b128 v[198:201], v153 offset:36864
	ds_read_b128 v[202:205], v153 offset:37888
	ds_read_b128 v[212:215], v153 offset:38912
	ds_read_b128 v[216:219], v153 offset:39936
	global_load_lds_dwordx4 v[226:227], off
	v_lshl_add_u64 v[226:227], s[26:27], 0, v[130:131]
	s_mov_b32 m0, s33
	s_nop 0
	global_load_lds_dwordx4 v[226:227], off
	s_waitcnt vmcnt(8)
	s_waitcnt lgkmcnt(0)
	s_barrier
; #define PG8_STAGE(bufoff, gbase, voff) do { _Pragma("unroll") for (int _i = 0; _i < 2; ++_i) \
;         __builtin_amdgcn_global_load_lds((const unsigned*)((const char*)(gbase) + (voff)[_i]), (PG8_LAS unsigned*)(lds + (bufoff) + ldsw + _i * 8192), 16, 0, 0); } while (0)
; #define PG8_LDA(dst, b, h) do { _Pragma("unroll") for (int m = 0; m < 4; ++m) _Pragma("unroll") for (int k = 0; k < 2; ++k) dst[m][k] = *(const PG8_LAS bf16x8*)(lds + PG8_SA(b, h) + aoff + m * 2048 + k * 1024); } while (0)
; #define PG8_LDB(dst, b, h) do { _Pragma("unroll") for (int n = 0; n < 2; ++n) _Pragma("unroll") for (int k = 0; k < 2; ++k) dst[n][k] = *(const PG8_LAS bf16x8*)(lds + PG8_SB(b, h) + boff + n * 2048 + k * 1024); } while (0)
; #define PG8_MMA(ai, bj, At, Bt) do { __builtin_amdgcn_s_setprio(1); _Pragma("unroll") for (int m = 0; m < 4; ++m) _Pragma("unroll") for (int n = 0; n < 2; ++n) _Pragma("unroll") for (int k = 0; k < 2; ++k) \
;         acc[ai][bj][m][n] = __builtin_amdgcn_mfma_f32_16x16x32_bf16(Bt[n][k], At[m][k], acc[ai][bj][m][n], 0, 0, 0); __builtin_amdgcn_s_setprio(0); } while (0)
; #define PG8_WAIT_V(n) asm volatile("s_waitcnt vmcnt(" #n ")" ::: "memory")
; #define PG8_WAIT_L(n) asm volatile("s_waitcnt lgkmcnt(" #n ")" ::: "memory")
; #define PG8_BAR __builtin_amdgcn_s_barrier()
; #define PG8_SCHED __builtin_amdgcn_sched_barrier(0)
; template <class Epi, class Sched, bool ALIGN_EPI = false, bool SP2 = false>
; __device__ __forceinline__ void gemm_phase(PG8_LAS unsigned char* lds, const Gemm g, const Sched& S, const Epi& E, const int wid) {
;     ...
;             PG8_LDB(B0, 1, 0); PG8_LDB(B1, 1, 1); PG8_SCHED; PG8_LDA(At, 1, 0); PG8_STAGE(PG8_SA(0, 1), a2 + hstep, voffA);
;             PG8_WAIT_V(8); PG8_WAIT_L(0); PG8_BAR; PG8_MMA(0, 0, At, B0); PG8_MMA(0, 1, At, B1); PG8_BAR; PG8_SCHED;
;             PG8_LDA(At, 1, 1); PG8_STAGE(PG8_SB(1, 0), b3, voffB); PG8_STAGE(PG8_SB(1, 1), b3 + hstep, voffB); PG8_STAGE(PG8_SA(1, 0), a3, voffA);
;             PG8_WAIT_V(8); PG8_WAIT_L(0); PG8_BAR; PG8_MMA(1, 0, At, B0); PG8_MMA(1, 1, At, B1); PG8_BAR; PG8_SCHED;
	s_waitcnt lgkmcnt(0)
	v_mfma_f32_16x16x32_bf16 v[124:127], v[144:147], v[182:185], v[124:127]
	v_mfma_f32_16x16x32_bf16 v[116:119], v[158:161], v[182:185], v[116:119]
	v_mfma_f32_16x16x32_bf16 v[108:111], v[144:147], v[190:193], v[108:111]
	v_mfma_f32_16x16x32_bf16 v[100:103], v[158:161], v[190:193], v[100:103]
	v_mfma_f32_16x16x32_bf16 v[92:95], v[144:147], v[198:201], v[92:95]
	v_mfma_f32_16x16x32_bf16 v[84:87], v[158:161], v[198:201], v[84:87]
	v_mfma_f32_16x16x32_bf16 v[76:79], v[144:147], v[212:215], v[76:79]
	v_mfma_f32_16x16x32_bf16 v[68:71], v[158:161], v[212:215], v[68:71]
	v_mfma_f32_16x16x32_bf16 v[124:127], v[154:157], v[186:189], v[124:127]
	v_mfma_f32_16x16x32_bf16 v[116:119], v[162:165], v[186:189], v[116:119]
	v_mfma_f32_16x16x32_bf16 v[108:111], v[154:157], v[194:197], v[108:111]
	v_mfma_f32_16x16x32_bf16 v[100:103], v[162:165], v[194:197], v[100:103]
	v_mfma_f32_16x16x32_bf16 v[92:95], v[154:157], v[202:205], v[92:95]
	v_mfma_f32_16x16x32_bf16 v[84:87], v[162:165], v[202:205], v[84:87]
	v_mfma_f32_16x16x32_bf16 v[76:79], v[154:157], v[216:219], v[76:79]
	v_mfma_f32_16x16x32_bf16 v[68:71], v[162:165], v[216:219], v[68:71]
	v_mfma_f32_16x16x32_bf16 v[120:123], v[166:169], v[182:185], v[120:123]
	v_mfma_f32_16x16x32_bf16 v[112:115], v[174:177], v[182:185], v[112:115]
	v_mfma_f32_16x16x32_bf16 v[104:107], v[166:169], v[190:193], v[104:107]
	v_mfma_f32_16x16x32_bf16 v[96:99], v[174:177], v[190:193], v[96:99]
	v_mfma_f32_16x16x32_bf16 v[88:91], v[166:169], v[198:201], v[88:91]
	v_mfma_f32_16x16x32_bf16 v[80:83], v[174:177], v[198:201], v[80:83]
	v_mfma_f32_16x16x32_bf16 v[72:75], v[166:169], v[212:215], v[72:75]
	v_mfma_f32_16x16x32_bf16 v[64:67], v[174:177], v[212:215], v[64:67]
	v_mfma_f32_16x16x32_bf16 v[120:123], v[170:173], v[186:189], v[120:123]
	v_mfma_f32_16x16x32_bf16 v[112:115], v[178:181], v[186:189], v[112:115]
	v_mfma_f32_16x16x32_bf16 v[104:107], v[170:173], v[194:197], v[104:107]
	v_mfma_f32_16x16x32_bf16 v[96:99], v[178:181], v[194:197], v[96:99]
	v_mfma_f32_16x16x32_bf16 v[88:91], v[170:173], v[202:205], v[88:91]
	v_mfma_f32_16x16x32_bf16 v[80:83], v[178:181], v[202:205], v[80:83]
	v_mfma_f32_16x16x32_bf16 v[72:75], v[170:173], v[216:219], v[72:75]
	v_mfma_f32_16x16x32_bf16 v[64:67], v[178:181], v[216:219], v[64:67]
	s_barrier
	s_add_i32 s26, s49, s9
	v_lshl_add_u64 v[206:207], v[206:207], 0, s[6:7]
	s_mov_b32 m0, s26
	ds_read_b128 v[182:185], v153 offset:49152
	ds_read_b128 v[186:189], v153 offset:50176
	ds_read_b128 v[190:193], v153 offset:51200
	ds_read_b128 v[194:197], v153 offset:52224
	ds_read_b128 v[198:201], v153 offset:53248
	ds_read_b128 v[202:205], v153 offset:54272
	ds_read_b128 v[212:215], v153 offset:55296
	ds_read_b128 v[216:219], v153 offset:56320
	global_load_lds_dwordx4 v[206:207], off
	s_add_i32 m0, s26, 0x2000
	s_add_u32 s24, s24, 0x40080
	v_lshl_add_u64 v[206:207], v[220:221], 0, s[6:7]
	s_addc_u32 s25, s25, 0
	s_add_i32 s26, s50, s9
	global_load_lds_dwordx4 v[206:207], off
	v_lshl_add_u64 v[206:207], s[24:25], 0, v[132:133]
	s_mov_b32 m0, s26
	s_nop 0
	global_load_lds_dwordx4 v[206:207], off
	v_lshl_add_u64 v[206:207], s[24:25], 0, v[128:129]
	s_add_i32 m0, s26, 0x2000
	s_nop 0
	global_load_lds_dwordx4 v[206:207], off
	v_lshl_add_u64 v[206:207], v[222:223], 0, s[6:7]
	s_mov_b32 m0, s38
	s_nop 0
	global_load_lds_dwordx4 v[206:207], off
	v_lshl_add_u64 v[206:207], v[224:225], 0, s[6:7]
	s_mov_b32 m0, s39
	s_nop 0
	global_load_lds_dwordx4 v[206:207], off
	s_waitcnt vmcnt(8)
	s_waitcnt lgkmcnt(0)
	s_barrier
	s_waitcnt lgkmcnt(0)
	v_mfma_f32_16x16x32_bf16 v[60:63], v[144:147], v[182:185], v[60:63]
	v_mfma_f32_16x16x32_bf16 v[52:55], v[158:161], v[182:185], v[52:55]
	v_mfma_f32_16x16x32_bf16 v[44:47], v[144:147], v[190:193], v[44:47]
	v_mfma_f32_16x16x32_bf16 v[36:39], v[158:161], v[190:193], v[36:39]
	v_mfma_f32_16x16x32_bf16 v[28:31], v[144:147], v[198:201], v[28:31]
	v_mfma_f32_16x16x32_bf16 v[20:23], v[158:161], v[198:201], v[20:23]
	v_mfma_f32_16x16x32_bf16 v[12:15], v[144:147], v[212:215], v[12:15]
	v_mfma_f32_16x16x32_bf16 v[4:7], v[158:161], v[212:215], v[4:7]
	v_mfma_f32_16x16x32_bf16 v[60:63], v[154:157], v[186:189], v[60:63]
	v_mfma_f32_16x16x32_bf16 v[52:55], v[162:165], v[186:189], v[52:55]
	v_mfma_f32_16x16x32_bf16 v[44:47], v[154:157], v[194:197], v[44:47]
	v_mfma_f32_16x16x32_bf16 v[36:39], v[162:165], v[194:197], v[36:39]
	v_mfma_f32_16x16x32_bf16 v[28:31], v[154:157], v[202:205], v[28:31]
	v_mfma_f32_16x16x32_bf16 v[20:23], v[162:165], v[202:205], v[20:23]
	v_mfma_f32_16x16x32_bf16 v[12:15], v[154:157], v[216:219], v[12:15]
	v_mfma_f32_16x16x32_bf16 v[4:7], v[162:165], v[216:219], v[4:7]
	v_mfma_f32_16x16x32_bf16 v[56:59], v[166:169], v[182:185], v[56:59]
	v_mfma_f32_16x16x32_bf16 v[48:51], v[174:177], v[182:185], v[48:51]
	v_mfma_f32_16x16x32_bf16 v[40:43], v[166:169], v[190:193], v[40:43]
	v_mfma_f32_16x16x32_bf16 v[32:35], v[174:177], v[190:193], v[32:35]
	v_mfma_f32_16x16x32_bf16 v[24:27], v[166:169], v[198:201], v[24:27]
	v_mfma_f32_16x16x32_bf16 v[16:19], v[174:177], v[198:201], v[16:19]
	v_mfma_f32_16x16x32_bf16 v[8:11], v[166:169], v[212:215], v[8:11]
	v_mfma_f32_16x16x32_bf16 v[0:3], v[174:177], v[212:215], v[0:3]
	v_mfma_f32_16x16x32_bf16 v[56:59], v[170:173], v[186:189], v[56:59]
	v_mfma_f32_16x16x32_bf16 v[48:51], v[178:181], v[186:189], v[48:51]
	v_mfma_f32_16x16x32_bf16 v[40:43], v[170:173], v[194:197], v[40:43]
	v_mfma_f32_16x16x32_bf16 v[32:35], v[178:181], v[194:197], v[32:35]
	v_mfma_f32_16x16x32_bf16 v[24:27], v[170:173], v[202:205], v[24:27]
	v_mfma_f32_16x16x32_bf16 v[16:19], v[178:181], v[202:205], v[16:19]
	v_mfma_f32_16x16x32_bf16 v[8:11], v[170:173], v[216:219], v[8:11]
	v_mfma_f32_16x16x32_bf16 v[0:3], v[178:181], v[216:219], v[0:3]
	s_barrier
	s_add_i32 s48, s48, 2
	s_add_u32 s22, s22, 0x100
	s_addc_u32 s23, s23, 0
	s_add_u32 s46, s46, 0x100
	s_addc_u32 s47, s47, 0
	s_cmp_gt_u32 s48, 13
	s_cbranch_scc0 .LBB0_269

; #define PG8_STAGE(bufoff, gbase, voff) do { _Pragma("unroll") for (int _i = 0; _i < 2; ++_i) \
;         __builtin_amdgcn_global_load_lds((const unsigned*)((const char*)(gbase) + (voff)[_i]), (PG8_LAS unsigned*)(lds + (bufoff) + ldsw + _i * 8192), 16, 0, 0); } while (0)
; #define PG8_LDA(dst, b, h) do { _Pragma("unroll") for (int m = 0; m < 4; ++m) _Pragma("unroll") for (int k = 0; k < 2; ++k) dst[m][k] = *(const PG8_LAS bf16x8*)(lds + PG8_SA(b, h) + aoff + m * 2048 + k * 1024); } while (0)
; #define PG8_LDB(dst, b, h) do { _Pragma("unroll") for (int n = 0; n < 2; ++n) _Pragma("unroll") for (int k = 0; k < 2; ++k) dst[n][k] = *(const PG8_LAS bf16x8*)(lds + PG8_SB(b, h) + boff + n * 2048 + k * 1024); } while (0)
; #define PG8_MMA(ai, bj, At, Bt) do { __builtin_amdgcn_s_setprio(1); _Pragma("unroll") for (int m = 0; m < 4; ++m) _Pragma("unroll") for (int n = 0; n < 2; ++n) _Pragma("unroll") for (int k = 0; k < 2; ++k) \
;         acc[ai][bj][m][n] = __builtin_amdgcn_mfma_f32_16x16x32_bf16(Bt[n][k], At[m][k], acc[ai][bj][m][n], 0, 0, 0); __builtin_amdgcn_s_setprio(0); } while (0)
; #define PG8_WAIT_V(n) asm volatile("s_waitcnt vmcnt(" #n ")" ::: "memory")
; #define PG8_WAIT_L(n) asm volatile("s_waitcnt lgkmcnt(" #n ")" ::: "memory")
; #define PG8_BAR __builtin_amdgcn_s_barrier()
; #define PG8_SCHED __builtin_amdgcn_sched_barrier(0)
; template <class Epi, class Sched, bool ALIGN_EPI = false, bool SP2 = false>
; __device__ __forceinline__ void gemm_phase(PG8_LAS unsigned char* lds, const Gemm g, const Sched& S, const Epi& E, const int wid) {
;     ...
;             PG8_LDB(B0, 0, 0); PG8_LDB(B1, 0, 1); PG8_SCHED; PG8_LDA(At, 0, 0); PG8_STAGE(PG8_SA(1, 1), a1 + hstep, voffA);
;             PG8_WAIT_V(8); PG8_WAIT_L(0); PG8_BAR; PG8_MMA(0, 0, At, B0); PG8_MMA(0, 1, At, B1); PG8_BAR; PG8_SCHED;
;             PG8_LDA(At, 0, 1); PG8_STAGE(PG8_SB(0, 0), b2, voffB); PG8_STAGE(PG8_SB(0, 1), b2 + hstep, voffB); PG8_STAGE(PG8_SA(0, 0), a2, voffA);
;             PG8_WAIT_V(8); PG8_WAIT_L(0); PG8_BAR; PG8_MMA(1, 0, At, B0); PG8_MMA(1, 1, At, B1); PG8_BAR; PG8_SCHED;
.LBB0_756:
	v_add_u32_e32 v151, s35, v149
	ds_read_b128 v[152:155], v151
	ds_read_b128 v[156:159], v151 offset:1024
	ds_read_b128 v[160:163], v151 offset:2048
	ds_read_b128 v[164:167], v151 offset:3072
	v_add_u32_e32 v151, s38, v149
	s_add_u32 s16, s2, s14
	ds_read_b128 v[168:171], v151
	ds_read_b128 v[172:175], v151 offset:1024
	ds_read_b128 v[176:179], v151 offset:2048
	ds_read_b128 v[180:183], v151 offset:3072
	s_addc_u32 s17, s3, s15
	s_add_u32 s16, s16, 0x100
	s_addc_u32 s17, s17, 0
	s_add_u32 s45, s42, s14
	s_addc_u32 s46, s43, s15
	s_cmpk_eq_i32 s14, 0x1500
	s_cselect_b32 s19, s13, s17
	s_cselect_b32 s18, s12, s16
	s_cselect_b32 s17, s9, s46
	s_cselect_b32 s16, s8, s45
	v_lshl_add_u64 v[206:207], v[144:145], 0, s[14:15]
	s_add_i32 m0, s25, 0xc000
	ds_read_b128 v[184:187], v150
	ds_read_b128 v[188:191], v150 offset:1024
	ds_read_b128 v[194:197], v150 offset:2048
	ds_read_b128 v[198:201], v150 offset:3072
	ds_read_b128 v[202:205], v150 offset:4096
	ds_read_b128 v[212:215], v150 offset:5120
	ds_read_b128 v[216:219], v150 offset:6144
	ds_read_b128 v[220:223], v150 offset:7168
	global_load_lds_dwordx4 v[206:207], off
	v_lshl_add_u64 v[206:207], v[146:147], 0, s[14:15]
	s_add_i32 m0, s25, 0xe000
	s_nop 0
	global_load_lds_dwordx4 v[206:207], off
	s_waitcnt vmcnt(8)
	s_waitcnt lgkmcnt(0)
	s_barrier
	s_waitcnt lgkmcnt(0)
	v_mfma_f32_16x16x32_bf16 v[120:123], v[152:155], v[184:187], v[120:123]
	v_mfma_f32_16x16x32_bf16 v[124:127], v[160:163], v[184:187], v[124:127]
	v_mfma_f32_16x16x32_bf16 v[108:111], v[152:155], v[194:197], v[108:111]
	v_mfma_f32_16x16x32_bf16 v[116:119], v[160:163], v[194:197], v[116:119]
	v_mfma_f32_16x16x32_bf16 v[92:95], v[152:155], v[202:205], v[92:95]
	v_mfma_f32_16x16x32_bf16 v[112:115], v[160:163], v[202:205], v[112:115]
	v_mfma_f32_16x16x32_bf16 v[72:75], v[152:155], v[216:219], v[72:75]
	v_mfma_f32_16x16x32_bf16 v[100:103], v[160:163], v[216:219], v[100:103]
	v_mfma_f32_16x16x32_bf16 v[120:123], v[156:159], v[188:191], v[120:123]
	v_mfma_f32_16x16x32_bf16 v[124:127], v[164:167], v[188:191], v[124:127]
	v_mfma_f32_16x16x32_bf16 v[108:111], v[156:159], v[198:201], v[108:111]
	v_mfma_f32_16x16x32_bf16 v[116:119], v[164:167], v[198:201], v[116:119]
	v_mfma_f32_16x16x32_bf16 v[92:95], v[156:159], v[212:215], v[92:95]
	v_mfma_f32_16x16x32_bf16 v[112:115], v[164:167], v[212:215], v[112:115]
	v_mfma_f32_16x16x32_bf16 v[72:75], v[156:159], v[220:223], v[72:75]
	v_mfma_f32_16x16x32_bf16 v[100:103], v[164:167], v[220:223], v[100:103]
	v_mfma_f32_16x16x32_bf16 v[104:107], v[168:171], v[184:187], v[104:107]
	v_mfma_f32_16x16x32_bf16 v[88:91], v[176:179], v[184:187], v[88:91]
	v_mfma_f32_16x16x32_bf16 v[96:99], v[168:171], v[194:197], v[96:99]
	v_mfma_f32_16x16x32_bf16 v[76:79], v[176:179], v[194:197], v[76:79]
	v_mfma_f32_16x16x32_bf16 v[84:87], v[168:171], v[202:205], v[84:87]
	v_mfma_f32_16x16x32_bf16 v[68:71], v[176:179], v[202:205], v[68:71]
	v_mfma_f32_16x16x32_bf16 v[80:83], v[168:171], v[216:219], v[80:83]
	v_mfma_f32_16x16x32_bf16 v[64:67], v[176:179], v[216:219], v[64:67]
	v_mfma_f32_16x16x32_bf16 v[104:107], v[172:175], v[188:191], v[104:107]
	v_mfma_f32_16x16x32_bf16 v[88:91], v[180:183], v[188:191], v[88:91]
	v_mfma_f32_16x16x32_bf16 v[96:99], v[172:175], v[198:201], v[96:99]
	v_mfma_f32_16x16x32_bf16 v[76:79], v[180:183], v[198:201], v[76:79]
	v_mfma_f32_16x16x32_bf16 v[84:87], v[172:175], v[212:215], v[84:87]
	v_mfma_f32_16x16x32_bf16 v[68:71], v[180:183], v[212:215], v[68:71]
	v_mfma_f32_16x16x32_bf16 v[80:83], v[172:175], v[220:223], v[80:83]
	v_mfma_f32_16x16x32_bf16 v[64:67], v[180:183], v[220:223], v[64:67]
	s_barrier
	s_add_i32 s45, s35, s23
	v_lshl_add_u64 v[206:207], s[16:17], 0, v[132:133]
	s_mov_b32 m0, s45
	ds_read_b128 v[184:187], v150 offset:16384
	ds_read_b128 v[188:191], v150 offset:17408
	ds_read_b128 v[194:197], v150 offset:18432
	ds_read_b128 v[198:201], v150 offset:19456
	ds_read_b128 v[202:205], v150 offset:20480
	ds_read_b128 v[212:215], v150 offset:21504
	ds_read_b128 v[216:219], v150 offset:22528
	ds_read_b128 v[220:223], v150 offset:23552
	global_load_lds_dwordx4 v[206:207], off
	s_add_i32 m0, s45, 0x2000
	s_add_u32 s46, s16, 0xb0000
	v_lshl_add_u64 v[224:225], s[16:17], 0, v[128:129]
	s_addc_u32 s47, s17, 0
	s_add_i32 s45, s38, s23
	global_load_lds_dwordx4 v[224:225], off
	v_lshl_add_u64 v[226:227], s[46:47], 0, v[132:133]
	s_mov_b32 m0, s45
	v_lshl_add_u64 v[228:229], s[18:19], 0, v[130:131]
	global_load_lds_dwordx4 v[226:227], off
	v_lshl_add_u64 v[226:227], s[46:47], 0, v[128:129]
	s_add_i32 m0, s45, 0x2000
	s_nop 0
	global_load_lds_dwordx4 v[226:227], off
	v_lshl_add_u64 v[226:227], s[18:19], 0, v[134:135]
	s_mov_b32 m0, s25
	s_nop 0
	global_load_lds_dwordx4 v[226:227], off
	s_mov_b32 m0, s27
	s_nop 0
	global_load_lds_dwordx4 v[228:229], off
	s_waitcnt vmcnt(8)
	s_waitcnt lgkmcnt(0)
	s_barrier
; #define PG8_STAGE(bufoff, gbase, voff) do { _Pragma("unroll") for (int _i = 0; _i < 2; ++_i) \
;         __builtin_amdgcn_global_load_lds((const unsigned*)((const char*)(gbase) + (voff)[_i]), (PG8_LAS unsigned*)(lds + (bufoff) + ldsw + _i * 8192), 16, 0, 0); } while (0)
; #define PG8_LDA(dst, b, h) do { _Pragma("unroll") for (int m = 0; m < 4; ++m) _Pragma("unroll") for (int k = 0; k < 2; ++k) dst[m][k] = *(const PG8_LAS bf16x8*)(lds + PG8_SA(b, h) + aoff + m * 2048 + k * 1024); } while (0)
; #define PG8_LDB(dst, b, h) do { _Pragma("unroll") for (int n = 0; n < 2; ++n) _Pragma("unroll") for (int k = 0; k < 2; ++k) dst[n][k] = *(const PG8_LAS bf16x8*)(lds + PG8_SB(b, h) + boff + n * 2048 + k * 1024); } while (0)
; #define PG8_MMA(ai, bj, At, Bt) do { __builtin_amdgcn_s_setprio(1); _Pragma("unroll") for (int m = 0; m < 4; ++m) _Pragma("unroll") for (int n = 0; n < 2; ++n) _Pragma("unroll") for (int k = 0; k < 2; ++k) \
;         acc[ai][bj][m][n] = __builtin_amdgcn_mfma_f32_16x16x32_bf16(Bt[n][k], At[m][k], acc[ai][bj][m][n], 0, 0, 0); __builtin_amdgcn_s_setprio(0); } while (0)
; #define PG8_WAIT_V(n) asm volatile("s_waitcnt vmcnt(" #n ")" ::: "memory")
; #define PG8_WAIT_L(n) asm volatile("s_waitcnt lgkmcnt(" #n ")" ::: "memory")
; #define PG8_BAR __builtin_amdgcn_s_barrier()
; #define PG8_SCHED __builtin_amdgcn_sched_barrier(0)
; template <class Epi, class Sched, bool ALIGN_EPI = false, bool SP2 = false>
; __device__ __forceinline__ void gemm_phase(PG8_LAS unsigned char* lds, const Gemm g, const Sched& S, const Epi& E, const int wid) {
;     ...
;             PG8_LDA(At, 0, 1); PG8_STAGE(PG8_SB(0, 0), b2, voffB); PG8_STAGE(PG8_SB(0, 1), b2 + hstep, voffB); PG8_STAGE(PG8_SA(0, 0), a2, voffA);
;             PG8_WAIT_V(8); PG8_WAIT_L(0); PG8_BAR; PG8_MMA(1, 0, At, B0); PG8_MMA(1, 1, At, B1); PG8_BAR; PG8_SCHED;
;             PG8_LDB(B0, 1, 0); PG8_LDB(B1, 1, 1); PG8_SCHED; PG8_LDA(At, 1, 0); PG8_STAGE(PG8_SA(0, 1), a2 + hstep, voffA);
;             PG8_WAIT_V(8); PG8_WAIT_L(0); PG8_BAR; PG8_MMA(0, 0, At, B0); PG8_MMA(0, 1, At, B1); PG8_BAR; PG8_SCHED;
	s_waitcnt lgkmcnt(0)
	v_mfma_f32_16x16x32_bf16 v[60:63], v[152:155], v[184:187], v[60:63]
	v_mfma_f32_16x16x32_bf16 v[56:59], v[160:163], v[184:187], v[56:59]
	v_mfma_f32_16x16x32_bf16 v[44:47], v[152:155], v[194:197], v[44:47]
	v_mfma_f32_16x16x32_bf16 v[40:43], v[160:163], v[194:197], v[40:43]
	v_mfma_f32_16x16x32_bf16 v[28:31], v[152:155], v[202:205], v[28:31]
	v_mfma_f32_16x16x32_bf16 v[24:27], v[160:163], v[202:205], v[24:27]
	v_mfma_f32_16x16x32_bf16 v[4:7], v[152:155], v[216:219], v[4:7]
	v_mfma_f32_16x16x32_bf16 v[12:15], v[160:163], v[216:219], v[12:15]
	v_mfma_f32_16x16x32_bf16 v[60:63], v[156:159], v[188:191], v[60:63]
	v_mfma_f32_16x16x32_bf16 v[56:59], v[164:167], v[188:191], v[56:59]
	v_mfma_f32_16x16x32_bf16 v[44:47], v[156:159], v[198:201], v[44:47]
	v_mfma_f32_16x16x32_bf16 v[40:43], v[164:167], v[198:201], v[40:43]
	v_mfma_f32_16x16x32_bf16 v[28:31], v[156:159], v[212:215], v[28:31]
	v_mfma_f32_16x16x32_bf16 v[24:27], v[164:167], v[212:215], v[24:27]
	v_mfma_f32_16x16x32_bf16 v[4:7], v[156:159], v[220:223], v[4:7]
	v_mfma_f32_16x16x32_bf16 v[12:15], v[164:167], v[220:223], v[12:15]
	v_mfma_f32_16x16x32_bf16 v[52:55], v[168:171], v[184:187], v[52:55]
	v_mfma_f32_16x16x32_bf16 v[48:51], v[176:179], v[184:187], v[48:51]
	v_mfma_f32_16x16x32_bf16 v[36:39], v[168:171], v[194:197], v[36:39]
	v_mfma_f32_16x16x32_bf16 v[32:35], v[176:179], v[194:197], v[32:35]
	v_mfma_f32_16x16x32_bf16 v[20:23], v[168:171], v[202:205], v[20:23]
	v_mfma_f32_16x16x32_bf16 v[16:19], v[176:179], v[202:205], v[16:19]
	v_mfma_f32_16x16x32_bf16 v[8:11], v[168:171], v[216:219], v[8:11]
	v_mfma_f32_16x16x32_bf16 v[0:3], v[176:179], v[216:219], v[0:3]
	v_mfma_f32_16x16x32_bf16 v[52:55], v[172:175], v[188:191], v[52:55]
	v_mfma_f32_16x16x32_bf16 v[48:51], v[180:183], v[188:191], v[48:51]
	v_mfma_f32_16x16x32_bf16 v[36:39], v[172:175], v[198:201], v[36:39]
	v_mfma_f32_16x16x32_bf16 v[32:35], v[180:183], v[198:201], v[32:35]
	v_mfma_f32_16x16x32_bf16 v[20:23], v[172:175], v[212:215], v[20:23]
	v_mfma_f32_16x16x32_bf16 v[16:19], v[180:183], v[212:215], v[16:19]
	v_mfma_f32_16x16x32_bf16 v[8:11], v[172:175], v[220:223], v[8:11]
	v_mfma_f32_16x16x32_bf16 v[0:3], v[180:183], v[220:223], v[0:3]
	s_barrier
	s_add_i32 s45, 0, 0x18000
	v_add_u32_e32 v151, s45, v149
	s_add_i32 s46, 0, 0x1c000
	ds_read_b128 v[152:155], v151
	ds_read_b128 v[156:159], v151 offset:1024
	ds_read_b128 v[160:163], v151 offset:2048
	ds_read_b128 v[164:167], v151 offset:3072
	v_add_u32_e32 v151, s46, v149
	ds_read_b128 v[168:171], v151
	ds_read_b128 v[172:175], v151 offset:1024
	ds_read_b128 v[176:179], v151 offset:2048
	ds_read_b128 v[180:183], v151 offset:3072
	s_add_u32 s18, s18, 0xb0000
	s_addc_u32 s19, s19, 0
	s_mov_b32 m0, s28
	v_lshl_add_u64 v[230:231], s[18:19], 0, v[134:135]
	ds_read_b128 v[184:187], v150 offset:32768
	ds_read_b128 v[188:191], v150 offset:33792
	ds_read_b128 v[194:197], v150 offset:34816
	ds_read_b128 v[198:201], v150 offset:35840
	ds_read_b128 v[202:205], v150 offset:36864
	ds_read_b128 v[212:215], v150 offset:37888
	ds_read_b128 v[216:219], v150 offset:38912
	ds_read_b128 v[220:223], v150 offset:39936
	global_load_lds_dwordx4 v[230:231], off
	v_lshl_add_u64 v[230:231], s[18:19], 0, v[130:131]
	s_mov_b32 m0, s29
	s_nop 0
	global_load_lds_dwordx4 v[230:231], off
	s_waitcnt vmcnt(8)
	s_waitcnt lgkmcnt(0)
	s_barrier
	s_waitcnt lgkmcnt(0)
	v_mfma_f32_16x16x32_bf16 v[120:123], v[152:155], v[184:187], v[120:123]
	v_mfma_f32_16x16x32_bf16 v[124:127], v[160:163], v[184:187], v[124:127]
	v_mfma_f32_16x16x32_bf16 v[108:111], v[152:155], v[194:197], v[108:111]
	v_mfma_f32_16x16x32_bf16 v[116:119], v[160:163], v[194:197], v[116:119]
	v_mfma_f32_16x16x32_bf16 v[92:95], v[152:155], v[202:205], v[92:95]
	v_mfma_f32_16x16x32_bf16 v[112:115], v[160:163], v[202:205], v[112:115]
	v_mfma_f32_16x16x32_bf16 v[72:75], v[152:155], v[216:219], v[72:75]
	v_mfma_f32_16x16x32_bf16 v[100:103], v[160:163], v[216:219], v[100:103]
	v_mfma_f32_16x16x32_bf16 v[120:123], v[156:159], v[188:191], v[120:123]
	v_mfma_f32_16x16x32_bf16 v[124:127], v[164:167], v[188:191], v[124:127]
	v_mfma_f32_16x16x32_bf16 v[108:111], v[156:159], v[198:201], v[108:111]
	v_mfma_f32_16x16x32_bf16 v[116:119], v[164:167], v[198:201], v[116:119]
	v_mfma_f32_16x16x32_bf16 v[92:95], v[156:159], v[212:215], v[92:95]
	v_mfma_f32_16x16x32_bf16 v[112:115], v[164:167], v[212:215], v[112:115]
	v_mfma_f32_16x16x32_bf16 v[72:75], v[156:159], v[220:223], v[72:75]
	v_mfma_f32_16x16x32_bf16 v[100:103], v[164:167], v[220:223], v[100:103]
	v_mfma_f32_16x16x32_bf16 v[104:107], v[168:171], v[184:187], v[104:107]
	v_mfma_f32_16x16x32_bf16 v[88:91], v[176:179], v[184:187], v[88:91]
	v_mfma_f32_16x16x32_bf16 v[96:99], v[168:171], v[194:197], v[96:99]
	v_mfma_f32_16x16x32_bf16 v[76:79], v[176:179], v[194:197], v[76:79]
	v_mfma_f32_16x16x32_bf16 v[84:87], v[168:171], v[202:205], v[84:87]
	v_mfma_f32_16x16x32_bf16 v[68:71], v[176:179], v[202:205], v[68:71]
	v_mfma_f32_16x16x32_bf16 v[80:83], v[168:171], v[216:219], v[80:83]
	v_mfma_f32_16x16x32_bf16 v[64:67], v[176:179], v[216:219], v[64:67]
	v_mfma_f32_16x16x32_bf16 v[104:107], v[172:175], v[188:191], v[104:107]
	v_mfma_f32_16x16x32_bf16 v[88:91], v[180:183], v[188:191], v[88:91]
	v_mfma_f32_16x16x32_bf16 v[96:99], v[172:175], v[198:201], v[96:99]
	v_mfma_f32_16x16x32_bf16 v[76:79], v[180:183], v[198:201], v[76:79]
	v_mfma_f32_16x16x32_bf16 v[84:87], v[172:175], v[212:215], v[84:87]
	v_mfma_f32_16x16x32_bf16 v[68:71], v[180:183], v[212:215], v[68:71]
	v_mfma_f32_16x16x32_bf16 v[80:83], v[172:175], v[220:223], v[80:83]
	v_mfma_f32_16x16x32_bf16 v[64:67], v[180:183], v[220:223], v[64:67]
	s_barrier
; #define PG8_STAGE(bufoff, gbase, voff) do { _Pragma("unroll") for (int _i = 0; _i < 2; ++_i) \
;         __builtin_amdgcn_global_load_lds((const unsigned*)((const char*)(gbase) + (voff)[_i]), (PG8_LAS unsigned*)(lds + (bufoff) + ldsw + _i * 8192), 16, 0, 0); } while (0)
; #define PG8_LDA(dst, b, h) do { _Pragma("unroll") for (int m = 0; m < 4; ++m) _Pragma("unroll") for (int k = 0; k < 2; ++k) dst[m][k] = *(const PG8_LAS bf16x8*)(lds + PG8_SA(b, h) + aoff + m * 2048 + k * 1024); } while (0)
; #define PG8_MMA(ai, bj, At, Bt) do { __builtin_amdgcn_s_setprio(1); _Pragma("unroll") for (int m = 0; m < 4; ++m) _Pragma("unroll") for (int n = 0; n < 2; ++n) _Pragma("unroll") for (int k = 0; k < 2; ++k) \
;         acc[ai][bj][m][n] = __builtin_amdgcn_mfma_f32_16x16x32_bf16(Bt[n][k], At[m][k], acc[ai][bj][m][n], 0, 0, 0); __builtin_amdgcn_s_setprio(0); } while (0)
; #define PG8_WAIT_V(n) asm volatile("s_waitcnt vmcnt(" #n ")" ::: "memory")
; #define PG8_WAIT_L(n) asm volatile("s_waitcnt lgkmcnt(" #n ")" ::: "memory")
; #define PG8_BAR __builtin_amdgcn_s_barrier()
; #define PG8_SCHED __builtin_amdgcn_sched_barrier(0)
; template <class Epi, class Sched, bool ALIGN_EPI = false, bool SP2 = false>
; __device__ __forceinline__ void gemm_phase(PG8_LAS unsigned char* lds, const Gemm g, const Sched& S, const Epi& E, const int wid) {
;     ...
;             PG8_LDA(At, 1, 1); PG8_STAGE(PG8_SB(1, 0), b3, voffB); PG8_STAGE(PG8_SB(1, 1), b3 + hstep, voffB); PG8_STAGE(PG8_SA(1, 0), a3, voffA);
;             PG8_WAIT_V(8); PG8_WAIT_L(0); PG8_BAR; PG8_MMA(1, 0, At, B0); PG8_MMA(1, 1, At, B1); PG8_BAR; PG8_SCHED;
;     ...
; #pragma unroll
;         for (int a = 0; a < 2; ++a)
; #pragma unroll
;             for (int b = 0; b < 2; ++b)
; #pragma unroll
;                 for (int m = 0; m < 4; ++m)
; #pragma unroll
;                     for (int n = 0; n < 2; ++n) acc[a][b][m][n] = (f32x4){0.f, 0.f, 0.f, 0.f};
;         cur = nxt; cA = nA; cB = nB; ++ui;
	s_add_i32 s18, s45, s23
	v_lshl_add_u64 v[206:207], v[206:207], 0, s[10:11]
	s_mov_b32 m0, s18
	ds_read_b128 v[184:187], v150 offset:49152
	ds_read_b128 v[188:191], v150 offset:50176
	ds_read_b128 v[194:197], v150 offset:51200
	ds_read_b128 v[198:201], v150 offset:52224
	ds_read_b128 v[202:205], v150 offset:53248
	ds_read_b128 v[212:215], v150 offset:54272
	ds_read_b128 v[216:219], v150 offset:55296
	ds_read_b128 v[220:223], v150 offset:56320
	global_load_lds_dwordx4 v[206:207], off
	s_add_i32 m0, s18, 0x2000
	s_add_u32 s16, s16, 0xb0080
	v_lshl_add_u64 v[206:207], v[224:225], 0, s[10:11]
	s_addc_u32 s17, s17, 0
	s_add_i32 s18, s46, s23
	global_load_lds_dwordx4 v[206:207], off
	v_lshl_add_u64 v[206:207], s[16:17], 0, v[132:133]
	s_mov_b32 m0, s18
	s_nop 0
	global_load_lds_dwordx4 v[206:207], off
	v_lshl_add_u64 v[206:207], s[16:17], 0, v[128:129]
	s_add_i32 m0, s18, 0x2000
	s_nop 0
	global_load_lds_dwordx4 v[206:207], off
	v_lshl_add_u64 v[206:207], v[226:227], 0, s[10:11]
	s_mov_b32 m0, s31
	s_nop 0
	global_load_lds_dwordx4 v[206:207], off
	v_lshl_add_u64 v[206:207], v[228:229], 0, s[10:11]
	s_mov_b32 m0, s33
	s_nop 0
	global_load_lds_dwordx4 v[206:207], off
	s_waitcnt vmcnt(8)
	s_waitcnt lgkmcnt(0)
	s_barrier
	s_waitcnt lgkmcnt(0)
	v_mfma_f32_16x16x32_bf16 v[60:63], v[152:155], v[184:187], v[60:63]
	v_mfma_f32_16x16x32_bf16 v[56:59], v[160:163], v[184:187], v[56:59]
	v_mfma_f32_16x16x32_bf16 v[44:47], v[152:155], v[194:197], v[44:47]
	v_mfma_f32_16x16x32_bf16 v[40:43], v[160:163], v[194:197], v[40:43]
	v_mfma_f32_16x16x32_bf16 v[28:31], v[152:155], v[202:205], v[28:31]
	v_mfma_f32_16x16x32_bf16 v[24:27], v[160:163], v[202:205], v[24:27]
	v_mfma_f32_16x16x32_bf16 v[4:7], v[152:155], v[216:219], v[4:7]
	v_mfma_f32_16x16x32_bf16 v[12:15], v[160:163], v[216:219], v[12:15]
	v_mfma_f32_16x16x32_bf16 v[60:63], v[156:159], v[188:191], v[60:63]
	v_mfma_f32_16x16x32_bf16 v[56:59], v[164:167], v[188:191], v[56:59]
	v_mfma_f32_16x16x32_bf16 v[44:47], v[156:159], v[198:201], v[44:47]
	v_mfma_f32_16x16x32_bf16 v[40:43], v[164:167], v[198:201], v[40:43]
	v_mfma_f32_16x16x32_bf16 v[28:31], v[156:159], v[212:215], v[28:31]
	v_mfma_f32_16x16x32_bf16 v[24:27], v[164:167], v[212:215], v[24:27]
	v_mfma_f32_16x16x32_bf16 v[4:7], v[156:159], v[220:223], v[4:7]
	v_mfma_f32_16x16x32_bf16 v[12:15], v[164:167], v[220:223], v[12:15]
	v_mfma_f32_16x16x32_bf16 v[52:55], v[168:171], v[184:187], v[52:55]
	v_mfma_f32_16x16x32_bf16 v[48:51], v[176:179], v[184:187], v[48:51]
	v_mfma_f32_16x16x32_bf16 v[36:39], v[168:171], v[194:197], v[36:39]
	v_mfma_f32_16x16x32_bf16 v[32:35], v[176:179], v[194:197], v[32:35]
	v_mfma_f32_16x16x32_bf16 v[20:23], v[168:171], v[202:205], v[20:23]
	v_mfma_f32_16x16x32_bf16 v[16:19], v[176:179], v[202:205], v[16:19]
	v_mfma_f32_16x16x32_bf16 v[8:11], v[168:171], v[216:219], v[8:11]
	v_mfma_f32_16x16x32_bf16 v[0:3], v[176:179], v[216:219], v[0:3]
	v_mfma_f32_16x16x32_bf16 v[52:55], v[172:175], v[188:191], v[52:55]
	v_mfma_f32_16x16x32_bf16 v[48:51], v[180:183], v[188:191], v[48:51]
	v_mfma_f32_16x16x32_bf16 v[36:39], v[172:175], v[198:201], v[36:39]
	v_mfma_f32_16x16x32_bf16 v[32:35], v[180:183], v[198:201], v[32:35]
	v_mfma_f32_16x16x32_bf16 v[20:23], v[172:175], v[212:215], v[20:23]
	v_mfma_f32_16x16x32_bf16 v[16:19], v[180:183], v[212:215], v[16:19]
	v_mfma_f32_16x16x32_bf16 v[8:11], v[172:175], v[220:223], v[8:11]
	v_mfma_f32_16x16x32_bf16 v[0:3], v[180:183], v[220:223], v[0:3]
	s_barrier
	s_add_i32 s44, s44, 2
	s_add_u32 s14, s14, 0x100
	s_addc_u32 s15, s15, 0
	s_cmp_gt_u32 s44, 41
	s_cbranch_scc0 .LBB0_756
	s_add_u32 s14, s42, 0xffffff00
	s_addc_u32 s15, s43, -1
	s_and_b64 vcc, exec, s[6:7]
	s_cbranch_vccnz .LBB0_743
	v_mov_b32_e32 v0, 0
	s_mov_b32 s0, s39
	s_mov_b32 s20, s40
	s_mov_b64 s[2:3], s[12:13]
	s_mov_b32 s34, s41
	v_mov_b32_e32 v1, v0
	v_mov_b32_e32 v2, v0
	v_mov_b32_e32 v3, v0
	v_mov_b32_e32 v8, v0
	v_mov_b32_e32 v9, v0
	v_mov_b32_e32 v10, v0
	v_mov_b32_e32 v11, v0
	v_mov_b32_e32 v16, v0
	v_mov_b32_e32 v17, v0
	v_mov_b32_e32 v18, v0
	v_mov_b32_e32 v19, v0
	v_mov_b32_e32 v20, v0
	v_mov_b32_e32 v21, v0
	v_mov_b32_e32 v22, v0
	v_mov_b32_e32 v23, v0
	v_mov_b32_e32 v32, v0
	v_mov_b32_e32 v33, v0
	v_mov_b32_e32 v34, v0
	v_mov_b32_e32 v35, v0
	v_mov_b32_e32 v36, v0
	v_mov_b32_e32 v37, v0
	v_mov_b32_e32 v38, v0
	v_mov_b32_e32 v39, v0
	v_mov_b32_e32 v48, v0
	v_mov_b32_e32 v49, v0
	v_mov_b32_e32 v50, v0
	v_mov_b32_e32 v51, v0
	v_mov_b32_e32 v52, v0
	v_mov_b32_e32 v53, v0
	v_mov_b32_e32 v54, v0
	v_mov_b32_e32 v55, v0
	v_mov_b32_e32 v12, v0
	v_mov_b32_e32 v13, v0
	v_mov_b32_e32 v14, v0
	v_mov_b32_e32 v15, v0
	v_mov_b32_e32 v4, v0
	v_mov_b32_e32 v5, v0
	v_mov_b32_e32 v6, v0
	v_mov_b32_e32 v7, v0
	v_mov_b32_e32 v24, v0
	v_mov_b32_e32 v25, v0
	v_mov_b32_e32 v26, v0
	v_mov_b32_e32 v27, v0
	v_mov_b32_e32 v28, v0
	v_mov_b32_e32 v29, v0
	v_mov_b32_e32 v30, v0
	v_mov_b32_e32 v31, v0
	v_mov_b32_e32 v40, v0
	v_mov_b32_e32 v41, v0
	v_mov_b32_e32 v42, v0
	v_mov_b32_e32 v43, v0
	v_mov_b32_e32 v44, v0
	v_mov_b32_e32 v45, v0
	v_mov_b32_e32 v46, v0
	v_mov_b32_e32 v47, v0
	v_mov_b32_e32 v56, v0
	v_mov_b32_e32 v57, v0
	v_mov_b32_e32 v58, v0
	v_mov_b32_e32 v59, v0
	v_mov_b32_e32 v60, v0
	v_mov_b32_e32 v61, v0
	v_mov_b32_e32 v62, v0
	v_mov_b32_e32 v63, v0
	v_mov_b32_e32 v64, v0
	v_mov_b32_e32 v65, v0
	v_mov_b32_e32 v66, v0
	v_mov_b32_e32 v67, v0
	v_mov_b32_e32 v80, v0
	v_mov_b32_e32 v81, v0
	v_mov_b32_e32 v82, v0
	v_mov_b32_e32 v83, v0
	v_mov_b32_e32 v68, v0
	v_mov_b32_e32 v69, v0
	v_mov_b32_e32 v70, v0
	v_mov_b32_e32 v71, v0
	v_mov_b32_e32 v84, v0
	v_mov_b32_e32 v85, v0
	v_mov_b32_e32 v86, v0
	v_mov_b32_e32 v87, v0
	v_mov_b32_e32 v76, v0
	v_mov_b32_e32 v77, v0
	v_mov_b32_e32 v78, v0
	v_mov_b32_e32 v79, v0
	v_mov_b32_e32 v96, v0
	v_mov_b32_e32 v97, v0
	v_mov_b32_e32 v98, v0
	v_mov_b32_e32 v99, v0
	v_mov_b32_e32 v88, v0
	v_mov_b32_e32 v89, v0
	v_mov_b32_e32 v90, v0
	v_mov_b32_e32 v91, v0
	v_mov_b32_e32 v104, v0
	v_mov_b32_e32 v105, v0
	v_mov_b32_e32 v106, v0
	v_mov_b32_e32 v107, v0
	v_mov_b32_e32 v100, v0
	v_mov_b32_e32 v101, v0
	v_mov_b32_e32 v102, v0
	v_mov_b32_e32 v103, v0
	v_mov_b32_e32 v72, v0
	v_mov_b32_e32 v73, v0
	v_mov_b32_e32 v74, v0
	v_mov_b32_e32 v75, v0
	v_mov_b32_e32 v112, v0
	v_mov_b32_e32 v113, v0
	v_mov_b32_e32 v114, v0
	v_mov_b32_e32 v115, v0
	v_mov_b32_e32 v92, v0
	v_mov_b32_e32 v93, v0
	v_mov_b32_e32 v94, v0
	v_mov_b32_e32 v95, v0
	v_mov_b32_e32 v116, v0
	v_mov_b32_e32 v117, v0
	v_mov_b32_e32 v118, v0
	v_mov_b32_e32 v119, v0
	v_mov_b32_e32 v108, v0
	v_mov_b32_e32 v109, v0
	v_mov_b32_e32 v110, v0
	v_mov_b32_e32 v111, v0
	v_mov_b32_e32 v124, v0
	v_mov_b32_e32 v125, v0
	v_mov_b32_e32 v126, v0
	v_mov_b32_e32 v127, v0
	v_mov_b32_e32 v120, v0
	v_mov_b32_e32 v121, v0
	v_mov_b32_e32 v122, v0
	v_mov_b32_e32 v123, v0
	s_andn2_b64 vcc, exec, s[4:5]
	s_cbranch_vccnz .LBB0_744

; template <class Epi, class Sched, bool ALIGN_EPI = false, bool SP2 = false>
; __device__ __forceinline__ void gemm_phase(PG8_LAS unsigned char* lds, const Gemm g, const Sched& S, const Epi& E, const int wid) {
;     ...
;         const bool has_next = S.next(ui + 1, nxt);
;         const char* nA = has_next ? (const char*)g.A + (size_t)nxt.pm * tstep : cA; const char* nB = has_next ? (const char*)g.Bt + (size_t)nxt.pn * tstep : cB;
;         for (int t = 0; t < nt; t += 2) {
;             const bool last = (t == nt - 2);
;             const char* a1 = cA + (size_t)(t + 1) * kstep;
;             const char* a2 = last ? nA : cA + (size_t)(t + 2) * kstep; const char* b2 = last ? nB : cB + (size_t)(t + 2) * kstep;
;             const char* a3 = a2 + kstep; const char* b3 = b2 + kstep;
.LBB0_881:
	s_ashr_i32 s13, s12, 31
	s_lshl_b64 s[14:15], s[12:13], 19
	s_add_u32 s14, s80, s14
	s_addc_u32 s15, s81, s15
	s_and_b64 s[18:19], s[4:5], exec
	s_cselect_b32 s13, s15, s21
	s_cselect_b32 s43, s14, s20
	s_ashr_i32 s9, s8, 31
	s_lshl_b64 s[18:19], s[8:9], 19
	s_add_u32 s18, s10, s18
	s_addc_u32 s19, s11, s19
	s_and_b64 s[24:25], s[4:5], exec
	s_cselect_b32 s9, s19, s23
	s_cselect_b32 s44, s18, s22
	s_add_u32 s20, s20, 0x40080
	s_addc_u32 s21, s21, 0
	s_add_u32 s45, s22, 0x100

; template <class Epi, class Sched, bool ALIGN_EPI = false, bool SP2 = false>
; __device__ __forceinline__ void gemm_phase(PG8_LAS unsigned char* lds, const Gemm g, const Sched& S, const Epi& E, const int wid) {
;     ...
;         const bool has_next = S.next(ui + 1, nxt);
;         const char* nA = has_next ? (const char*)g.A + (size_t)nxt.pm * tstep : cA; const char* nB = has_next ? (const char*)g.Bt + (size_t)nxt.pn * tstep : cB;
;         for (int t = 0; t < nt; t += 2) {
;             const bool last = (t == nt - 2);
;             const char* a1 = cA + (size_t)(t + 1) * kstep;
;             const char* a2 = last ? nA : cA + (size_t)(t + 2) * kstep; const char* b2 = last ? nB : cB + (size_t)(t + 2) * kstep;
;             const char* a3 = a2 + kstep; const char* b3 = b2 + kstep;
	s_addc_u32 s46, s23, 0
	s_mov_b32 s47, -2


; #define PG8_STAGE(bufoff, gbase, voff) do { _Pragma("unroll") for (int _i = 0; _i < 2; ++_i) \
;         __builtin_amdgcn_global_load_lds((const unsigned*)((const char*)(gbase) + (voff)[_i]), (PG8_LAS unsigned*)(lds + (bufoff) + ldsw + _i * 8192), 16, 0, 0); } while (0)
; #define PG8_LDA(dst, b, h) do { _Pragma("unroll") for (int m = 0; m < 4; ++m) _Pragma("unroll") for (int k = 0; k < 2; ++k) dst[m][k] = *(const PG8_LAS bf16x8*)(lds + PG8_SA(b, h) + aoff + m * 2048 + k * 1024); } while (0)
; #define PG8_LDB(dst, b, h) do { _Pragma("unroll") for (int n = 0; n < 2; ++n) _Pragma("unroll") for (int k = 0; k < 2; ++k) dst[n][k] = *(const PG8_LAS bf16x8*)(lds + PG8_SB(b, h) + boff + n * 2048 + k * 1024); } while (0)
; #define PG8_MMA(ai, bj, At, Bt) do { __builtin_amdgcn_s_setprio(1); _Pragma("unroll") for (int m = 0; m < 4; ++m) _Pragma("unroll") for (int n = 0; n < 2; ++n) _Pragma("unroll") for (int k = 0; k < 2; ++k) \
;         acc[ai][bj][m][n] = __builtin_amdgcn_mfma_f32_16x16x32_bf16(Bt[n][k], At[m][k], acc[ai][bj][m][n], 0, 0, 0); __builtin_amdgcn_s_setprio(0); } while (0)
; #define PG8_WAIT_V(n) asm volatile("s_waitcnt vmcnt(" #n ")" ::: "memory")
; #define PG8_BAR __builtin_amdgcn_s_barrier()
; template <class Epi, class Sched, bool ALIGN_EPI = false, bool SP2 = false>
; __device__ __forceinline__ void gemm_phase(PG8_LAS unsigned char* lds, const Gemm g, const Sched& S, const Epi& E, const int wid) {
;     ...
;         for (int t = 0; t < nt; t += 2) {
;             const bool last = (t == nt - 2);
;             const char* a1 = cA + (size_t)(t + 1) * kstep;
;             const char* a2 = last ? nA : cA + (size_t)(t + 2) * kstep; const char* b2 = last ? nB : cB + (size_t)(t + 2) * kstep;
;             const char* a3 = a2 + kstep; const char* b3 = b2 + kstep;
;             if (last && has_next) S.a_ready(nxt);
;             if constexpr (SP2) {
;             PG8_LDB(B0, 0, 0); PG8_LDB(B1, 0, 1); PG8_SCHED; PG8_LDA(At, 0, 0); PG8_STAGE(PG8_SA(1, 1), a1 + hstep, voffA);
;             PG8_WAIT_V(8); PG8_WAIT_L(0); PG8_BAR; PG8_MMA(0, 0, At, B0); PG8_MMA(0, 1, At, B1); PG8_BAR; PG8_SCHED;
;             PG8_LDA(At, 0, 1); PG8_STAGE(PG8_SB(0, 0), b2, voffB); PG8_STAGE(PG8_SB(0, 1), b2 + hstep, voffB); PG8_STAGE(PG8_SA(0, 0), a2, voffA);
;             PG8_WAIT_V(8); PG8_WAIT_L(0); PG8_BAR; PG8_MMA(1, 0, At, B0); PG8_MMA(1, 1, At, B1); PG8_BAR; PG8_SCHED;
	ds_read_b128 v[152:155], v149
	ds_read_b128 v[156:159], v149 offset:1024
	ds_read_b128 v[160:163], v149 offset:2048
	ds_read_b128 v[164:167], v149 offset:3072
	ds_read_b128 v[168:171], v150
	ds_read_b128 v[172:175], v150 offset:1024
	ds_read_b128 v[176:179], v150 offset:2048
	ds_read_b128 v[180:183], v150 offset:3072
	s_add_u32 s22, s20, 0xfffc0080
	s_addc_u32 s23, s21, -1
	s_cmp_eq_u32 s47, 12
	s_cselect_b32 s25, s13, s23
	s_cselect_b32 s24, s43, s22
	s_cselect_b32 s23, s9, s46
	s_cselect_b32 s22, s44, s45
	v_lshl_add_u64 v[144:145], s[20:21], 0, v[136:137]
	s_add_i32 m0, s17, 0xc000
	ds_read_b128 v[184:187], v151
	ds_read_b128 v[188:191], v151 offset:1024
	ds_read_b128 v[192:195], v151 offset:2048
	ds_read_b128 v[196:199], v151 offset:3072
	ds_read_b128 v[200:203], v151 offset:4096
	ds_read_b128 v[204:207], v151 offset:5120
	ds_read_b128 v[212:215], v151 offset:6144
	ds_read_b128 v[216:219], v151 offset:7168
	global_load_lds_dwordx4 v[144:145], off
	v_lshl_add_u64 v[144:145], s[20:21], 0, v[138:139]
	s_add_i32 m0, s17, 0xe000
	s_nop 0
	global_load_lds_dwordx4 v[144:145], off
	s_waitcnt vmcnt(8)
	s_waitcnt lgkmcnt(0)
	s_barrier
	s_waitcnt lgkmcnt(0)
	v_mfma_f32_16x16x32_bf16 v[124:127], v[152:155], v[184:187], 0
	v_mfma_f32_16x16x32_bf16 v[120:123], v[160:163], v[184:187], 0
	v_mfma_f32_16x16x32_bf16 v[116:119], v[152:155], v[192:195], 0
	v_mfma_f32_16x16x32_bf16 v[108:111], v[160:163], v[192:195], 0
	v_mfma_f32_16x16x32_bf16 v[100:103], v[152:155], v[200:203], 0
	v_mfma_f32_16x16x32_bf16 v[92:95], v[160:163], v[200:203], 0
	v_mfma_f32_16x16x32_bf16 v[84:87], v[152:155], v[212:215], 0
	v_mfma_f32_16x16x32_bf16 v[76:79], v[160:163], v[212:215], 0
	v_mfma_f32_16x16x32_bf16 v[124:127], v[156:159], v[188:191], v[124:127]
	v_mfma_f32_16x16x32_bf16 v[120:123], v[164:167], v[188:191], v[120:123]
	v_mfma_f32_16x16x32_bf16 v[116:119], v[156:159], v[196:199], v[116:119]
	v_mfma_f32_16x16x32_bf16 v[108:111], v[164:167], v[196:199], v[108:111]
	v_mfma_f32_16x16x32_bf16 v[100:103], v[156:159], v[204:207], v[100:103]
	v_mfma_f32_16x16x32_bf16 v[92:95], v[164:167], v[204:207], v[92:95]
	v_mfma_f32_16x16x32_bf16 v[84:87], v[156:159], v[216:219], v[84:87]
	v_mfma_f32_16x16x32_bf16 v[76:79], v[164:167], v[216:219], v[76:79]
	v_mfma_f32_16x16x32_bf16 v[112:115], v[168:171], v[184:187], 0
	v_mfma_f32_16x16x32_bf16 v[104:107], v[176:179], v[184:187], 0
	v_mfma_f32_16x16x32_bf16 v[96:99], v[168:171], v[192:195], 0
	v_mfma_f32_16x16x32_bf16 v[88:91], v[176:179], v[192:195], 0
	v_mfma_f32_16x16x32_bf16 v[80:83], v[168:171], v[200:203], 0
	v_mfma_f32_16x16x32_bf16 v[72:75], v[176:179], v[200:203], 0
	v_mfma_f32_16x16x32_bf16 v[68:71], v[168:171], v[212:215], 0
	v_mfma_f32_16x16x32_bf16 v[64:67], v[176:179], v[212:215], 0
	v_mfma_f32_16x16x32_bf16 v[112:115], v[172:175], v[188:191], v[112:115]
	v_mfma_f32_16x16x32_bf16 v[104:107], v[180:183], v[188:191], v[104:107]
	v_mfma_f32_16x16x32_bf16 v[96:99], v[172:175], v[196:199], v[96:99]
	v_mfma_f32_16x16x32_bf16 v[88:91], v[180:183], v[196:199], v[88:91]
	v_mfma_f32_16x16x32_bf16 v[80:83], v[172:175], v[204:207], v[80:83]
	v_mfma_f32_16x16x32_bf16 v[72:75], v[180:183], v[204:207], v[72:75]
	v_mfma_f32_16x16x32_bf16 v[68:71], v[172:175], v[216:219], v[68:71]
	v_mfma_f32_16x16x32_bf16 v[64:67], v[180:183], v[216:219], v[64:67]
	s_barrier
	s_add_i32 s48, s39, s26
	v_lshl_add_u64 v[144:145], s[22:23], 0, v[132:133]
	s_mov_b32 m0, s48
	ds_read_b128 v[184:187], v151 offset:16384
	ds_read_b128 v[188:191], v151 offset:17408
	ds_read_b128 v[192:195], v151 offset:18432
	ds_read_b128 v[196:199], v151 offset:19456
	ds_read_b128 v[200:203], v151 offset:20480
	ds_read_b128 v[204:207], v151 offset:21504
	ds_read_b128 v[212:215], v151 offset:22528
	ds_read_b128 v[216:219], v151 offset:23552
	global_load_lds_dwordx4 v[144:145], off
	s_add_i32 m0, s48, 0x2000
	s_add_u32 s48, s22, 0x40000
	v_lshl_add_u64 v[220:221], s[22:23], 0, v[128:129]
	s_addc_u32 s49, s23, 0
	s_add_i32 s50, s40, s26
	global_load_lds_dwordx4 v[220:221], off
	v_lshl_add_u64 v[222:223], s[48:49], 0, v[132:133]
	s_mov_b32 m0, s50
	v_lshl_add_u64 v[224:225], s[24:25], 0, v[130:131]
	global_load_lds_dwordx4 v[222:223], off
	v_lshl_add_u64 v[222:223], s[48:49], 0, v[128:129]
	s_add_i32 m0, s50, 0x2000
	s_nop 0
	global_load_lds_dwordx4 v[222:223], off
	v_lshl_add_u64 v[222:223], s[24:25], 0, v[134:135]
	s_mov_b32 m0, s17
	s_nop 0
	global_load_lds_dwordx4 v[222:223], off
	s_mov_b32 m0, s29
	s_nop 0
	global_load_lds_dwordx4 v[224:225], off
	s_waitcnt vmcnt(8)
	s_waitcnt lgkmcnt(0)
	s_barrier
	s_waitcnt lgkmcnt(0)
	v_mfma_f32_16x16x32_bf16 v[60:63], v[152:155], v[184:187], 0
	v_mfma_f32_16x16x32_bf16 v[56:59], v[160:163], v[184:187], 0
	v_mfma_f32_16x16x32_bf16 v[52:55], v[152:155], v[192:195], 0
	v_mfma_f32_16x16x32_bf16 v[44:47], v[160:163], v[192:195], 0
	v_mfma_f32_16x16x32_bf16 v[36:39], v[152:155], v[200:203], 0
	v_mfma_f32_16x16x32_bf16 v[28:31], v[160:163], v[200:203], 0
	v_mfma_f32_16x16x32_bf16 v[20:23], v[152:155], v[212:215], 0
	v_mfma_f32_16x16x32_bf16 v[12:15], v[160:163], v[212:215], 0
	v_mfma_f32_16x16x32_bf16 v[60:63], v[156:159], v[188:191], v[60:63]
	v_mfma_f32_16x16x32_bf16 v[56:59], v[164:167], v[188:191], v[56:59]
	v_mfma_f32_16x16x32_bf16 v[52:55], v[156:159], v[196:199], v[52:55]
	v_mfma_f32_16x16x32_bf16 v[44:47], v[164:167], v[196:199], v[44:47]
	v_mfma_f32_16x16x32_bf16 v[36:39], v[156:159], v[204:207], v[36:39]
	v_mfma_f32_16x16x32_bf16 v[28:31], v[164:167], v[204:207], v[28:31]
	v_mfma_f32_16x16x32_bf16 v[20:23], v[156:159], v[216:219], v[20:23]
	v_mfma_f32_16x16x32_bf16 v[12:15], v[164:167], v[216:219], v[12:15]
	v_mfma_f32_16x16x32_bf16 v[48:51], v[168:171], v[184:187], 0
	v_mfma_f32_16x16x32_bf16 v[40:43], v[176:179], v[184:187], 0
	v_mfma_f32_16x16x32_bf16 v[32:35], v[168:171], v[192:195], 0
	v_mfma_f32_16x16x32_bf16 v[24:27], v[176:179], v[192:195], 0
	v_mfma_f32_16x16x32_bf16 v[16:19], v[168:171], v[200:203], 0
	v_mfma_f32_16x16x32_bf16 v[8:11], v[176:179], v[200:203], 0
	v_mfma_f32_16x16x32_bf16 v[4:7], v[168:171], v[212:215], 0
	v_mfma_f32_16x16x32_bf16 v[0:3], v[176:179], v[212:215], 0
	v_mfma_f32_16x16x32_bf16 v[48:51], v[172:175], v[188:191], v[48:51]
	v_mfma_f32_16x16x32_bf16 v[40:43], v[180:183], v[188:191], v[40:43]
	v_mfma_f32_16x16x32_bf16 v[32:35], v[172:175], v[196:199], v[32:35]
	v_mfma_f32_16x16x32_bf16 v[24:27], v[180:183], v[196:199], v[24:27]
	v_mfma_f32_16x16x32_bf16 v[16:19], v[172:175], v[204:207], v[16:19]
	v_mfma_f32_16x16x32_bf16 v[8:11], v[180:183], v[204:207], v[8:11]
	v_mfma_f32_16x16x32_bf16 v[4:7], v[172:175], v[216:219], v[4:7]
	v_mfma_f32_16x16x32_bf16 v[0:3], v[180:183], v[216:219], v[0:3]
	s_barrier
; #define PG8_STAGE(bufoff, gbase, voff) do { _Pragma("unroll") for (int _i = 0; _i < 2; ++_i) \
;         __builtin_amdgcn_global_load_lds((const unsigned*)((const char*)(gbase) + (voff)[_i]), (PG8_LAS unsigned*)(lds + (bufoff) + ldsw + _i * 8192), 16, 0, 0); } while (0)
; #define PG8_LDA(dst, b, h) do { _Pragma("unroll") for (int m = 0; m < 4; ++m) _Pragma("unroll") for (int k = 0; k < 2; ++k) dst[m][k] = *(const PG8_LAS bf16x8*)(lds + PG8_SA(b, h) + aoff + m * 2048 + k * 1024); } while (0)
; #define PG8_LDB(dst, b, h) do { _Pragma("unroll") for (int n = 0; n < 2; ++n) _Pragma("unroll") for (int k = 0; k < 2; ++k) dst[n][k] = *(const PG8_LAS bf16x8*)(lds + PG8_SB(b, h) + boff + n * 2048 + k * 1024); } while (0)
; #define PG8_MMA(ai, bj, At, Bt) do { __builtin_amdgcn_s_setprio(1); _Pragma("unroll") for (int m = 0; m < 4; ++m) _Pragma("unroll") for (int n = 0; n < 2; ++n) _Pragma("unroll") for (int k = 0; k < 2; ++k) \
;         acc[ai][bj][m][n] = __builtin_amdgcn_mfma_f32_16x16x32_bf16(Bt[n][k], At[m][k], acc[ai][bj][m][n], 0, 0, 0); __builtin_amdgcn_s_setprio(0); } while (0)
; #define PG8_WAIT_V(n) asm volatile("s_waitcnt vmcnt(" #n ")" ::: "memory")
; #define PG8_WAIT_L(n) asm volatile("s_waitcnt lgkmcnt(" #n ")" ::: "memory")
; #define PG8_BAR __builtin_amdgcn_s_barrier()
; #define PG8_SCHED __builtin_amdgcn_sched_barrier(0)
; template <class Epi, class Sched, bool ALIGN_EPI = false, bool SP2 = false>
; __device__ __forceinline__ void gemm_phase(PG8_LAS unsigned char* lds, const Gemm g, const Sched& S, const Epi& E, const int wid) {
;     ...
;             PG8_LDB(B0, 1, 0); PG8_LDB(B1, 1, 1); PG8_SCHED; PG8_LDA(At, 1, 0); PG8_STAGE(PG8_SA(0, 1), a2 + hstep, voffA);
;             PG8_WAIT_V(8); PG8_WAIT_L(0); PG8_BAR; PG8_MMA(0, 0, At, B0); PG8_MMA(0, 1, At, B1); PG8_BAR; PG8_SCHED;
;             PG8_LDA(At, 1, 1); PG8_STAGE(PG8_SB(1, 0), b3, voffB); PG8_STAGE(PG8_SB(1, 1), b3 + hstep, voffB); PG8_STAGE(PG8_SA(1, 0), a3, voffA);
;             PG8_WAIT_V(8); PG8_WAIT_L(0); PG8_BAR; PG8_MMA(1, 0, At, B0); PG8_MMA(1, 1, At, B1); PG8_BAR; PG8_SCHED;
	s_add_i32 s48, 0, 0x18000
	s_add_i32 s49, 0, 0x1c000
	v_add_u32_e32 v164, s48, v147
	v_add_u32_e32 v180, s49, v147
	ds_read_b128 v[152:155], v164
	ds_read_b128 v[156:159], v164 offset:1024
	ds_read_b128 v[160:163], v164 offset:2048
	ds_read_b128 v[164:167], v164 offset:3072
	ds_read_b128 v[168:171], v180
	ds_read_b128 v[172:175], v180 offset:1024
	ds_read_b128 v[176:179], v180 offset:2048
	ds_read_b128 v[180:183], v180 offset:3072
	s_add_u32 s24, s24, 0x40000
	s_addc_u32 s25, s25, 0
	s_mov_b32 m0, s30
	v_lshl_add_u64 v[226:227], s[24:25], 0, v[134:135]
	ds_read_b128 v[184:187], v151 offset:32768
	ds_read_b128 v[188:191], v151 offset:33792
	ds_read_b128 v[192:195], v151 offset:34816
	ds_read_b128 v[196:199], v151 offset:35840
	ds_read_b128 v[200:203], v151 offset:36864
	ds_read_b128 v[204:207], v151 offset:37888
	ds_read_b128 v[212:215], v151 offset:38912
	ds_read_b128 v[216:219], v151 offset:39936
	global_load_lds_dwordx4 v[226:227], off
	v_lshl_add_u64 v[226:227], s[24:25], 0, v[130:131]
	s_mov_b32 m0, s31
	s_nop 0
	global_load_lds_dwordx4 v[226:227], off
	s_waitcnt vmcnt(8)
	s_waitcnt lgkmcnt(0)
	s_barrier
	s_waitcnt lgkmcnt(0)
	v_mfma_f32_16x16x32_bf16 v[124:127], v[152:155], v[184:187], v[124:127]
	v_mfma_f32_16x16x32_bf16 v[120:123], v[160:163], v[184:187], v[120:123]
	v_mfma_f32_16x16x32_bf16 v[116:119], v[152:155], v[192:195], v[116:119]
	v_mfma_f32_16x16x32_bf16 v[108:111], v[160:163], v[192:195], v[108:111]
	v_mfma_f32_16x16x32_bf16 v[100:103], v[152:155], v[200:203], v[100:103]
	v_mfma_f32_16x16x32_bf16 v[92:95], v[160:163], v[200:203], v[92:95]
	v_mfma_f32_16x16x32_bf16 v[84:87], v[152:155], v[212:215], v[84:87]
	v_mfma_f32_16x16x32_bf16 v[76:79], v[160:163], v[212:215], v[76:79]
	v_mfma_f32_16x16x32_bf16 v[124:127], v[156:159], v[188:191], v[124:127]
	v_mfma_f32_16x16x32_bf16 v[120:123], v[164:167], v[188:191], v[120:123]
	v_mfma_f32_16x16x32_bf16 v[116:119], v[156:159], v[196:199], v[116:119]
	v_mfma_f32_16x16x32_bf16 v[108:111], v[164:167], v[196:199], v[108:111]
	v_mfma_f32_16x16x32_bf16 v[100:103], v[156:159], v[204:207], v[100:103]
	v_mfma_f32_16x16x32_bf16 v[92:95], v[164:167], v[204:207], v[92:95]
	v_mfma_f32_16x16x32_bf16 v[84:87], v[156:159], v[216:219], v[84:87]
	v_mfma_f32_16x16x32_bf16 v[76:79], v[164:167], v[216:219], v[76:79]
	v_mfma_f32_16x16x32_bf16 v[112:115], v[168:171], v[184:187], v[112:115]
	v_mfma_f32_16x16x32_bf16 v[104:107], v[176:179], v[184:187], v[104:107]
	v_mfma_f32_16x16x32_bf16 v[96:99], v[168:171], v[192:195], v[96:99]
	v_mfma_f32_16x16x32_bf16 v[88:91], v[176:179], v[192:195], v[88:91]
	v_mfma_f32_16x16x32_bf16 v[80:83], v[168:171], v[200:203], v[80:83]
	v_mfma_f32_16x16x32_bf16 v[72:75], v[176:179], v[200:203], v[72:75]
	v_mfma_f32_16x16x32_bf16 v[68:71], v[168:171], v[212:215], v[68:71]
	v_mfma_f32_16x16x32_bf16 v[64:67], v[176:179], v[212:215], v[64:67]
	v_mfma_f32_16x16x32_bf16 v[112:115], v[172:175], v[188:191], v[112:115]
	v_mfma_f32_16x16x32_bf16 v[104:107], v[180:183], v[188:191], v[104:107]
	v_mfma_f32_16x16x32_bf16 v[96:99], v[172:175], v[196:199], v[96:99]
	v_mfma_f32_16x16x32_bf16 v[88:91], v[180:183], v[196:199], v[88:91]
	v_mfma_f32_16x16x32_bf16 v[80:83], v[172:175], v[204:207], v[80:83]
	v_mfma_f32_16x16x32_bf16 v[72:75], v[180:183], v[204:207], v[72:75]
	v_mfma_f32_16x16x32_bf16 v[68:71], v[172:175], v[216:219], v[68:71]
	v_mfma_f32_16x16x32_bf16 v[64:67], v[180:183], v[216:219], v[64:67]
	s_barrier
	s_add_i32 s24, s48, s26
	v_lshl_add_u64 v[144:145], v[144:145], 0, s[6:7]
	s_mov_b32 m0, s24
	ds_read_b128 v[184:187], v151 offset:49152
	ds_read_b128 v[188:191], v151 offset:50176
	ds_read_b128 v[192:195], v151 offset:51200
	ds_read_b128 v[196:199], v151 offset:52224
	ds_read_b128 v[200:203], v151 offset:53248
	ds_read_b128 v[204:207], v151 offset:54272
	ds_read_b128 v[212:215], v151 offset:55296
	ds_read_b128 v[216:219], v151 offset:56320
	global_load_lds_dwordx4 v[144:145], off
	s_add_i32 m0, s24, 0x2000
	s_add_u32 s22, s22, 0x40080
	v_lshl_add_u64 v[144:145], v[220:221], 0, s[6:7]
	s_addc_u32 s23, s23, 0
	s_add_i32 s24, s49, s26
	global_load_lds_dwordx4 v[144:145], off
	v_lshl_add_u64 v[144:145], s[22:23], 0, v[132:133]
	s_mov_b32 m0, s24
	s_nop 0
	global_load_lds_dwordx4 v[144:145], off
	v_lshl_add_u64 v[144:145], s[22:23], 0, v[128:129]
	s_add_i32 m0, s24, 0x2000
	s_nop 0
	global_load_lds_dwordx4 v[144:145], off
	v_lshl_add_u64 v[144:145], v[222:223], 0, s[6:7]
	s_mov_b32 m0, s37
	s_nop 0
	global_load_lds_dwordx4 v[144:145], off
	v_lshl_add_u64 v[144:145], v[224:225], 0, s[6:7]
	s_mov_b32 m0, s38
	s_nop 0
	global_load_lds_dwordx4 v[144:145], off
	s_waitcnt vmcnt(8)
	s_waitcnt lgkmcnt(0)
	s_barrier
; #define PG8_STAGE(bufoff, gbase, voff) do { _Pragma("unroll") for (int _i = 0; _i < 2; ++_i) \
;         __builtin_amdgcn_global_load_lds((const unsigned*)((const char*)(gbase) + (voff)[_i]), (PG8_LAS unsigned*)(lds + (bufoff) + ldsw + _i * 8192), 16, 0, 0); } while (0)
; #define PG8_LDA(dst, b, h) do { _Pragma("unroll") for (int m = 0; m < 4; ++m) _Pragma("unroll") for (int k = 0; k < 2; ++k) dst[m][k] = *(const PG8_LAS bf16x8*)(lds + PG8_SA(b, h) + aoff + m * 2048 + k * 1024); } while (0)
; #define PG8_WAIT_V(n) asm volatile("s_waitcnt vmcnt(" #n ")" ::: "memory")
; #define PG8_WAIT_L(n) asm volatile("s_waitcnt lgkmcnt(" #n ")" ::: "memory")
; #define PG8_BAR __builtin_amdgcn_s_barrier()
; template <class Epi, class Sched, bool ALIGN_EPI = false, bool SP2 = false>
; __device__ __forceinline__ void gemm_phase(PG8_LAS unsigned char* lds, const Gemm g, const Sched& S, const Epi& E, const int wid) {
;     ...
;         for (int t = 0; t < nt; t += 2) {
;             const bool last = (t == nt - 2);
;             const char* a1 = cA + (size_t)(t + 1) * kstep;
;             const char* a2 = last ? nA : cA + (size_t)(t + 2) * kstep; const char* b2 = last ? nB : cB + (size_t)(t + 2) * kstep;
;             const char* a3 = a2 + kstep; const char* b3 = b2 + kstep;
;             if (last && has_next) S.a_ready(nxt);
;             if constexpr (SP2) {
;             PG8_LDB(B0, 0, 0); PG8_LDB(B1, 0, 1); PG8_SCHED; PG8_LDA(At, 0, 0); PG8_STAGE(PG8_SA(1, 1), a1 + hstep, voffA);
;             PG8_WAIT_V(8); PG8_WAIT_L(0); PG8_BAR; PG8_MMA(0, 0, At, B0); PG8_MMA(0, 1, At, B1); PG8_BAR; PG8_SCHED;
;             PG8_LDA(At, 0, 1); PG8_STAGE(PG8_SB(0, 0), b2, voffB); PG8_STAGE(PG8_SB(0, 1), b2 + hstep, voffB); PG8_STAGE(PG8_SA(0, 0), a2, voffA);
;             PG8_WAIT_V(8); PG8_WAIT_L(0); PG8_BAR; PG8_MMA(1, 0, At, B0); PG8_MMA(1, 1, At, B1); PG8_BAR; PG8_SCHED;
;             PG8_LDB(B0, 1, 0); PG8_LDB(B1, 1, 1); PG8_SCHED; PG8_LDA(At, 1, 0); PG8_STAGE(PG8_SA(0, 1), a2 + hstep, voffA);
;             PG8_WAIT_V(8); PG8_WAIT_L(0); PG8_BAR; PG8_MMA(0, 0, At, B0); PG8_MMA(0, 1, At, B1); PG8_BAR; PG8_SCHED;
;             PG8_LDA(At, 1, 1); PG8_STAGE(PG8_SB(1, 0), b3, voffB); PG8_STAGE(PG8_SB(1, 1), b3 + hstep, voffB); PG8_STAGE(PG8_SA(1, 0), a3, voffA);
;             PG8_WAIT_V(8); PG8_WAIT_L(0); PG8_BAR; PG8_MMA(1, 0, At, B0); PG8_MMA(1, 1, At, B1); PG8_BAR; PG8_SCHED;
	s_waitcnt lgkmcnt(0)
	v_mfma_f32_16x16x32_bf16 v[60:63], v[152:155], v[184:187], v[60:63]
	v_mfma_f32_16x16x32_bf16 v[56:59], v[160:163], v[184:187], v[56:59]
	v_mfma_f32_16x16x32_bf16 v[52:55], v[152:155], v[192:195], v[52:55]
	v_mfma_f32_16x16x32_bf16 v[44:47], v[160:163], v[192:195], v[44:47]
	v_mfma_f32_16x16x32_bf16 v[36:39], v[152:155], v[200:203], v[36:39]
	v_mfma_f32_16x16x32_bf16 v[28:31], v[160:163], v[200:203], v[28:31]
	v_mfma_f32_16x16x32_bf16 v[20:23], v[152:155], v[212:215], v[20:23]
	v_mfma_f32_16x16x32_bf16 v[12:15], v[160:163], v[212:215], v[12:15]
	v_mfma_f32_16x16x32_bf16 v[60:63], v[156:159], v[188:191], v[60:63]
	v_mfma_f32_16x16x32_bf16 v[56:59], v[164:167], v[188:191], v[56:59]
	v_mfma_f32_16x16x32_bf16 v[52:55], v[156:159], v[196:199], v[52:55]
	v_mfma_f32_16x16x32_bf16 v[44:47], v[164:167], v[196:199], v[44:47]
	v_mfma_f32_16x16x32_bf16 v[36:39], v[156:159], v[204:207], v[36:39]
	v_mfma_f32_16x16x32_bf16 v[28:31], v[164:167], v[204:207], v[28:31]
	v_mfma_f32_16x16x32_bf16 v[20:23], v[156:159], v[216:219], v[20:23]
	v_mfma_f32_16x16x32_bf16 v[12:15], v[164:167], v[216:219], v[12:15]
	v_mfma_f32_16x16x32_bf16 v[48:51], v[168:171], v[184:187], v[48:51]
	v_mfma_f32_16x16x32_bf16 v[40:43], v[176:179], v[184:187], v[40:43]
	v_mfma_f32_16x16x32_bf16 v[32:35], v[168:171], v[192:195], v[32:35]
	v_mfma_f32_16x16x32_bf16 v[24:27], v[176:179], v[192:195], v[24:27]
	v_mfma_f32_16x16x32_bf16 v[16:19], v[168:171], v[200:203], v[16:19]
	v_mfma_f32_16x16x32_bf16 v[8:11], v[176:179], v[200:203], v[8:11]
	v_mfma_f32_16x16x32_bf16 v[4:7], v[168:171], v[212:215], v[4:7]
	v_mfma_f32_16x16x32_bf16 v[0:3], v[176:179], v[212:215], v[0:3]
	v_mfma_f32_16x16x32_bf16 v[48:51], v[172:175], v[188:191], v[48:51]
	v_mfma_f32_16x16x32_bf16 v[40:43], v[180:183], v[188:191], v[40:43]
	v_mfma_f32_16x16x32_bf16 v[32:35], v[172:175], v[196:199], v[32:35]
	v_mfma_f32_16x16x32_bf16 v[24:27], v[180:183], v[196:199], v[24:27]
	v_mfma_f32_16x16x32_bf16 v[16:19], v[172:175], v[204:207], v[16:19]
	v_mfma_f32_16x16x32_bf16 v[8:11], v[180:183], v[204:207], v[8:11]
	v_mfma_f32_16x16x32_bf16 v[4:7], v[172:175], v[216:219], v[4:7]
	v_mfma_f32_16x16x32_bf16 v[0:3], v[180:183], v[216:219], v[0:3]
	s_barrier
	s_add_i32 s47, s47, 2
	s_add_u32 s20, s20, 0x100
	s_addc_u32 s21, s21, 0
	s_add_u32 s45, s45, 0x100
	s_addc_u32 s46, s46, 0
	s_cmp_gt_u32 s47, 13
	s_cbranch_scc0 .LBB0_882
	s_branch .Lkp_exit_2
.LBB0_882:
	ds_read_b128 v[152:155], v149
	ds_read_b128 v[156:159], v149 offset:1024
	ds_read_b128 v[160:163], v149 offset:2048
	ds_read_b128 v[164:167], v149 offset:3072
	ds_read_b128 v[168:171], v150
	ds_read_b128 v[172:175], v150 offset:1024
	ds_read_b128 v[176:179], v150 offset:2048
	ds_read_b128 v[180:183], v150 offset:3072
	s_add_u32 s22, s20, 0xfffc0080
	s_addc_u32 s23, s21, -1
	s_cmp_eq_u32 s47, 12
	s_cselect_b32 s25, s13, s23
	s_cselect_b32 s24, s43, s22
	s_cselect_b32 s23, s9, s46
	s_cselect_b32 s22, s44, s45
	v_lshl_add_u64 v[144:145], s[20:21], 0, v[136:137]
	s_add_i32 m0, s17, 0xc000
	ds_read_b128 v[184:187], v151
	ds_read_b128 v[188:191], v151 offset:1024
	ds_read_b128 v[192:195], v151 offset:2048
	ds_read_b128 v[196:199], v151 offset:3072
	ds_read_b128 v[200:203], v151 offset:4096
	ds_read_b128 v[204:207], v151 offset:5120
	ds_read_b128 v[212:215], v151 offset:6144
	ds_read_b128 v[216:219], v151 offset:7168
	global_load_lds_dwordx4 v[144:145], off
	v_lshl_add_u64 v[144:145], s[20:21], 0, v[138:139]
	s_add_i32 m0, s17, 0xe000
	s_nop 0
	global_load_lds_dwordx4 v[144:145], off
	s_waitcnt vmcnt(8)
	s_waitcnt lgkmcnt(0)
	s_barrier
	s_waitcnt lgkmcnt(0)
	v_mfma_f32_16x16x32_bf16 v[124:127], v[152:155], v[184:187], v[124:127]
	v_mfma_f32_16x16x32_bf16 v[120:123], v[160:163], v[184:187], v[120:123]
	v_mfma_f32_16x16x32_bf16 v[116:119], v[152:155], v[192:195], v[116:119]
	v_mfma_f32_16x16x32_bf16 v[108:111], v[160:163], v[192:195], v[108:111]
	v_mfma_f32_16x16x32_bf16 v[100:103], v[152:155], v[200:203], v[100:103]
	v_mfma_f32_16x16x32_bf16 v[92:95], v[160:163], v[200:203], v[92:95]
	v_mfma_f32_16x16x32_bf16 v[84:87], v[152:155], v[212:215], v[84:87]
	v_mfma_f32_16x16x32_bf16 v[76:79], v[160:163], v[212:215], v[76:79]
	v_mfma_f32_16x16x32_bf16 v[124:127], v[156:159], v[188:191], v[124:127]
	v_mfma_f32_16x16x32_bf16 v[120:123], v[164:167], v[188:191], v[120:123]
	v_mfma_f32_16x16x32_bf16 v[116:119], v[156:159], v[196:199], v[116:119]
	v_mfma_f32_16x16x32_bf16 v[108:111], v[164:167], v[196:199], v[108:111]
	v_mfma_f32_16x16x32_bf16 v[100:103], v[156:159], v[204:207], v[100:103]
	v_mfma_f32_16x16x32_bf16 v[92:95], v[164:167], v[204:207], v[92:95]
	v_mfma_f32_16x16x32_bf16 v[84:87], v[156:159], v[216:219], v[84:87]
	v_mfma_f32_16x16x32_bf16 v[76:79], v[164:167], v[216:219], v[76:79]
	v_mfma_f32_16x16x32_bf16 v[112:115], v[168:171], v[184:187], v[112:115]
	v_mfma_f32_16x16x32_bf16 v[104:107], v[176:179], v[184:187], v[104:107]
	v_mfma_f32_16x16x32_bf16 v[96:99], v[168:171], v[192:195], v[96:99]
	v_mfma_f32_16x16x32_bf16 v[88:91], v[176:179], v[192:195], v[88:91]
	v_mfma_f32_16x16x32_bf16 v[80:83], v[168:171], v[200:203], v[80:83]
	v_mfma_f32_16x16x32_bf16 v[72:75], v[176:179], v[200:203], v[72:75]
	v_mfma_f32_16x16x32_bf16 v[68:71], v[168:171], v[212:215], v[68:71]
	v_mfma_f32_16x16x32_bf16 v[64:67], v[176:179], v[212:215], v[64:67]
	v_mfma_f32_16x16x32_bf16 v[112:115], v[172:175], v[188:191], v[112:115]
	v_mfma_f32_16x16x32_bf16 v[104:107], v[180:183], v[188:191], v[104:107]
	v_mfma_f32_16x16x32_bf16 v[96:99], v[172:175], v[196:199], v[96:99]
	v_mfma_f32_16x16x32_bf16 v[88:91], v[180:183], v[196:199], v[88:91]
	v_mfma_f32_16x16x32_bf16 v[80:83], v[172:175], v[204:207], v[80:83]
	v_mfma_f32_16x16x32_bf16 v[72:75], v[180:183], v[204:207], v[72:75]
	v_mfma_f32_16x16x32_bf16 v[68:71], v[172:175], v[216:219], v[68:71]
	v_mfma_f32_16x16x32_bf16 v[64:67], v[180:183], v[216:219], v[64:67]
	s_barrier
; #define PG8_STAGE(bufoff, gbase, voff) do { _Pragma("unroll") for (int _i = 0; _i < 2; ++_i) \
;         __builtin_amdgcn_global_load_lds((const unsigned*)((const char*)(gbase) + (voff)[_i]), (PG8_LAS unsigned*)(lds + (bufoff) + ldsw + _i * 8192), 16, 0, 0); } while (0)
; #define PG8_LDA(dst, b, h) do { _Pragma("unroll") for (int m = 0; m < 4; ++m) _Pragma("unroll") for (int k = 0; k < 2; ++k) dst[m][k] = *(const PG8_LAS bf16x8*)(lds + PG8_SA(b, h) + aoff + m * 2048 + k * 1024); } while (0)
; #define PG8_LDB(dst, b, h) do { _Pragma("unroll") for (int n = 0; n < 2; ++n) _Pragma("unroll") for (int k = 0; k < 2; ++k) dst[n][k] = *(const PG8_LAS bf16x8*)(lds + PG8_SB(b, h) + boff + n * 2048 + k * 1024); } while (0)
; #define PG8_MMA(ai, bj, At, Bt) do { __builtin_amdgcn_s_setprio(1); _Pragma("unroll") for (int m = 0; m < 4; ++m) _Pragma("unroll") for (int n = 0; n < 2; ++n) _Pragma("unroll") for (int k = 0; k < 2; ++k) \
;         acc[ai][bj][m][n] = __builtin_amdgcn_mfma_f32_16x16x32_bf16(Bt[n][k], At[m][k], acc[ai][bj][m][n], 0, 0, 0); __builtin_amdgcn_s_setprio(0); } while (0)
; #define PG8_WAIT_V(n) asm volatile("s_waitcnt vmcnt(" #n ")" ::: "memory")
; #define PG8_WAIT_L(n) asm volatile("s_waitcnt lgkmcnt(" #n ")" ::: "memory")
; #define PG8_BAR __builtin_amdgcn_s_barrier()
; #define PG8_SCHED __builtin_amdgcn_sched_barrier(0)
; template <class Epi, class Sched, bool ALIGN_EPI = false, bool SP2 = false>
; __device__ __forceinline__ void gemm_phase(PG8_LAS unsigned char* lds, const Gemm g, const Sched& S, const Epi& E, const int wid) {
;     ...
;             PG8_LDB(B0, 0, 0); PG8_LDB(B1, 0, 1); PG8_SCHED; PG8_LDA(At, 0, 0); PG8_STAGE(PG8_SA(1, 1), a1 + hstep, voffA);
;             PG8_WAIT_V(8); PG8_WAIT_L(0); PG8_BAR; PG8_MMA(0, 0, At, B0); PG8_MMA(0, 1, At, B1); PG8_BAR; PG8_SCHED;
;             PG8_LDA(At, 0, 1); PG8_STAGE(PG8_SB(0, 0), b2, voffB); PG8_STAGE(PG8_SB(0, 1), b2 + hstep, voffB); PG8_STAGE(PG8_SA(0, 0), a2, voffA);
;             PG8_WAIT_V(8); PG8_WAIT_L(0); PG8_BAR; PG8_MMA(1, 0, At, B0); PG8_MMA(1, 1, At, B1); PG8_BAR; PG8_SCHED;
;             PG8_LDB(B0, 1, 0); PG8_LDB(B1, 1, 1); PG8_SCHED; PG8_LDA(At, 1, 0); PG8_STAGE(PG8_SA(0, 1), a2 + hstep, voffA);
;             PG8_WAIT_V(8); PG8_WAIT_L(0); PG8_BAR; PG8_MMA(0, 0, At, B0); PG8_MMA(0, 1, At, B1); PG8_BAR; PG8_SCHED;
	s_add_i32 s48, s39, s26
	v_lshl_add_u64 v[144:145], s[22:23], 0, v[132:133]
	s_mov_b32 m0, s48
	ds_read_b128 v[184:187], v151 offset:16384
	ds_read_b128 v[188:191], v151 offset:17408
	ds_read_b128 v[192:195], v151 offset:18432
	ds_read_b128 v[196:199], v151 offset:19456
	ds_read_b128 v[200:203], v151 offset:20480
	ds_read_b128 v[204:207], v151 offset:21504
	ds_read_b128 v[212:215], v151 offset:22528
	ds_read_b128 v[216:219], v151 offset:23552
	global_load_lds_dwordx4 v[144:145], off
	s_add_i32 m0, s48, 0x2000
	s_add_u32 s48, s22, 0x40000
	v_lshl_add_u64 v[220:221], s[22:23], 0, v[128:129]
	s_addc_u32 s49, s23, 0
	s_add_i32 s50, s40, s26
	global_load_lds_dwordx4 v[220:221], off
	v_lshl_add_u64 v[222:223], s[48:49], 0, v[132:133]
	s_mov_b32 m0, s50
	v_lshl_add_u64 v[224:225], s[24:25], 0, v[130:131]
	global_load_lds_dwordx4 v[222:223], off
	v_lshl_add_u64 v[222:223], s[48:49], 0, v[128:129]
	s_add_i32 m0, s50, 0x2000
	s_nop 0
	global_load_lds_dwordx4 v[222:223], off
	v_lshl_add_u64 v[222:223], s[24:25], 0, v[134:135]
	s_mov_b32 m0, s17
	s_nop 0
	global_load_lds_dwordx4 v[222:223], off
	s_mov_b32 m0, s29
	s_nop 0
	global_load_lds_dwordx4 v[224:225], off
	s_waitcnt vmcnt(8)
	s_waitcnt lgkmcnt(0)
	s_barrier
	s_waitcnt lgkmcnt(0)
	v_mfma_f32_16x16x32_bf16 v[60:63], v[152:155], v[184:187], v[60:63]
	v_mfma_f32_16x16x32_bf16 v[56:59], v[160:163], v[184:187], v[56:59]
	v_mfma_f32_16x16x32_bf16 v[52:55], v[152:155], v[192:195], v[52:55]
	v_mfma_f32_16x16x32_bf16 v[44:47], v[160:163], v[192:195], v[44:47]
	v_mfma_f32_16x16x32_bf16 v[36:39], v[152:155], v[200:203], v[36:39]
	v_mfma_f32_16x16x32_bf16 v[28:31], v[160:163], v[200:203], v[28:31]
	v_mfma_f32_16x16x32_bf16 v[20:23], v[152:155], v[212:215], v[20:23]
	v_mfma_f32_16x16x32_bf16 v[12:15], v[160:163], v[212:215], v[12:15]
	v_mfma_f32_16x16x32_bf16 v[60:63], v[156:159], v[188:191], v[60:63]
	v_mfma_f32_16x16x32_bf16 v[56:59], v[164:167], v[188:191], v[56:59]
	v_mfma_f32_16x16x32_bf16 v[52:55], v[156:159], v[196:199], v[52:55]
	v_mfma_f32_16x16x32_bf16 v[44:47], v[164:167], v[196:199], v[44:47]
	v_mfma_f32_16x16x32_bf16 v[36:39], v[156:159], v[204:207], v[36:39]
	v_mfma_f32_16x16x32_bf16 v[28:31], v[164:167], v[204:207], v[28:31]
	v_mfma_f32_16x16x32_bf16 v[20:23], v[156:159], v[216:219], v[20:23]
	v_mfma_f32_16x16x32_bf16 v[12:15], v[164:167], v[216:219], v[12:15]
	v_mfma_f32_16x16x32_bf16 v[48:51], v[168:171], v[184:187], v[48:51]
	v_mfma_f32_16x16x32_bf16 v[40:43], v[176:179], v[184:187], v[40:43]
	v_mfma_f32_16x16x32_bf16 v[32:35], v[168:171], v[192:195], v[32:35]
	v_mfma_f32_16x16x32_bf16 v[24:27], v[176:179], v[192:195], v[24:27]
	v_mfma_f32_16x16x32_bf16 v[16:19], v[168:171], v[200:203], v[16:19]
	v_mfma_f32_16x16x32_bf16 v[8:11], v[176:179], v[200:203], v[8:11]
	v_mfma_f32_16x16x32_bf16 v[4:7], v[168:171], v[212:215], v[4:7]
	v_mfma_f32_16x16x32_bf16 v[0:3], v[176:179], v[212:215], v[0:3]
	v_mfma_f32_16x16x32_bf16 v[48:51], v[172:175], v[188:191], v[48:51]
	v_mfma_f32_16x16x32_bf16 v[40:43], v[180:183], v[188:191], v[40:43]
	v_mfma_f32_16x16x32_bf16 v[32:35], v[172:175], v[196:199], v[32:35]
	v_mfma_f32_16x16x32_bf16 v[24:27], v[180:183], v[196:199], v[24:27]
	v_mfma_f32_16x16x32_bf16 v[16:19], v[172:175], v[204:207], v[16:19]
	v_mfma_f32_16x16x32_bf16 v[8:11], v[180:183], v[204:207], v[8:11]
	v_mfma_f32_16x16x32_bf16 v[4:7], v[172:175], v[216:219], v[4:7]
	v_mfma_f32_16x16x32_bf16 v[0:3], v[180:183], v[216:219], v[0:3]
	s_barrier
	s_add_i32 s48, 0, 0x18000
	s_add_i32 s49, 0, 0x1c000
	v_add_u32_e32 v164, s48, v147
	v_add_u32_e32 v180, s49, v147
	ds_read_b128 v[152:155], v164
	ds_read_b128 v[156:159], v164 offset:1024
	ds_read_b128 v[160:163], v164 offset:2048
	ds_read_b128 v[164:167], v164 offset:3072
	ds_read_b128 v[168:171], v180
	ds_read_b128 v[172:175], v180 offset:1024
	ds_read_b128 v[176:179], v180 offset:2048
	ds_read_b128 v[180:183], v180 offset:3072
	s_add_u32 s24, s24, 0x40000
	s_addc_u32 s25, s25, 0
	s_mov_b32 m0, s30
	v_lshl_add_u64 v[226:227], s[24:25], 0, v[134:135]
	ds_read_b128 v[184:187], v151 offset:32768
	ds_read_b128 v[188:191], v151 offset:33792
	ds_read_b128 v[192:195], v151 offset:34816
	ds_read_b128 v[196:199], v151 offset:35840
	ds_read_b128 v[200:203], v151 offset:36864
	ds_read_b128 v[204:207], v151 offset:37888
	ds_read_b128 v[212:215], v151 offset:38912
	ds_read_b128 v[216:219], v151 offset:39936
	global_load_lds_dwordx4 v[226:227], off
	v_lshl_add_u64 v[226:227], s[24:25], 0, v[130:131]
	s_mov_b32 m0, s31
	s_nop 0
	global_load_lds_dwordx4 v[226:227], off
	s_waitcnt vmcnt(8)
	s_waitcnt lgkmcnt(0)
	s_barrier
; #define PG8_STAGE(bufoff, gbase, voff) do { _Pragma("unroll") for (int _i = 0; _i < 2; ++_i) \
;         __builtin_amdgcn_global_load_lds((const unsigned*)((const char*)(gbase) + (voff)[_i]), (PG8_LAS unsigned*)(lds + (bufoff) + ldsw + _i * 8192), 16, 0, 0); } while (0)
; #define PG8_LDA(dst, b, h) do { _Pragma("unroll") for (int m = 0; m < 4; ++m) _Pragma("unroll") for (int k = 0; k < 2; ++k) dst[m][k] = *(const PG8_LAS bf16x8*)(lds + PG8_SA(b, h) + aoff + m * 2048 + k * 1024); } while (0)
; #define PG8_WAIT_V(n) asm volatile("s_waitcnt vmcnt(" #n ")" ::: "memory")
; #define PG8_WAIT_L(n) asm volatile("s_waitcnt lgkmcnt(" #n ")" ::: "memory")
; #define PG8_BAR __builtin_amdgcn_s_barrier()
; template <class Epi, class Sched, bool ALIGN_EPI = false, bool SP2 = false>
; __device__ __forceinline__ void gemm_phase(PG8_LAS unsigned char* lds, const Gemm g, const Sched& S, const Epi& E, const int wid) {
;     ...
;         for (int t = 0; t < nt; t += 2) {
;             const bool last = (t == nt - 2);
;             const char* a1 = cA + (size_t)(t + 1) * kstep;
;             const char* a2 = last ? nA : cA + (size_t)(t + 2) * kstep; const char* b2 = last ? nB : cB + (size_t)(t + 2) * kstep;
;             const char* a3 = a2 + kstep; const char* b3 = b2 + kstep;
;             if (last && has_next) S.a_ready(nxt);
;             if constexpr (SP2) {
;             PG8_LDB(B0, 0, 0); PG8_LDB(B1, 0, 1); PG8_SCHED; PG8_LDA(At, 0, 0); PG8_STAGE(PG8_SA(1, 1), a1 + hstep, voffA);
;             PG8_WAIT_V(8); PG8_WAIT_L(0); PG8_BAR; PG8_MMA(0, 0, At, B0); PG8_MMA(0, 1, At, B1); PG8_BAR; PG8_SCHED;
;             PG8_LDA(At, 0, 1); PG8_STAGE(PG8_SB(0, 0), b2, voffB); PG8_STAGE(PG8_SB(0, 1), b2 + hstep, voffB); PG8_STAGE(PG8_SA(0, 0), a2, voffA);
;             PG8_WAIT_V(8); PG8_WAIT_L(0); PG8_BAR; PG8_MMA(1, 0, At, B0); PG8_MMA(1, 1, At, B1); PG8_BAR; PG8_SCHED;
;             PG8_LDB(B0, 1, 0); PG8_LDB(B1, 1, 1); PG8_SCHED; PG8_LDA(At, 1, 0); PG8_STAGE(PG8_SA(0, 1), a2 + hstep, voffA);
;             PG8_WAIT_V(8); PG8_WAIT_L(0); PG8_BAR; PG8_MMA(0, 0, At, B0); PG8_MMA(0, 1, At, B1); PG8_BAR; PG8_SCHED;
;             PG8_LDA(At, 1, 1); PG8_STAGE(PG8_SB(1, 0), b3, voffB); PG8_STAGE(PG8_SB(1, 1), b3 + hstep, voffB); PG8_STAGE(PG8_SA(1, 0), a3, voffA);
;             PG8_WAIT_V(8); PG8_WAIT_L(0); PG8_BAR; PG8_MMA(1, 0, At, B0); PG8_MMA(1, 1, At, B1); PG8_BAR; PG8_SCHED;
	s_waitcnt lgkmcnt(0)
	v_mfma_f32_16x16x32_bf16 v[124:127], v[152:155], v[184:187], v[124:127]
	v_mfma_f32_16x16x32_bf16 v[120:123], v[160:163], v[184:187], v[120:123]
	v_mfma_f32_16x16x32_bf16 v[116:119], v[152:155], v[192:195], v[116:119]
	v_mfma_f32_16x16x32_bf16 v[108:111], v[160:163], v[192:195], v[108:111]
	v_mfma_f32_16x16x32_bf16 v[100:103], v[152:155], v[200:203], v[100:103]
	v_mfma_f32_16x16x32_bf16 v[92:95], v[160:163], v[200:203], v[92:95]
	v_mfma_f32_16x16x32_bf16 v[84:87], v[152:155], v[212:215], v[84:87]
	v_mfma_f32_16x16x32_bf16 v[76:79], v[160:163], v[212:215], v[76:79]
	v_mfma_f32_16x16x32_bf16 v[124:127], v[156:159], v[188:191], v[124:127]
	v_mfma_f32_16x16x32_bf16 v[120:123], v[164:167], v[188:191], v[120:123]
	v_mfma_f32_16x16x32_bf16 v[116:119], v[156:159], v[196:199], v[116:119]
	v_mfma_f32_16x16x32_bf16 v[108:111], v[164:167], v[196:199], v[108:111]
	v_mfma_f32_16x16x32_bf16 v[100:103], v[156:159], v[204:207], v[100:103]
	v_mfma_f32_16x16x32_bf16 v[92:95], v[164:167], v[204:207], v[92:95]
	v_mfma_f32_16x16x32_bf16 v[84:87], v[156:159], v[216:219], v[84:87]
	v_mfma_f32_16x16x32_bf16 v[76:79], v[164:167], v[216:219], v[76:79]
	v_mfma_f32_16x16x32_bf16 v[112:115], v[168:171], v[184:187], v[112:115]
	v_mfma_f32_16x16x32_bf16 v[104:107], v[176:179], v[184:187], v[104:107]
	v_mfma_f32_16x16x32_bf16 v[96:99], v[168:171], v[192:195], v[96:99]
	v_mfma_f32_16x16x32_bf16 v[88:91], v[176:179], v[192:195], v[88:91]
	v_mfma_f32_16x16x32_bf16 v[80:83], v[168:171], v[200:203], v[80:83]
	v_mfma_f32_16x16x32_bf16 v[72:75], v[176:179], v[200:203], v[72:75]
	v_mfma_f32_16x16x32_bf16 v[68:71], v[168:171], v[212:215], v[68:71]
	v_mfma_f32_16x16x32_bf16 v[64:67], v[176:179], v[212:215], v[64:67]
	v_mfma_f32_16x16x32_bf16 v[112:115], v[172:175], v[188:191], v[112:115]
	v_mfma_f32_16x16x32_bf16 v[104:107], v[180:183], v[188:191], v[104:107]
	v_mfma_f32_16x16x32_bf16 v[96:99], v[172:175], v[196:199], v[96:99]
	v_mfma_f32_16x16x32_bf16 v[88:91], v[180:183], v[196:199], v[88:91]
	v_mfma_f32_16x16x32_bf16 v[80:83], v[172:175], v[204:207], v[80:83]
	v_mfma_f32_16x16x32_bf16 v[72:75], v[180:183], v[204:207], v[72:75]
	v_mfma_f32_16x16x32_bf16 v[68:71], v[172:175], v[216:219], v[68:71]
	v_mfma_f32_16x16x32_bf16 v[64:67], v[180:183], v[216:219], v[64:67]
	s_barrier
	s_add_i32 s24, s48, s26
	v_lshl_add_u64 v[144:145], v[144:145], 0, s[6:7]
	s_mov_b32 m0, s24
	ds_read_b128 v[184:187], v151 offset:49152
	ds_read_b128 v[188:191], v151 offset:50176
	ds_read_b128 v[192:195], v151 offset:51200
	ds_read_b128 v[196:199], v151 offset:52224
	ds_read_b128 v[200:203], v151 offset:53248
	ds_read_b128 v[204:207], v151 offset:54272
	ds_read_b128 v[212:215], v151 offset:55296
	ds_read_b128 v[216:219], v151 offset:56320
	global_load_lds_dwordx4 v[144:145], off
	s_add_i32 m0, s24, 0x2000
	s_add_u32 s22, s22, 0x40080
	v_lshl_add_u64 v[144:145], v[220:221], 0, s[6:7]
	s_addc_u32 s23, s23, 0
	s_add_i32 s24, s49, s26
	global_load_lds_dwordx4 v[144:145], off
	v_lshl_add_u64 v[144:145], s[22:23], 0, v[132:133]
	s_mov_b32 m0, s24
	s_nop 0
	global_load_lds_dwordx4 v[144:145], off
	v_lshl_add_u64 v[144:145], s[22:23], 0, v[128:129]
	s_add_i32 m0, s24, 0x2000
	s_nop 0
	global_load_lds_dwordx4 v[144:145], off
	v_lshl_add_u64 v[144:145], v[222:223], 0, s[6:7]
	s_mov_b32 m0, s37
	s_nop 0
	global_load_lds_dwordx4 v[144:145], off
	v_lshl_add_u64 v[144:145], v[224:225], 0, s[6:7]
	s_mov_b32 m0, s38
	s_nop 0
	global_load_lds_dwordx4 v[144:145], off
	s_waitcnt vmcnt(8)
	s_waitcnt lgkmcnt(0)
	s_barrier
	s_waitcnt lgkmcnt(0)
	v_mfma_f32_16x16x32_bf16 v[60:63], v[152:155], v[184:187], v[60:63]
	v_mfma_f32_16x16x32_bf16 v[56:59], v[160:163], v[184:187], v[56:59]
	v_mfma_f32_16x16x32_bf16 v[52:55], v[152:155], v[192:195], v[52:55]
	v_mfma_f32_16x16x32_bf16 v[44:47], v[160:163], v[192:195], v[44:47]
	v_mfma_f32_16x16x32_bf16 v[36:39], v[152:155], v[200:203], v[36:39]
	v_mfma_f32_16x16x32_bf16 v[28:31], v[160:163], v[200:203], v[28:31]
	v_mfma_f32_16x16x32_bf16 v[20:23], v[152:155], v[212:215], v[20:23]
	v_mfma_f32_16x16x32_bf16 v[12:15], v[160:163], v[212:215], v[12:15]
	v_mfma_f32_16x16x32_bf16 v[60:63], v[156:159], v[188:191], v[60:63]
	v_mfma_f32_16x16x32_bf16 v[56:59], v[164:167], v[188:191], v[56:59]
	v_mfma_f32_16x16x32_bf16 v[52:55], v[156:159], v[196:199], v[52:55]
	v_mfma_f32_16x16x32_bf16 v[44:47], v[164:167], v[196:199], v[44:47]
	v_mfma_f32_16x16x32_bf16 v[36:39], v[156:159], v[204:207], v[36:39]
	v_mfma_f32_16x16x32_bf16 v[28:31], v[164:167], v[204:207], v[28:31]
	v_mfma_f32_16x16x32_bf16 v[20:23], v[156:159], v[216:219], v[20:23]
	v_mfma_f32_16x16x32_bf16 v[12:15], v[164:167], v[216:219], v[12:15]
	v_mfma_f32_16x16x32_bf16 v[48:51], v[168:171], v[184:187], v[48:51]
	v_mfma_f32_16x16x32_bf16 v[40:43], v[176:179], v[184:187], v[40:43]
	v_mfma_f32_16x16x32_bf16 v[32:35], v[168:171], v[192:195], v[32:35]
	v_mfma_f32_16x16x32_bf16 v[24:27], v[176:179], v[192:195], v[24:27]
	v_mfma_f32_16x16x32_bf16 v[16:19], v[168:171], v[200:203], v[16:19]
	v_mfma_f32_16x16x32_bf16 v[8:11], v[176:179], v[200:203], v[8:11]
	v_mfma_f32_16x16x32_bf16 v[4:7], v[168:171], v[212:215], v[4:7]
	v_mfma_f32_16x16x32_bf16 v[0:3], v[176:179], v[212:215], v[0:3]
	v_mfma_f32_16x16x32_bf16 v[48:51], v[172:175], v[188:191], v[48:51]
	v_mfma_f32_16x16x32_bf16 v[40:43], v[180:183], v[188:191], v[40:43]
	v_mfma_f32_16x16x32_bf16 v[32:35], v[172:175], v[196:199], v[32:35]
	v_mfma_f32_16x16x32_bf16 v[24:27], v[180:183], v[196:199], v[24:27]
	v_mfma_f32_16x16x32_bf16 v[16:19], v[172:175], v[204:207], v[16:19]
	v_mfma_f32_16x16x32_bf16 v[8:11], v[180:183], v[204:207], v[8:11]
	v_mfma_f32_16x16x32_bf16 v[4:7], v[172:175], v[216:219], v[4:7]
	v_mfma_f32_16x16x32_bf16 v[0:3], v[180:183], v[216:219], v[0:3]
	s_barrier
	s_add_i32 s47, s47, 2
	s_add_u32 s20, s20, 0x100
	s_addc_u32 s21, s21, 0
	s_add_u32 s45, s45, 0x100
	s_addc_u32 s46, s46, 0
	s_cmp_gt_u32 s47, 13
	s_cbranch_scc0 .LBB0_882

; #define PG8_STAGE(bufoff, gbase, voff) do { _Pragma("unroll") for (int _i = 0; _i < 2; ++_i) \
;         __builtin_amdgcn_global_load_lds((const unsigned*)((const char*)(gbase) + (voff)[_i]), (PG8_LAS unsigned*)(lds + (bufoff) + ldsw + _i * 8192), 16, 0, 0); } while (0)
; #define PG8_LDA(dst, b, h) do { _Pragma("unroll") for (int m = 0; m < 4; ++m) _Pragma("unroll") for (int k = 0; k < 2; ++k) dst[m][k] = *(const PG8_LAS bf16x8*)(lds + PG8_SA(b, h) + aoff + m * 2048 + k * 1024); } while (0)
; #define PG8_LDB(dst, b, h) do { _Pragma("unroll") for (int n = 0; n < 2; ++n) _Pragma("unroll") for (int k = 0; k < 2; ++k) dst[n][k] = *(const PG8_LAS bf16x8*)(lds + PG8_SB(b, h) + boff + n * 2048 + k * 1024); } while (0)
; #define PG8_MMA(ai, bj, At, Bt) do { __builtin_amdgcn_s_setprio(1); _Pragma("unroll") for (int m = 0; m < 4; ++m) _Pragma("unroll") for (int n = 0; n < 2; ++n) _Pragma("unroll") for (int k = 0; k < 2; ++k) \
;         acc[ai][bj][m][n] = __builtin_amdgcn_mfma_f32_16x16x32_bf16(Bt[n][k], At[m][k], acc[ai][bj][m][n], 0, 0, 0); __builtin_amdgcn_s_setprio(0); } while (0)
; #define PG8_WAIT_V(n) asm volatile("s_waitcnt vmcnt(" #n ")" ::: "memory")
; #define PG8_WAIT_L(n) asm volatile("s_waitcnt lgkmcnt(" #n ")" ::: "memory")
; #define PG8_BAR __builtin_amdgcn_s_barrier()
; #define PG8_SCHED __builtin_amdgcn_sched_barrier(0)
; template <class Epi, class Sched, bool ALIGN_EPI = false, bool SP2 = false>
; __device__ __forceinline__ void gemm_phase(PG8_LAS unsigned char* lds, const Gemm g, const Sched& S, const Epi& E, const int wid) {
;     ...
;             PG8_LDB(B0, 0, 0); PG8_LDB(B1, 0, 1); PG8_SCHED; PG8_LDA(At, 0, 0); PG8_STAGE(PG8_SA(1, 1), a1 + hstep, voffA);
;             PG8_WAIT_V(8); PG8_WAIT_L(0); PG8_BAR; PG8_MMA(0, 0, At, B0); PG8_MMA(0, 1, At, B1); PG8_BAR; PG8_SCHED;
;             PG8_LDA(At, 0, 1); PG8_STAGE(PG8_SB(0, 0), b2, voffB); PG8_STAGE(PG8_SB(0, 1), b2 + hstep, voffB); PG8_STAGE(PG8_SA(0, 0), a2, voffA);
;             PG8_WAIT_V(8); PG8_WAIT_L(0); PG8_BAR; PG8_MMA(1, 0, At, B0); PG8_MMA(1, 1, At, B1); PG8_BAR; PG8_SCHED;
.LBB0_1786:
	v_add_u32_e32 v164, s41, v150
	v_add_u32_e32 v180, s42, v150
	s_add_u32 s22, s8, s20
	ds_read_b128 v[152:155], v164
	ds_read_b128 v[156:159], v164 offset:1024
	ds_read_b128 v[160:163], v164 offset:2048
	ds_read_b128 v[164:167], v164 offset:3072
	ds_read_b128 v[168:171], v180
	ds_read_b128 v[172:175], v180 offset:1024
	ds_read_b128 v[176:179], v180 offset:2048
	ds_read_b128 v[180:183], v180 offset:3072
	s_addc_u32 s23, s9, s21
	s_add_u32 s22, s22, 0x100
	s_addc_u32 s23, s23, 0
	s_add_u32 s49, s44, s20
	s_addc_u32 s50, s45, s21
	s_cmpk_eq_i32 s20, 0x700
	s_cselect_b32 s25, s15, s23
	s_cselect_b32 s24, s46, s22
	s_cselect_b32 s23, s13, s50
	s_cselect_b32 s22, s47, s49
	v_lshl_add_u64 v[206:207], v[144:145], 0, s[20:21]
	s_add_i32 m0, s33, 0xc000
	ds_read_b128 v[186:189], v151
	ds_read_b128 v[190:193], v151 offset:1024
	ds_read_b128 v[194:197], v151 offset:2048
	ds_read_b128 v[198:201], v151 offset:3072
	ds_read_b128 v[202:205], v151 offset:4096
	ds_read_b128 v[210:213], v151 offset:5120
	ds_read_b128 v[214:217], v151 offset:6144
	ds_read_b128 v[218:221], v151 offset:7168
	global_load_lds_dwordx4 v[206:207], off
	v_lshl_add_u64 v[206:207], v[146:147], 0, s[20:21]
	s_add_i32 m0, s33, 0xe000
	s_nop 0
	global_load_lds_dwordx4 v[206:207], off
	s_waitcnt vmcnt(8)
	s_waitcnt lgkmcnt(0)
	s_barrier
	s_waitcnt lgkmcnt(0)
	v_mfma_f32_16x16x32_bf16 v[124:127], v[152:155], v[186:189], v[124:127]
	v_mfma_f32_16x16x32_bf16 v[120:123], v[160:163], v[186:189], v[120:123]
	v_mfma_f32_16x16x32_bf16 v[112:115], v[152:155], v[194:197], v[112:115]
	v_mfma_f32_16x16x32_bf16 v[104:107], v[160:163], v[194:197], v[104:107]
	v_mfma_f32_16x16x32_bf16 v[96:99], v[152:155], v[202:205], v[96:99]
	v_mfma_f32_16x16x32_bf16 v[88:91], v[160:163], v[202:205], v[88:91]
	v_mfma_f32_16x16x32_bf16 v[80:83], v[152:155], v[214:217], v[80:83]
	v_mfma_f32_16x16x32_bf16 v[72:75], v[160:163], v[214:217], v[72:75]
	v_mfma_f32_16x16x32_bf16 v[124:127], v[156:159], v[190:193], v[124:127]
	v_mfma_f32_16x16x32_bf16 v[120:123], v[164:167], v[190:193], v[120:123]
	v_mfma_f32_16x16x32_bf16 v[112:115], v[156:159], v[198:201], v[112:115]
	v_mfma_f32_16x16x32_bf16 v[104:107], v[164:167], v[198:201], v[104:107]
	v_mfma_f32_16x16x32_bf16 v[96:99], v[156:159], v[210:213], v[96:99]
	v_mfma_f32_16x16x32_bf16 v[88:91], v[164:167], v[210:213], v[88:91]
	v_mfma_f32_16x16x32_bf16 v[80:83], v[156:159], v[218:221], v[80:83]
	v_mfma_f32_16x16x32_bf16 v[72:75], v[164:167], v[218:221], v[72:75]
	v_mfma_f32_16x16x32_bf16 v[116:119], v[168:171], v[186:189], v[116:119]
	v_mfma_f32_16x16x32_bf16 v[108:111], v[176:179], v[186:189], v[108:111]
	v_mfma_f32_16x16x32_bf16 v[100:103], v[168:171], v[194:197], v[100:103]
	v_mfma_f32_16x16x32_bf16 v[92:95], v[176:179], v[194:197], v[92:95]
	v_mfma_f32_16x16x32_bf16 v[84:87], v[168:171], v[202:205], v[84:87]
	v_mfma_f32_16x16x32_bf16 v[76:79], v[176:179], v[202:205], v[76:79]
	v_mfma_f32_16x16x32_bf16 v[68:71], v[168:171], v[214:217], v[68:71]
	v_mfma_f32_16x16x32_bf16 v[64:67], v[176:179], v[214:217], v[64:67]
	v_mfma_f32_16x16x32_bf16 v[116:119], v[172:175], v[190:193], v[116:119]
	v_mfma_f32_16x16x32_bf16 v[108:111], v[180:183], v[190:193], v[108:111]
	v_mfma_f32_16x16x32_bf16 v[100:103], v[172:175], v[198:201], v[100:103]
	v_mfma_f32_16x16x32_bf16 v[92:95], v[180:183], v[198:201], v[92:95]
	v_mfma_f32_16x16x32_bf16 v[84:87], v[172:175], v[210:213], v[84:87]
	v_mfma_f32_16x16x32_bf16 v[76:79], v[180:183], v[210:213], v[76:79]
	v_mfma_f32_16x16x32_bf16 v[68:71], v[172:175], v[218:221], v[68:71]
	v_mfma_f32_16x16x32_bf16 v[64:67], v[180:183], v[218:221], v[64:67]
	s_barrier
	s_add_i32 s49, s41, s31
	v_lshl_add_u64 v[206:207], s[22:23], 0, v[130:131]
	s_mov_b32 m0, s49
	ds_read_b128 v[186:189], v151 offset:16384
	ds_read_b128 v[190:193], v151 offset:17408
	ds_read_b128 v[194:197], v151 offset:18432
	ds_read_b128 v[198:201], v151 offset:19456
	ds_read_b128 v[202:205], v151 offset:20480
	ds_read_b128 v[210:213], v151 offset:21504
	ds_read_b128 v[214:217], v151 offset:22528
	ds_read_b128 v[218:221], v151 offset:23552
	global_load_lds_dwordx4 v[206:207], off
	s_add_i32 m0, s49, 0x2000
	s_add_u32 s50, s22, 0x40000
	v_lshl_add_u64 v[222:223], s[22:23], 0, v[134:135]
	s_addc_u32 s51, s23, 0
	s_add_i32 s49, s42, s31
	global_load_lds_dwordx4 v[222:223], off
	v_lshl_add_u64 v[224:225], s[50:51], 0, v[130:131]
	s_mov_b32 m0, s49
	v_lshl_add_u64 v[226:227], s[24:25], 0, v[132:133]
	global_load_lds_dwordx4 v[224:225], off
	v_lshl_add_u64 v[224:225], s[50:51], 0, v[134:135]
	s_add_i32 m0, s49, 0x2000
	s_nop 0
	global_load_lds_dwordx4 v[224:225], off
	v_lshl_add_u64 v[224:225], s[24:25], 0, v[128:129]
	s_mov_b32 m0, s33
	s_nop 0
	global_load_lds_dwordx4 v[224:225], off
	s_mov_b32 m0, s34
	s_nop 0
	global_load_lds_dwordx4 v[226:227], off
	s_waitcnt vmcnt(8)
	s_waitcnt lgkmcnt(0)
	s_barrier
; #define PG8_STAGE(bufoff, gbase, voff) do { _Pragma("unroll") for (int _i = 0; _i < 2; ++_i) \
;         __builtin_amdgcn_global_load_lds((const unsigned*)((const char*)(gbase) + (voff)[_i]), (PG8_LAS unsigned*)(lds + (bufoff) + ldsw + _i * 8192), 16, 0, 0); } while (0)
; #define PG8_LDA(dst, b, h) do { _Pragma("unroll") for (int m = 0; m < 4; ++m) _Pragma("unroll") for (int k = 0; k < 2; ++k) dst[m][k] = *(const PG8_LAS bf16x8*)(lds + PG8_SA(b, h) + aoff + m * 2048 + k * 1024); } while (0)
; #define PG8_LDB(dst, b, h) do { _Pragma("unroll") for (int n = 0; n < 2; ++n) _Pragma("unroll") for (int k = 0; k < 2; ++k) dst[n][k] = *(const PG8_LAS bf16x8*)(lds + PG8_SB(b, h) + boff + n * 2048 + k * 1024); } while (0)
; #define PG8_MMA(ai, bj, At, Bt) do { __builtin_amdgcn_s_setprio(1); _Pragma("unroll") for (int m = 0; m < 4; ++m) _Pragma("unroll") for (int n = 0; n < 2; ++n) _Pragma("unroll") for (int k = 0; k < 2; ++k) \
;         acc[ai][bj][m][n] = __builtin_amdgcn_mfma_f32_16x16x32_bf16(Bt[n][k], At[m][k], acc[ai][bj][m][n], 0, 0, 0); __builtin_amdgcn_s_setprio(0); } while (0)
; #define PG8_WAIT_V(n) asm volatile("s_waitcnt vmcnt(" #n ")" ::: "memory")
; #define PG8_WAIT_L(n) asm volatile("s_waitcnt lgkmcnt(" #n ")" ::: "memory")
; #define PG8_BAR __builtin_amdgcn_s_barrier()
; #define PG8_SCHED __builtin_amdgcn_sched_barrier(0)
; template <class Epi, class Sched, bool ALIGN_EPI = false, bool SP2 = false>
; __device__ __forceinline__ void gemm_phase(PG8_LAS unsigned char* lds, const Gemm g, const Sched& S, const Epi& E, const int wid) {
;     ...
;             PG8_LDA(At, 0, 1); PG8_STAGE(PG8_SB(0, 0), b2, voffB); PG8_STAGE(PG8_SB(0, 1), b2 + hstep, voffB); PG8_STAGE(PG8_SA(0, 0), a2, voffA);
;             PG8_WAIT_V(8); PG8_WAIT_L(0); PG8_BAR; PG8_MMA(1, 0, At, B0); PG8_MMA(1, 1, At, B1); PG8_BAR; PG8_SCHED;
;             PG8_LDB(B0, 1, 0); PG8_LDB(B1, 1, 1); PG8_SCHED; PG8_LDA(At, 1, 0); PG8_STAGE(PG8_SA(0, 1), a2 + hstep, voffA);
;             PG8_WAIT_V(8); PG8_WAIT_L(0); PG8_BAR; PG8_MMA(0, 0, At, B0); PG8_MMA(0, 1, At, B1); PG8_BAR; PG8_SCHED;
;             PG8_LDA(At, 1, 1); PG8_STAGE(PG8_SB(1, 0), b3, voffB); PG8_STAGE(PG8_SB(1, 1), b3 + hstep, voffB); PG8_STAGE(PG8_SA(1, 0), a3, voffA);
	s_waitcnt lgkmcnt(0)
	v_mfma_f32_16x16x32_bf16 v[60:63], v[152:155], v[186:189], v[60:63]
	v_mfma_f32_16x16x32_bf16 v[56:59], v[160:163], v[186:189], v[56:59]
	v_mfma_f32_16x16x32_bf16 v[44:47], v[152:155], v[194:197], v[44:47]
	v_mfma_f32_16x16x32_bf16 v[40:43], v[160:163], v[194:197], v[40:43]
	v_mfma_f32_16x16x32_bf16 v[28:31], v[152:155], v[202:205], v[28:31]
	v_mfma_f32_16x16x32_bf16 v[24:27], v[160:163], v[202:205], v[24:27]
	v_mfma_f32_16x16x32_bf16 v[12:15], v[152:155], v[214:217], v[12:15]
	v_mfma_f32_16x16x32_bf16 v[8:11], v[160:163], v[214:217], v[8:11]
	v_mfma_f32_16x16x32_bf16 v[60:63], v[156:159], v[190:193], v[60:63]
	v_mfma_f32_16x16x32_bf16 v[56:59], v[164:167], v[190:193], v[56:59]
	v_mfma_f32_16x16x32_bf16 v[44:47], v[156:159], v[198:201], v[44:47]
	v_mfma_f32_16x16x32_bf16 v[40:43], v[164:167], v[198:201], v[40:43]
	v_mfma_f32_16x16x32_bf16 v[28:31], v[156:159], v[210:213], v[28:31]
	v_mfma_f32_16x16x32_bf16 v[24:27], v[164:167], v[210:213], v[24:27]
	v_mfma_f32_16x16x32_bf16 v[12:15], v[156:159], v[218:221], v[12:15]
	v_mfma_f32_16x16x32_bf16 v[8:11], v[164:167], v[218:221], v[8:11]
	v_mfma_f32_16x16x32_bf16 v[52:55], v[168:171], v[186:189], v[52:55]
	v_mfma_f32_16x16x32_bf16 v[48:51], v[176:179], v[186:189], v[48:51]
	v_mfma_f32_16x16x32_bf16 v[36:39], v[168:171], v[194:197], v[36:39]
	v_mfma_f32_16x16x32_bf16 v[32:35], v[176:179], v[194:197], v[32:35]
	v_mfma_f32_16x16x32_bf16 v[20:23], v[168:171], v[202:205], v[20:23]
	v_mfma_f32_16x16x32_bf16 v[16:19], v[176:179], v[202:205], v[16:19]
	v_mfma_f32_16x16x32_bf16 v[4:7], v[168:171], v[214:217], v[4:7]
	v_mfma_f32_16x16x32_bf16 v[0:3], v[176:179], v[214:217], v[0:3]
	v_mfma_f32_16x16x32_bf16 v[52:55], v[172:175], v[190:193], v[52:55]
	v_mfma_f32_16x16x32_bf16 v[48:51], v[180:183], v[190:193], v[48:51]
	v_mfma_f32_16x16x32_bf16 v[36:39], v[172:175], v[198:201], v[36:39]
	v_mfma_f32_16x16x32_bf16 v[32:35], v[180:183], v[198:201], v[32:35]
	v_mfma_f32_16x16x32_bf16 v[20:23], v[172:175], v[210:213], v[20:23]
	v_mfma_f32_16x16x32_bf16 v[16:19], v[180:183], v[210:213], v[16:19]
	v_mfma_f32_16x16x32_bf16 v[4:7], v[172:175], v[218:221], v[4:7]
	v_mfma_f32_16x16x32_bf16 v[0:3], v[180:183], v[218:221], v[0:3]
	s_barrier
	s_add_i32 s49, 0, 0x18000
	s_add_i32 s50, 0, 0x1c000
	v_add_u32_e32 v164, s49, v150
	v_add_u32_e32 v180, s50, v150
	ds_read_b128 v[152:155], v164
	ds_read_b128 v[156:159], v164 offset:1024
	ds_read_b128 v[160:163], v164 offset:2048
	ds_read_b128 v[164:167], v164 offset:3072
	ds_read_b128 v[168:171], v180
	ds_read_b128 v[172:175], v180 offset:1024
	ds_read_b128 v[176:179], v180 offset:2048
	ds_read_b128 v[180:183], v180 offset:3072
	s_add_u32 s24, s24, 0x40000
	s_addc_u32 s25, s25, 0
	s_mov_b32 m0, s35
	v_lshl_add_u64 v[228:229], s[24:25], 0, v[128:129]
	ds_read_b128 v[186:189], v151 offset:32768
	ds_read_b128 v[190:193], v151 offset:33792
	ds_read_b128 v[194:197], v151 offset:34816
	ds_read_b128 v[198:201], v151 offset:35840
	ds_read_b128 v[202:205], v151 offset:36864
	ds_read_b128 v[210:213], v151 offset:37888
	ds_read_b128 v[214:217], v151 offset:38912
	ds_read_b128 v[218:221], v151 offset:39936
	global_load_lds_dwordx4 v[228:229], off
	v_lshl_add_u64 v[228:229], s[24:25], 0, v[132:133]
	s_mov_b32 m0, s36
	s_nop 0
	global_load_lds_dwordx4 v[228:229], off
	s_waitcnt vmcnt(8)
	s_waitcnt lgkmcnt(0)
	s_barrier
	s_waitcnt lgkmcnt(0)
	v_mfma_f32_16x16x32_bf16 v[124:127], v[152:155], v[186:189], v[124:127]
	v_mfma_f32_16x16x32_bf16 v[120:123], v[160:163], v[186:189], v[120:123]
	v_mfma_f32_16x16x32_bf16 v[112:115], v[152:155], v[194:197], v[112:115]
	v_mfma_f32_16x16x32_bf16 v[104:107], v[160:163], v[194:197], v[104:107]
	v_mfma_f32_16x16x32_bf16 v[96:99], v[152:155], v[202:205], v[96:99]
	v_mfma_f32_16x16x32_bf16 v[88:91], v[160:163], v[202:205], v[88:91]
	v_mfma_f32_16x16x32_bf16 v[80:83], v[152:155], v[214:217], v[80:83]
	v_mfma_f32_16x16x32_bf16 v[72:75], v[160:163], v[214:217], v[72:75]
	v_mfma_f32_16x16x32_bf16 v[124:127], v[156:159], v[190:193], v[124:127]
	v_mfma_f32_16x16x32_bf16 v[120:123], v[164:167], v[190:193], v[120:123]
	v_mfma_f32_16x16x32_bf16 v[112:115], v[156:159], v[198:201], v[112:115]
	v_mfma_f32_16x16x32_bf16 v[104:107], v[164:167], v[198:201], v[104:107]
	v_mfma_f32_16x16x32_bf16 v[96:99], v[156:159], v[210:213], v[96:99]
	v_mfma_f32_16x16x32_bf16 v[88:91], v[164:167], v[210:213], v[88:91]
	v_mfma_f32_16x16x32_bf16 v[80:83], v[156:159], v[218:221], v[80:83]
	v_mfma_f32_16x16x32_bf16 v[72:75], v[164:167], v[218:221], v[72:75]
	v_mfma_f32_16x16x32_bf16 v[116:119], v[168:171], v[186:189], v[116:119]
	v_mfma_f32_16x16x32_bf16 v[108:111], v[176:179], v[186:189], v[108:111]
	v_mfma_f32_16x16x32_bf16 v[100:103], v[168:171], v[194:197], v[100:103]
	v_mfma_f32_16x16x32_bf16 v[92:95], v[176:179], v[194:197], v[92:95]
	v_mfma_f32_16x16x32_bf16 v[84:87], v[168:171], v[202:205], v[84:87]
	v_mfma_f32_16x16x32_bf16 v[76:79], v[176:179], v[202:205], v[76:79]
	v_mfma_f32_16x16x32_bf16 v[68:71], v[168:171], v[214:217], v[68:71]
	v_mfma_f32_16x16x32_bf16 v[64:67], v[176:179], v[214:217], v[64:67]
	v_mfma_f32_16x16x32_bf16 v[116:119], v[172:175], v[190:193], v[116:119]
	v_mfma_f32_16x16x32_bf16 v[108:111], v[180:183], v[190:193], v[108:111]
	v_mfma_f32_16x16x32_bf16 v[100:103], v[172:175], v[198:201], v[100:103]
	v_mfma_f32_16x16x32_bf16 v[92:95], v[180:183], v[198:201], v[92:95]
	v_mfma_f32_16x16x32_bf16 v[84:87], v[172:175], v[210:213], v[84:87]
	v_mfma_f32_16x16x32_bf16 v[76:79], v[180:183], v[210:213], v[76:79]
	v_mfma_f32_16x16x32_bf16 v[68:71], v[172:175], v[218:221], v[68:71]
	v_mfma_f32_16x16x32_bf16 v[64:67], v[180:183], v[218:221], v[64:67]
	s_barrier
; #define PG8_STAGE(bufoff, gbase, voff) do { _Pragma("unroll") for (int _i = 0; _i < 2; ++_i) \
;         __builtin_amdgcn_global_load_lds((const unsigned*)((const char*)(gbase) + (voff)[_i]), (PG8_LAS unsigned*)(lds + (bufoff) + ldsw + _i * 8192), 16, 0, 0); } while (0)
; #define PG8_LDA(dst, b, h) do { _Pragma("unroll") for (int m = 0; m < 4; ++m) _Pragma("unroll") for (int k = 0; k < 2; ++k) dst[m][k] = *(const PG8_LAS bf16x8*)(lds + PG8_SA(b, h) + aoff + m * 2048 + k * 1024); } while (0)
; #define PG8_MMA(ai, bj, At, Bt) do { __builtin_amdgcn_s_setprio(1); _Pragma("unroll") for (int m = 0; m < 4; ++m) _Pragma("unroll") for (int n = 0; n < 2; ++n) _Pragma("unroll") for (int k = 0; k < 2; ++k) \
;         acc[ai][bj][m][n] = __builtin_amdgcn_mfma_f32_16x16x32_bf16(Bt[n][k], At[m][k], acc[ai][bj][m][n], 0, 0, 0); __builtin_amdgcn_s_setprio(0); } while (0)
; #define PG8_WAIT_V(n) asm volatile("s_waitcnt vmcnt(" #n ")" ::: "memory")
; #define PG8_WAIT_L(n) asm volatile("s_waitcnt lgkmcnt(" #n ")" ::: "memory")
; #define PG8_BAR __builtin_amdgcn_s_barrier()
; #define PG8_SCHED __builtin_amdgcn_sched_barrier(0)
; template <class Epi, class Sched, bool ALIGN_EPI = false, bool SP2 = false>
; __device__ __forceinline__ void gemm_phase(PG8_LAS unsigned char* lds, const Gemm g, const Sched& S, const Epi& E, const int wid) {
;     ...
;             PG8_LDA(At, 1, 1); PG8_STAGE(PG8_SB(1, 0), b3, voffB); PG8_STAGE(PG8_SB(1, 1), b3 + hstep, voffB); PG8_STAGE(PG8_SA(1, 0), a3, voffA);
;             PG8_WAIT_V(8); PG8_WAIT_L(0); PG8_BAR; PG8_MMA(1, 0, At, B0); PG8_MMA(1, 1, At, B1); PG8_BAR; PG8_SCHED;
;     ...
;         if (!has_next) break;
; #pragma unroll
;         for (int a = 0; a < 2; ++a)
; #pragma unroll
;             for (int b = 0; b < 2; ++b)
; #pragma unroll
;                 for (int m = 0; m < 4; ++m)
; #pragma unroll
;                     for (int n = 0; n < 2; ++n) acc[a][b][m][n] = (f32x4){0.f, 0.f, 0.f, 0.f};
;         cur = nxt; cA = nA; cB = nB; ++ui;
	s_add_i32 s24, s49, s31
	v_lshl_add_u64 v[206:207], v[206:207], 0, s[10:11]
	s_mov_b32 m0, s24
	ds_read_b128 v[186:189], v151 offset:49152
	ds_read_b128 v[190:193], v151 offset:50176
	ds_read_b128 v[194:197], v151 offset:51200
	ds_read_b128 v[198:201], v151 offset:52224
	ds_read_b128 v[202:205], v151 offset:53248
	ds_read_b128 v[210:213], v151 offset:54272
	ds_read_b128 v[214:217], v151 offset:55296
	ds_read_b128 v[218:221], v151 offset:56320
	global_load_lds_dwordx4 v[206:207], off
	s_add_i32 m0, s24, 0x2000
	s_add_u32 s22, s22, 0x40080
	v_lshl_add_u64 v[206:207], v[222:223], 0, s[10:11]
	s_addc_u32 s23, s23, 0
	s_add_i32 s24, s50, s31
	global_load_lds_dwordx4 v[206:207], off
	v_lshl_add_u64 v[206:207], s[22:23], 0, v[130:131]
	s_mov_b32 m0, s24
	s_nop 0
	global_load_lds_dwordx4 v[206:207], off
	v_lshl_add_u64 v[206:207], s[22:23], 0, v[134:135]
	s_add_i32 m0, s24, 0x2000
	s_nop 0
	global_load_lds_dwordx4 v[206:207], off
	v_lshl_add_u64 v[206:207], v[224:225], 0, s[10:11]
	s_mov_b32 m0, s38
	s_nop 0
	global_load_lds_dwordx4 v[206:207], off
	v_lshl_add_u64 v[206:207], v[226:227], 0, s[10:11]
	s_mov_b32 m0, s39
	s_nop 0
	global_load_lds_dwordx4 v[206:207], off
	s_waitcnt vmcnt(8)
	s_waitcnt lgkmcnt(0)
	s_barrier
	s_waitcnt lgkmcnt(0)
	v_mfma_f32_16x16x32_bf16 v[60:63], v[152:155], v[186:189], v[60:63]
	v_mfma_f32_16x16x32_bf16 v[56:59], v[160:163], v[186:189], v[56:59]
	v_mfma_f32_16x16x32_bf16 v[44:47], v[152:155], v[194:197], v[44:47]
	v_mfma_f32_16x16x32_bf16 v[40:43], v[160:163], v[194:197], v[40:43]
	v_mfma_f32_16x16x32_bf16 v[28:31], v[152:155], v[202:205], v[28:31]
	v_mfma_f32_16x16x32_bf16 v[24:27], v[160:163], v[202:205], v[24:27]
	v_mfma_f32_16x16x32_bf16 v[12:15], v[152:155], v[214:217], v[12:15]
	v_mfma_f32_16x16x32_bf16 v[8:11], v[160:163], v[214:217], v[8:11]
	v_mfma_f32_16x16x32_bf16 v[60:63], v[156:159], v[190:193], v[60:63]
	v_mfma_f32_16x16x32_bf16 v[56:59], v[164:167], v[190:193], v[56:59]
	v_mfma_f32_16x16x32_bf16 v[44:47], v[156:159], v[198:201], v[44:47]
	v_mfma_f32_16x16x32_bf16 v[40:43], v[164:167], v[198:201], v[40:43]
	v_mfma_f32_16x16x32_bf16 v[28:31], v[156:159], v[210:213], v[28:31]
	v_mfma_f32_16x16x32_bf16 v[24:27], v[164:167], v[210:213], v[24:27]
	v_mfma_f32_16x16x32_bf16 v[12:15], v[156:159], v[218:221], v[12:15]
	v_mfma_f32_16x16x32_bf16 v[8:11], v[164:167], v[218:221], v[8:11]
	v_mfma_f32_16x16x32_bf16 v[52:55], v[168:171], v[186:189], v[52:55]
	v_mfma_f32_16x16x32_bf16 v[48:51], v[176:179], v[186:189], v[48:51]
	v_mfma_f32_16x16x32_bf16 v[36:39], v[168:171], v[194:197], v[36:39]
	v_mfma_f32_16x16x32_bf16 v[32:35], v[176:179], v[194:197], v[32:35]
	v_mfma_f32_16x16x32_bf16 v[20:23], v[168:171], v[202:205], v[20:23]
	v_mfma_f32_16x16x32_bf16 v[16:19], v[176:179], v[202:205], v[16:19]
	v_mfma_f32_16x16x32_bf16 v[4:7], v[168:171], v[214:217], v[4:7]
	v_mfma_f32_16x16x32_bf16 v[0:3], v[176:179], v[214:217], v[0:3]
	v_mfma_f32_16x16x32_bf16 v[52:55], v[172:175], v[190:193], v[52:55]
	v_mfma_f32_16x16x32_bf16 v[48:51], v[180:183], v[190:193], v[48:51]
	v_mfma_f32_16x16x32_bf16 v[36:39], v[172:175], v[198:201], v[36:39]
	v_mfma_f32_16x16x32_bf16 v[32:35], v[180:183], v[198:201], v[32:35]
	v_mfma_f32_16x16x32_bf16 v[20:23], v[172:175], v[210:213], v[20:23]
	v_mfma_f32_16x16x32_bf16 v[16:19], v[180:183], v[210:213], v[16:19]
	v_mfma_f32_16x16x32_bf16 v[4:7], v[172:175], v[218:221], v[4:7]
	v_mfma_f32_16x16x32_bf16 v[0:3], v[180:183], v[218:221], v[0:3]
	s_barrier
	s_add_i32 s48, s48, 2
	s_add_u32 s20, s20, 0x100
	s_addc_u32 s21, s21, 0
	s_cmp_gt_u32 s48, 13
	s_cbranch_scc0 .LBB0_1786
	s_add_u32 s20, s44, 0xffffff00
	s_addc_u32 s21, s45, -1
	s_andn2_b64 vcc, exec, s[6:7]
	s_cbranch_vccnz .LBB0_1777
	v_mov_b32_e32 v0, 0
	s_mov_b32 s2, s12
	s_mov_b32 s0, s14
	s_mov_b64 s[8:9], s[18:19]
	s_mov_b32 s40, s43
	v_mov_b32_e32 v1, v0
	v_mov_b32_e32 v2, v0
	v_mov_b32_e32 v3, v0
	v_mov_b32_e32 v4, v0
	v_mov_b32_e32 v5, v0
	v_mov_b32_e32 v6, v0
	v_mov_b32_e32 v7, v0
	v_mov_b32_e32 v16, v0
	v_mov_b32_e32 v17, v0
	v_mov_b32_e32 v18, v0
	v_mov_b32_e32 v19, v0
	v_mov_b32_e32 v20, v0
	v_mov_b32_e32 v21, v0
	v_mov_b32_e32 v22, v0
	v_mov_b32_e32 v23, v0
	v_mov_b32_e32 v32, v0
	v_mov_b32_e32 v33, v0
	v_mov_b32_e32 v34, v0
	v_mov_b32_e32 v35, v0
	v_mov_b32_e32 v36, v0
	v_mov_b32_e32 v37, v0
	v_mov_b32_e32 v38, v0
	v_mov_b32_e32 v39, v0
	v_mov_b32_e32 v48, v0
	v_mov_b32_e32 v49, v0
	v_mov_b32_e32 v50, v0
	v_mov_b32_e32 v51, v0
	v_mov_b32_e32 v52, v0
	v_mov_b32_e32 v53, v0
	v_mov_b32_e32 v54, v0
	v_mov_b32_e32 v55, v0
	v_mov_b32_e32 v8, v0
	v_mov_b32_e32 v9, v0
	v_mov_b32_e32 v10, v0
	v_mov_b32_e32 v11, v0
	v_mov_b32_e32 v12, v0
	v_mov_b32_e32 v13, v0
	v_mov_b32_e32 v14, v0
	v_mov_b32_e32 v15, v0
	v_mov_b32_e32 v24, v0
	v_mov_b32_e32 v25, v0
	v_mov_b32_e32 v26, v0
	v_mov_b32_e32 v27, v0
	v_mov_b32_e32 v28, v0
	v_mov_b32_e32 v29, v0
	v_mov_b32_e32 v30, v0
	v_mov_b32_e32 v31, v0
	v_mov_b32_e32 v40, v0
	v_mov_b32_e32 v41, v0
	v_mov_b32_e32 v42, v0
	v_mov_b32_e32 v43, v0
	v_mov_b32_e32 v44, v0
	v_mov_b32_e32 v45, v0
	v_mov_b32_e32 v46, v0
	v_mov_b32_e32 v47, v0
	v_mov_b32_e32 v56, v0
	v_mov_b32_e32 v57, v0
	v_mov_b32_e32 v58, v0
	v_mov_b32_e32 v59, v0
	v_mov_b32_e32 v60, v0
	v_mov_b32_e32 v61, v0
	v_mov_b32_e32 v62, v0
	v_mov_b32_e32 v63, v0
	v_mov_b32_e32 v64, v0
	v_mov_b32_e32 v65, v0
	v_mov_b32_e32 v66, v0
	v_mov_b32_e32 v67, v0
	v_mov_b32_e32 v68, v0
	v_mov_b32_e32 v69, v0
	v_mov_b32_e32 v70, v0
	v_mov_b32_e32 v71, v0
	v_mov_b32_e32 v76, v0
	v_mov_b32_e32 v77, v0
	v_mov_b32_e32 v78, v0
	v_mov_b32_e32 v79, v0
	v_mov_b32_e32 v84, v0
	v_mov_b32_e32 v85, v0
	v_mov_b32_e32 v86, v0
	v_mov_b32_e32 v87, v0
	v_mov_b32_e32 v92, v0
	v_mov_b32_e32 v93, v0
	v_mov_b32_e32 v94, v0
	v_mov_b32_e32 v95, v0
	v_mov_b32_e32 v100, v0
	v_mov_b32_e32 v101, v0
	v_mov_b32_e32 v102, v0
	v_mov_b32_e32 v103, v0
	v_mov_b32_e32 v108, v0
	v_mov_b32_e32 v109, v0
	v_mov_b32_e32 v110, v0
	v_mov_b32_e32 v111, v0
	v_mov_b32_e32 v116, v0
	v_mov_b32_e32 v117, v0
	v_mov_b32_e32 v118, v0
	v_mov_b32_e32 v119, v0
	v_mov_b32_e32 v72, v0
	v_mov_b32_e32 v73, v0
	v_mov_b32_e32 v74, v0
	v_mov_b32_e32 v75, v0
	v_mov_b32_e32 v80, v0
	v_mov_b32_e32 v81, v0
	v_mov_b32_e32 v82, v0
	v_mov_b32_e32 v83, v0
	v_mov_b32_e32 v88, v0
	v_mov_b32_e32 v89, v0
	v_mov_b32_e32 v90, v0
	v_mov_b32_e32 v91, v0
	v_mov_b32_e32 v96, v0
	v_mov_b32_e32 v97, v0
	v_mov_b32_e32 v98, v0
	v_mov_b32_e32 v99, v0
	v_mov_b32_e32 v104, v0
	v_mov_b32_e32 v105, v0
	v_mov_b32_e32 v106, v0
	v_mov_b32_e32 v107, v0
	v_mov_b32_e32 v112, v0
	v_mov_b32_e32 v113, v0
	v_mov_b32_e32 v114, v0
	v_mov_b32_e32 v115, v0
	v_mov_b32_e32 v120, v0
	v_mov_b32_e32 v121, v0
	v_mov_b32_e32 v122, v0
	v_mov_b32_e32 v123, v0
	v_mov_b32_e32 v124, v0
	v_mov_b32_e32 v125, v0
	v_mov_b32_e32 v126, v0
	v_mov_b32_e32 v127, v0
	s_andn2_b64 vcc, exec, s[4:5]
	s_cbranch_vccnz .LBB0_1778

; template <class Epi, class Sched, bool ALIGN_EPI = false, bool SP2 = false>
; __device__ __forceinline__ void gemm_phase(PG8_LAS unsigned char* lds, const Gemm g, const Sched& S, const Epi& E, const int wid) {
;     ...
;         const bool has_next = S.next(ui + 1, nxt);
;         const char* nA = has_next ? (const char*)g.A + (size_t)nxt.pm * tstep : cA; const char* nB = has_next ? (const char*)g.Bt + (size_t)nxt.pn * tstep : cB;
;         for (int t = 0; t < nt; t += 2) {
;             const bool last = (t == nt - 2);
;             const char* a1 = cA + (size_t)(t + 1) * kstep;
;             const char* a2 = last ? nA : cA + (size_t)(t + 2) * kstep; const char* b2 = last ? nB : cB + (size_t)(t + 2) * kstep;
;             const char* a3 = a2 + kstep; const char* b3 = b2 + kstep;
.LBB0_1911:
	s_ashr_i32 s15, s14, 31
	s_lshl_b64 s[16:17], s[14:15], 19
	s_add_u32 s16, s80, s16
	s_addc_u32 s17, s81, s17
	s_and_b64 s[18:19], s[4:5], exec
	s_cselect_b32 s15, s17, s23
	s_cselect_b32 s42, s16, s22
	s_ashr_i32 s13, s12, 31
	s_lshl_b64 s[18:19], s[12:13], 19
	s_add_u32 s18, s10, s18
	s_addc_u32 s19, s11, s19
	s_and_b64 s[26:27], s[4:5], exec
	s_cselect_b32 s13, s19, s25
	s_cselect_b32 s43, s18, s24
	s_add_u32 s22, s22, 0x40080
	s_addc_u32 s23, s23, 0
	s_add_u32 s44, s24, 0x100

; template <class Epi, class Sched, bool ALIGN_EPI = false, bool SP2 = false>
; __device__ __forceinline__ void gemm_phase(PG8_LAS unsigned char* lds, const Gemm g, const Sched& S, const Epi& E, const int wid) {
;     ...
;         for (int t = 0; t < nt; t += 2) {
;             const bool last = (t == nt - 2);
;             const char* a1 = cA + (size_t)(t + 1) * kstep;
;             const char* a2 = last ? nA : cA + (size_t)(t + 2) * kstep; const char* b2 = last ? nB : cB + (size_t)(t + 2) * kstep;
	s_addc_u32 s45, s25, 0
	s_mov_b32 s46, -2


; #define PG8_STAGE(bufoff, gbase, voff) do { _Pragma("unroll") for (int _i = 0; _i < 2; ++_i) \
;         __builtin_amdgcn_global_load_lds((const unsigned*)((const char*)(gbase) + (voff)[_i]), (PG8_LAS unsigned*)(lds + (bufoff) + ldsw + _i * 8192), 16, 0, 0); } while (0)
; #define PG8_LDA(dst, b, h) do { _Pragma("unroll") for (int m = 0; m < 4; ++m) _Pragma("unroll") for (int k = 0; k < 2; ++k) dst[m][k] = *(const PG8_LAS bf16x8*)(lds + PG8_SA(b, h) + aoff + m * 2048 + k * 1024); } while (0)
; #define PG8_LDB(dst, b, h) do { _Pragma("unroll") for (int n = 0; n < 2; ++n) _Pragma("unroll") for (int k = 0; k < 2; ++k) dst[n][k] = *(const PG8_LAS bf16x8*)(lds + PG8_SB(b, h) + boff + n * 2048 + k * 1024); } while (0)
; #define PG8_MMA(ai, bj, At, Bt) do { __builtin_amdgcn_s_setprio(1); _Pragma("unroll") for (int m = 0; m < 4; ++m) _Pragma("unroll") for (int n = 0; n < 2; ++n) _Pragma("unroll") for (int k = 0; k < 2; ++k) \
;         acc[ai][bj][m][n] = __builtin_amdgcn_mfma_f32_16x16x32_bf16(Bt[n][k], At[m][k], acc[ai][bj][m][n], 0, 0, 0); __builtin_amdgcn_s_setprio(0); } while (0)
; #define PG8_WAIT_V(n) asm volatile("s_waitcnt vmcnt(" #n ")" ::: "memory")
; #define PG8_BAR __builtin_amdgcn_s_barrier()
; template <class Epi, class Sched, bool ALIGN_EPI = false, bool SP2 = false>
; __device__ __forceinline__ void gemm_phase(PG8_LAS unsigned char* lds, const Gemm g, const Sched& S, const Epi& E, const int wid) {
;     ...
;         for (int t = 0; t < nt; t += 2) {
;             const bool last = (t == nt - 2);
;             const char* a1 = cA + (size_t)(t + 1) * kstep;
;             const char* a2 = last ? nA : cA + (size_t)(t + 2) * kstep; const char* b2 = last ? nB : cB + (size_t)(t + 2) * kstep;
;             const char* a3 = a2 + kstep; const char* b3 = b2 + kstep;
;             if (last && has_next) S.a_ready(nxt);
;             if constexpr (SP2) {
;             PG8_LDB(B0, 0, 0); PG8_LDB(B1, 0, 1); PG8_SCHED; PG8_LDA(At, 0, 0); PG8_STAGE(PG8_SA(1, 1), a1 + hstep, voffA);
;             PG8_WAIT_V(8); PG8_WAIT_L(0); PG8_BAR; PG8_MMA(0, 0, At, B0); PG8_MMA(0, 1, At, B1); PG8_BAR; PG8_SCHED;
;             PG8_LDA(At, 0, 1); PG8_STAGE(PG8_SB(0, 0), b2, voffB); PG8_STAGE(PG8_SB(0, 1), b2 + hstep, voffB); PG8_STAGE(PG8_SA(0, 0), a2, voffA);
;             PG8_WAIT_V(8); PG8_WAIT_L(0); PG8_BAR; PG8_MMA(1, 0, At, B0); PG8_MMA(1, 1, At, B1); PG8_BAR; PG8_SCHED;
	ds_read_b128 v[144:147], v151
	ds_read_b128 v[154:157], v151 offset:1024
	ds_read_b128 v[158:161], v151 offset:2048
	ds_read_b128 v[162:165], v151 offset:3072
	ds_read_b128 v[166:169], v152
	ds_read_b128 v[170:173], v152 offset:1024
	ds_read_b128 v[174:177], v152 offset:2048
	ds_read_b128 v[178:181], v152 offset:3072
	s_add_u32 s24, s22, 0xfffc0080
	s_addc_u32 s25, s23, -1
	s_cmp_eq_u32 s46, 12
	s_cselect_b32 s27, s15, s25
	s_cselect_b32 s26, s42, s24
	s_cselect_b32 s25, s13, s45
	s_cselect_b32 s24, s43, s44
	v_lshl_add_u64 v[206:207], s[22:23], 0, v[136:137]
	s_add_i32 m0, s21, 0xc000
	ds_read_b128 v[182:185], v153
	ds_read_b128 v[186:189], v153 offset:1024
	ds_read_b128 v[190:193], v153 offset:2048
	ds_read_b128 v[194:197], v153 offset:3072
	ds_read_b128 v[198:201], v153 offset:4096
	ds_read_b128 v[202:205], v153 offset:5120
	ds_read_b128 v[210:213], v153 offset:6144
	ds_read_b128 v[214:217], v153 offset:7168
	global_load_lds_dwordx4 v[206:207], off
	v_lshl_add_u64 v[206:207], s[22:23], 0, v[138:139]
	s_add_i32 m0, s21, 0xe000
	s_nop 0
	global_load_lds_dwordx4 v[206:207], off
	s_waitcnt vmcnt(8)
	s_waitcnt lgkmcnt(0)
	s_barrier
	s_waitcnt lgkmcnt(0)
	v_mfma_f32_16x16x32_bf16 v[124:127], v[144:147], v[182:185], 0
	v_mfma_f32_16x16x32_bf16 v[116:119], v[158:161], v[182:185], 0
	v_mfma_f32_16x16x32_bf16 v[108:111], v[144:147], v[190:193], 0
	v_mfma_f32_16x16x32_bf16 v[100:103], v[158:161], v[190:193], 0
	v_mfma_f32_16x16x32_bf16 v[92:95], v[144:147], v[198:201], 0
	v_mfma_f32_16x16x32_bf16 v[84:87], v[158:161], v[198:201], 0
	v_mfma_f32_16x16x32_bf16 v[76:79], v[144:147], v[210:213], 0
	v_mfma_f32_16x16x32_bf16 v[68:71], v[158:161], v[210:213], 0
	v_mfma_f32_16x16x32_bf16 v[124:127], v[154:157], v[186:189], v[124:127]
	v_mfma_f32_16x16x32_bf16 v[116:119], v[162:165], v[186:189], v[116:119]
	v_mfma_f32_16x16x32_bf16 v[108:111], v[154:157], v[194:197], v[108:111]
	v_mfma_f32_16x16x32_bf16 v[100:103], v[162:165], v[194:197], v[100:103]
	v_mfma_f32_16x16x32_bf16 v[92:95], v[154:157], v[202:205], v[92:95]
	v_mfma_f32_16x16x32_bf16 v[84:87], v[162:165], v[202:205], v[84:87]
	v_mfma_f32_16x16x32_bf16 v[76:79], v[154:157], v[214:217], v[76:79]
	v_mfma_f32_16x16x32_bf16 v[68:71], v[162:165], v[214:217], v[68:71]
	v_mfma_f32_16x16x32_bf16 v[120:123], v[166:169], v[182:185], 0
	v_mfma_f32_16x16x32_bf16 v[112:115], v[174:177], v[182:185], 0
	v_mfma_f32_16x16x32_bf16 v[104:107], v[166:169], v[190:193], 0
	v_mfma_f32_16x16x32_bf16 v[96:99], v[174:177], v[190:193], 0
	v_mfma_f32_16x16x32_bf16 v[88:91], v[166:169], v[198:201], 0
	v_mfma_f32_16x16x32_bf16 v[80:83], v[174:177], v[198:201], 0
	v_mfma_f32_16x16x32_bf16 v[72:75], v[166:169], v[210:213], 0
	v_mfma_f32_16x16x32_bf16 v[64:67], v[174:177], v[210:213], 0
	v_mfma_f32_16x16x32_bf16 v[120:123], v[170:173], v[186:189], v[120:123]
	v_mfma_f32_16x16x32_bf16 v[112:115], v[178:181], v[186:189], v[112:115]
	v_mfma_f32_16x16x32_bf16 v[104:107], v[170:173], v[194:197], v[104:107]
	v_mfma_f32_16x16x32_bf16 v[96:99], v[178:181], v[194:197], v[96:99]
	v_mfma_f32_16x16x32_bf16 v[88:91], v[170:173], v[202:205], v[88:91]
	v_mfma_f32_16x16x32_bf16 v[80:83], v[178:181], v[202:205], v[80:83]
	v_mfma_f32_16x16x32_bf16 v[72:75], v[170:173], v[214:217], v[72:75]
	v_mfma_f32_16x16x32_bf16 v[64:67], v[178:181], v[214:217], v[64:67]
	s_barrier
	s_add_i32 s47, s38, s9
	v_lshl_add_u64 v[206:207], s[24:25], 0, v[132:133]
	s_mov_b32 m0, s47
	ds_read_b128 v[182:185], v153 offset:16384
	ds_read_b128 v[186:189], v153 offset:17408
	ds_read_b128 v[190:193], v153 offset:18432
	ds_read_b128 v[194:197], v153 offset:19456
	ds_read_b128 v[198:201], v153 offset:20480
	ds_read_b128 v[202:205], v153 offset:21504
	ds_read_b128 v[210:213], v153 offset:22528
	ds_read_b128 v[214:217], v153 offset:23552
	global_load_lds_dwordx4 v[206:207], off
	s_add_i32 m0, s47, 0x2000
	s_add_u32 s48, s24, 0x40000
	v_lshl_add_u64 v[218:219], s[24:25], 0, v[128:129]
	s_addc_u32 s49, s25, 0
	s_add_i32 s47, s39, s9
	global_load_lds_dwordx4 v[218:219], off
	v_lshl_add_u64 v[220:221], s[48:49], 0, v[132:133]
	s_mov_b32 m0, s47
	v_lshl_add_u64 v[222:223], s[26:27], 0, v[130:131]
	global_load_lds_dwordx4 v[220:221], off
	v_lshl_add_u64 v[220:221], s[48:49], 0, v[128:129]
	s_add_i32 m0, s47, 0x2000
	s_nop 0
	global_load_lds_dwordx4 v[220:221], off
	v_lshl_add_u64 v[220:221], s[26:27], 0, v[134:135]
	s_mov_b32 m0, s21
	s_nop 0
	global_load_lds_dwordx4 v[220:221], off
	s_mov_b32 m0, s30
	s_nop 0
	global_load_lds_dwordx4 v[222:223], off
	s_waitcnt vmcnt(8)
	s_waitcnt lgkmcnt(0)
	s_barrier
	s_waitcnt lgkmcnt(0)
	v_mfma_f32_16x16x32_bf16 v[60:63], v[144:147], v[182:185], 0
	v_mfma_f32_16x16x32_bf16 v[52:55], v[158:161], v[182:185], 0
	v_mfma_f32_16x16x32_bf16 v[44:47], v[144:147], v[190:193], 0
	v_mfma_f32_16x16x32_bf16 v[36:39], v[158:161], v[190:193], 0
	v_mfma_f32_16x16x32_bf16 v[28:31], v[144:147], v[198:201], 0
	v_mfma_f32_16x16x32_bf16 v[20:23], v[158:161], v[198:201], 0
	v_mfma_f32_16x16x32_bf16 v[12:15], v[144:147], v[210:213], 0
	v_mfma_f32_16x16x32_bf16 v[4:7], v[158:161], v[210:213], 0
	v_mfma_f32_16x16x32_bf16 v[60:63], v[154:157], v[186:189], v[60:63]
	v_mfma_f32_16x16x32_bf16 v[52:55], v[162:165], v[186:189], v[52:55]
	v_mfma_f32_16x16x32_bf16 v[44:47], v[154:157], v[194:197], v[44:47]
	v_mfma_f32_16x16x32_bf16 v[36:39], v[162:165], v[194:197], v[36:39]
	v_mfma_f32_16x16x32_bf16 v[28:31], v[154:157], v[202:205], v[28:31]
	v_mfma_f32_16x16x32_bf16 v[20:23], v[162:165], v[202:205], v[20:23]
	v_mfma_f32_16x16x32_bf16 v[12:15], v[154:157], v[214:217], v[12:15]
	v_mfma_f32_16x16x32_bf16 v[4:7], v[162:165], v[214:217], v[4:7]
	v_mfma_f32_16x16x32_bf16 v[56:59], v[166:169], v[182:185], 0
	v_mfma_f32_16x16x32_bf16 v[48:51], v[174:177], v[182:185], 0
	v_mfma_f32_16x16x32_bf16 v[40:43], v[166:169], v[190:193], 0
	v_mfma_f32_16x16x32_bf16 v[32:35], v[174:177], v[190:193], 0
	v_mfma_f32_16x16x32_bf16 v[24:27], v[166:169], v[198:201], 0
	v_mfma_f32_16x16x32_bf16 v[16:19], v[174:177], v[198:201], 0
	v_mfma_f32_16x16x32_bf16 v[8:11], v[166:169], v[210:213], 0
	v_mfma_f32_16x16x32_bf16 v[0:3], v[174:177], v[210:213], 0
	v_mfma_f32_16x16x32_bf16 v[56:59], v[170:173], v[186:189], v[56:59]
	v_mfma_f32_16x16x32_bf16 v[48:51], v[178:181], v[186:189], v[48:51]
	v_mfma_f32_16x16x32_bf16 v[40:43], v[170:173], v[194:197], v[40:43]
	v_mfma_f32_16x16x32_bf16 v[32:35], v[178:181], v[194:197], v[32:35]
	v_mfma_f32_16x16x32_bf16 v[24:27], v[170:173], v[202:205], v[24:27]
	v_mfma_f32_16x16x32_bf16 v[16:19], v[178:181], v[202:205], v[16:19]
	v_mfma_f32_16x16x32_bf16 v[8:11], v[170:173], v[214:217], v[8:11]
	v_mfma_f32_16x16x32_bf16 v[0:3], v[178:181], v[214:217], v[0:3]
	s_barrier
; #define PG8_STAGE(bufoff, gbase, voff) do { _Pragma("unroll") for (int _i = 0; _i < 2; ++_i) \
;         __builtin_amdgcn_global_load_lds((const unsigned*)((const char*)(gbase) + (voff)[_i]), (PG8_LAS unsigned*)(lds + (bufoff) + ldsw + _i * 8192), 16, 0, 0); } while (0)
; #define PG8_LDA(dst, b, h) do { _Pragma("unroll") for (int m = 0; m < 4; ++m) _Pragma("unroll") for (int k = 0; k < 2; ++k) dst[m][k] = *(const PG8_LAS bf16x8*)(lds + PG8_SA(b, h) + aoff + m * 2048 + k * 1024); } while (0)
; #define PG8_LDB(dst, b, h) do { _Pragma("unroll") for (int n = 0; n < 2; ++n) _Pragma("unroll") for (int k = 0; k < 2; ++k) dst[n][k] = *(const PG8_LAS bf16x8*)(lds + PG8_SB(b, h) + boff + n * 2048 + k * 1024); } while (0)
; #define PG8_MMA(ai, bj, At, Bt) do { __builtin_amdgcn_s_setprio(1); _Pragma("unroll") for (int m = 0; m < 4; ++m) _Pragma("unroll") for (int n = 0; n < 2; ++n) _Pragma("unroll") for (int k = 0; k < 2; ++k) \
;         acc[ai][bj][m][n] = __builtin_amdgcn_mfma_f32_16x16x32_bf16(Bt[n][k], At[m][k], acc[ai][bj][m][n], 0, 0, 0); __builtin_amdgcn_s_setprio(0); } while (0)
; #define PG8_WAIT_V(n) asm volatile("s_waitcnt vmcnt(" #n ")" ::: "memory")
; #define PG8_WAIT_L(n) asm volatile("s_waitcnt lgkmcnt(" #n ")" ::: "memory")
; #define PG8_BAR __builtin_amdgcn_s_barrier()
; #define PG8_SCHED __builtin_amdgcn_sched_barrier(0)
; template <class Epi, class Sched, bool ALIGN_EPI = false, bool SP2 = false>
; __device__ __forceinline__ void gemm_phase(PG8_LAS unsigned char* lds, const Gemm g, const Sched& S, const Epi& E, const int wid) {
;     ...
;             PG8_LDB(B0, 1, 0); PG8_LDB(B1, 1, 1); PG8_SCHED; PG8_LDA(At, 1, 0); PG8_STAGE(PG8_SA(0, 1), a2 + hstep, voffA);
;             PG8_WAIT_V(8); PG8_WAIT_L(0); PG8_BAR; PG8_MMA(0, 0, At, B0); PG8_MMA(0, 1, At, B1); PG8_BAR; PG8_SCHED;
;             PG8_LDA(At, 1, 1); PG8_STAGE(PG8_SB(1, 0), b3, voffB); PG8_STAGE(PG8_SB(1, 1), b3 + hstep, voffB); PG8_STAGE(PG8_SA(1, 0), a3, voffA);
;             PG8_WAIT_V(8); PG8_WAIT_L(0); PG8_BAR; PG8_MMA(1, 0, At, B0); PG8_MMA(1, 1, At, B1); PG8_BAR; PG8_SCHED;
	s_add_i32 s47, 0, 0x18000
	s_add_i32 s48, 0, 0x1c000
	v_add_u32_e32 v162, s47, v149
	v_add_u32_e32 v178, s48, v149
	ds_read_b128 v[144:147], v162
	ds_read_b128 v[154:157], v162 offset:1024
	ds_read_b128 v[158:161], v162 offset:2048
	ds_read_b128 v[162:165], v162 offset:3072
	ds_read_b128 v[166:169], v178
	ds_read_b128 v[170:173], v178 offset:1024
	ds_read_b128 v[174:177], v178 offset:2048
	ds_read_b128 v[178:181], v178 offset:3072
	s_add_u32 s26, s26, 0x40000
	s_addc_u32 s27, s27, 0
	s_mov_b32 m0, s31
	v_lshl_add_u64 v[224:225], s[26:27], 0, v[134:135]
	ds_read_b128 v[182:185], v153 offset:32768
	ds_read_b128 v[186:189], v153 offset:33792
	ds_read_b128 v[190:193], v153 offset:34816
	ds_read_b128 v[194:197], v153 offset:35840
	ds_read_b128 v[198:201], v153 offset:36864
	ds_read_b128 v[202:205], v153 offset:37888
	ds_read_b128 v[210:213], v153 offset:38912
	ds_read_b128 v[214:217], v153 offset:39936
	global_load_lds_dwordx4 v[224:225], off
	v_lshl_add_u64 v[224:225], s[26:27], 0, v[130:131]
	s_mov_b32 m0, s33
	s_nop 0
	global_load_lds_dwordx4 v[224:225], off
	s_waitcnt vmcnt(8)
	s_waitcnt lgkmcnt(0)
	s_barrier
	s_waitcnt lgkmcnt(0)
	v_mfma_f32_16x16x32_bf16 v[124:127], v[144:147], v[182:185], v[124:127]
	v_mfma_f32_16x16x32_bf16 v[116:119], v[158:161], v[182:185], v[116:119]
	v_mfma_f32_16x16x32_bf16 v[108:111], v[144:147], v[190:193], v[108:111]
	v_mfma_f32_16x16x32_bf16 v[100:103], v[158:161], v[190:193], v[100:103]
	v_mfma_f32_16x16x32_bf16 v[92:95], v[144:147], v[198:201], v[92:95]
	v_mfma_f32_16x16x32_bf16 v[84:87], v[158:161], v[198:201], v[84:87]
	v_mfma_f32_16x16x32_bf16 v[76:79], v[144:147], v[210:213], v[76:79]
	v_mfma_f32_16x16x32_bf16 v[68:71], v[158:161], v[210:213], v[68:71]
	v_mfma_f32_16x16x32_bf16 v[124:127], v[154:157], v[186:189], v[124:127]
	v_mfma_f32_16x16x32_bf16 v[116:119], v[162:165], v[186:189], v[116:119]
	v_mfma_f32_16x16x32_bf16 v[108:111], v[154:157], v[194:197], v[108:111]
	v_mfma_f32_16x16x32_bf16 v[100:103], v[162:165], v[194:197], v[100:103]
	v_mfma_f32_16x16x32_bf16 v[92:95], v[154:157], v[202:205], v[92:95]
	v_mfma_f32_16x16x32_bf16 v[84:87], v[162:165], v[202:205], v[84:87]
	v_mfma_f32_16x16x32_bf16 v[76:79], v[154:157], v[214:217], v[76:79]
	v_mfma_f32_16x16x32_bf16 v[68:71], v[162:165], v[214:217], v[68:71]
	v_mfma_f32_16x16x32_bf16 v[120:123], v[166:169], v[182:185], v[120:123]
	v_mfma_f32_16x16x32_bf16 v[112:115], v[174:177], v[182:185], v[112:115]
	v_mfma_f32_16x16x32_bf16 v[104:107], v[166:169], v[190:193], v[104:107]
	v_mfma_f32_16x16x32_bf16 v[96:99], v[174:177], v[190:193], v[96:99]
	v_mfma_f32_16x16x32_bf16 v[88:91], v[166:169], v[198:201], v[88:91]
	v_mfma_f32_16x16x32_bf16 v[80:83], v[174:177], v[198:201], v[80:83]
	v_mfma_f32_16x16x32_bf16 v[72:75], v[166:169], v[210:213], v[72:75]
	v_mfma_f32_16x16x32_bf16 v[64:67], v[174:177], v[210:213], v[64:67]
	v_mfma_f32_16x16x32_bf16 v[120:123], v[170:173], v[186:189], v[120:123]
	v_mfma_f32_16x16x32_bf16 v[112:115], v[178:181], v[186:189], v[112:115]
	v_mfma_f32_16x16x32_bf16 v[104:107], v[170:173], v[194:197], v[104:107]
	v_mfma_f32_16x16x32_bf16 v[96:99], v[178:181], v[194:197], v[96:99]
	v_mfma_f32_16x16x32_bf16 v[88:91], v[170:173], v[202:205], v[88:91]
	v_mfma_f32_16x16x32_bf16 v[80:83], v[178:181], v[202:205], v[80:83]
	v_mfma_f32_16x16x32_bf16 v[72:75], v[170:173], v[214:217], v[72:75]
	v_mfma_f32_16x16x32_bf16 v[64:67], v[178:181], v[214:217], v[64:67]
	s_barrier
	s_add_i32 s26, s47, s9
	v_lshl_add_u64 v[206:207], v[206:207], 0, s[2:3]
	s_mov_b32 m0, s26
	ds_read_b128 v[182:185], v153 offset:49152
	ds_read_b128 v[186:189], v153 offset:50176
	ds_read_b128 v[190:193], v153 offset:51200
	ds_read_b128 v[194:197], v153 offset:52224
	ds_read_b128 v[198:201], v153 offset:53248
	ds_read_b128 v[202:205], v153 offset:54272
	ds_read_b128 v[210:213], v153 offset:55296
	ds_read_b128 v[214:217], v153 offset:56320
	global_load_lds_dwordx4 v[206:207], off
	s_add_i32 m0, s26, 0x2000
	s_add_u32 s24, s24, 0x40080
	v_lshl_add_u64 v[206:207], v[218:219], 0, s[2:3]
	s_addc_u32 s25, s25, 0
	s_add_i32 s26, s48, s9
	global_load_lds_dwordx4 v[206:207], off
	v_lshl_add_u64 v[206:207], s[24:25], 0, v[132:133]
	s_mov_b32 m0, s26
	s_nop 0
	global_load_lds_dwordx4 v[206:207], off
	v_lshl_add_u64 v[206:207], s[24:25], 0, v[128:129]
	s_add_i32 m0, s26, 0x2000
	s_nop 0
	global_load_lds_dwordx4 v[206:207], off
	v_lshl_add_u64 v[206:207], v[220:221], 0, s[2:3]
	s_mov_b32 m0, s35
	s_nop 0
	global_load_lds_dwordx4 v[206:207], off
	v_lshl_add_u64 v[206:207], v[222:223], 0, s[2:3]
	s_mov_b32 m0, s36
	s_nop 0
	global_load_lds_dwordx4 v[206:207], off
	s_waitcnt vmcnt(8)
	s_waitcnt lgkmcnt(0)
	s_barrier
; #define PG8_STAGE(bufoff, gbase, voff) do { _Pragma("unroll") for (int _i = 0; _i < 2; ++_i) \
;         __builtin_amdgcn_global_load_lds((const unsigned*)((const char*)(gbase) + (voff)[_i]), (PG8_LAS unsigned*)(lds + (bufoff) + ldsw + _i * 8192), 16, 0, 0); } while (0)
; #define PG8_LDA(dst, b, h) do { _Pragma("unroll") for (int m = 0; m < 4; ++m) _Pragma("unroll") for (int k = 0; k < 2; ++k) dst[m][k] = *(const PG8_LAS bf16x8*)(lds + PG8_SA(b, h) + aoff + m * 2048 + k * 1024); } while (0)
; #define PG8_WAIT_V(n) asm volatile("s_waitcnt vmcnt(" #n ")" ::: "memory")
; #define PG8_WAIT_L(n) asm volatile("s_waitcnt lgkmcnt(" #n ")" ::: "memory")
; #define PG8_BAR __builtin_amdgcn_s_barrier()
; template <class Epi, class Sched, bool ALIGN_EPI = false, bool SP2 = false>
; __device__ __forceinline__ void gemm_phase(PG8_LAS unsigned char* lds, const Gemm g, const Sched& S, const Epi& E, const int wid) {
;     ...
;         for (int t = 0; t < nt; t += 2) {
;             const bool last = (t == nt - 2);
;             const char* a1 = cA + (size_t)(t + 1) * kstep;
;             const char* a2 = last ? nA : cA + (size_t)(t + 2) * kstep; const char* b2 = last ? nB : cB + (size_t)(t + 2) * kstep;
;             const char* a3 = a2 + kstep; const char* b3 = b2 + kstep;
;             if (last && has_next) S.a_ready(nxt);
;             if constexpr (SP2) {
;             PG8_LDB(B0, 0, 0); PG8_LDB(B1, 0, 1); PG8_SCHED; PG8_LDA(At, 0, 0); PG8_STAGE(PG8_SA(1, 1), a1 + hstep, voffA);
;             PG8_WAIT_V(8); PG8_WAIT_L(0); PG8_BAR; PG8_MMA(0, 0, At, B0); PG8_MMA(0, 1, At, B1); PG8_BAR; PG8_SCHED;
;             PG8_LDA(At, 0, 1); PG8_STAGE(PG8_SB(0, 0), b2, voffB); PG8_STAGE(PG8_SB(0, 1), b2 + hstep, voffB); PG8_STAGE(PG8_SA(0, 0), a2, voffA);
;             PG8_WAIT_V(8); PG8_WAIT_L(0); PG8_BAR; PG8_MMA(1, 0, At, B0); PG8_MMA(1, 1, At, B1); PG8_BAR; PG8_SCHED;
;             PG8_LDB(B0, 1, 0); PG8_LDB(B1, 1, 1); PG8_SCHED; PG8_LDA(At, 1, 0); PG8_STAGE(PG8_SA(0, 1), a2 + hstep, voffA);
;             PG8_WAIT_V(8); PG8_WAIT_L(0); PG8_BAR; PG8_MMA(0, 0, At, B0); PG8_MMA(0, 1, At, B1); PG8_BAR; PG8_SCHED;
;             PG8_LDA(At, 1, 1); PG8_STAGE(PG8_SB(1, 0), b3, voffB); PG8_STAGE(PG8_SB(1, 1), b3 + hstep, voffB); PG8_STAGE(PG8_SA(1, 0), a3, voffA);
;             PG8_WAIT_V(8); PG8_WAIT_L(0); PG8_BAR; PG8_MMA(1, 0, At, B0); PG8_MMA(1, 1, At, B1); PG8_BAR; PG8_SCHED;
	s_waitcnt lgkmcnt(0)
	v_mfma_f32_16x16x32_bf16 v[60:63], v[144:147], v[182:185], v[60:63]
	v_mfma_f32_16x16x32_bf16 v[52:55], v[158:161], v[182:185], v[52:55]
	v_mfma_f32_16x16x32_bf16 v[44:47], v[144:147], v[190:193], v[44:47]
	v_mfma_f32_16x16x32_bf16 v[36:39], v[158:161], v[190:193], v[36:39]
	v_mfma_f32_16x16x32_bf16 v[28:31], v[144:147], v[198:201], v[28:31]
	v_mfma_f32_16x16x32_bf16 v[20:23], v[158:161], v[198:201], v[20:23]
	v_mfma_f32_16x16x32_bf16 v[12:15], v[144:147], v[210:213], v[12:15]
	v_mfma_f32_16x16x32_bf16 v[4:7], v[158:161], v[210:213], v[4:7]
	v_mfma_f32_16x16x32_bf16 v[60:63], v[154:157], v[186:189], v[60:63]
	v_mfma_f32_16x16x32_bf16 v[52:55], v[162:165], v[186:189], v[52:55]
	v_mfma_f32_16x16x32_bf16 v[44:47], v[154:157], v[194:197], v[44:47]
	v_mfma_f32_16x16x32_bf16 v[36:39], v[162:165], v[194:197], v[36:39]
	v_mfma_f32_16x16x32_bf16 v[28:31], v[154:157], v[202:205], v[28:31]
	v_mfma_f32_16x16x32_bf16 v[20:23], v[162:165], v[202:205], v[20:23]
	v_mfma_f32_16x16x32_bf16 v[12:15], v[154:157], v[214:217], v[12:15]
	v_mfma_f32_16x16x32_bf16 v[4:7], v[162:165], v[214:217], v[4:7]
	v_mfma_f32_16x16x32_bf16 v[56:59], v[166:169], v[182:185], v[56:59]
	v_mfma_f32_16x16x32_bf16 v[48:51], v[174:177], v[182:185], v[48:51]
	v_mfma_f32_16x16x32_bf16 v[40:43], v[166:169], v[190:193], v[40:43]
	v_mfma_f32_16x16x32_bf16 v[32:35], v[174:177], v[190:193], v[32:35]
	v_mfma_f32_16x16x32_bf16 v[24:27], v[166:169], v[198:201], v[24:27]
	v_mfma_f32_16x16x32_bf16 v[16:19], v[174:177], v[198:201], v[16:19]
	v_mfma_f32_16x16x32_bf16 v[8:11], v[166:169], v[210:213], v[8:11]
	v_mfma_f32_16x16x32_bf16 v[0:3], v[174:177], v[210:213], v[0:3]
	v_mfma_f32_16x16x32_bf16 v[56:59], v[170:173], v[186:189], v[56:59]
	v_mfma_f32_16x16x32_bf16 v[48:51], v[178:181], v[186:189], v[48:51]
	v_mfma_f32_16x16x32_bf16 v[40:43], v[170:173], v[194:197], v[40:43]
	v_mfma_f32_16x16x32_bf16 v[32:35], v[178:181], v[194:197], v[32:35]
	v_mfma_f32_16x16x32_bf16 v[24:27], v[170:173], v[202:205], v[24:27]
	v_mfma_f32_16x16x32_bf16 v[16:19], v[178:181], v[202:205], v[16:19]
	v_mfma_f32_16x16x32_bf16 v[8:11], v[170:173], v[214:217], v[8:11]
	v_mfma_f32_16x16x32_bf16 v[0:3], v[178:181], v[214:217], v[0:3]
	s_barrier
	s_add_i32 s46, s46, 2
	s_add_u32 s22, s22, 0x100
	s_addc_u32 s23, s23, 0
	s_add_u32 s44, s44, 0x100
	s_addc_u32 s45, s45, 0
	s_cmp_gt_u32 s46, 13
	s_cbranch_scc0 .LBB0_1912
	s_branch .Lkp_exit_4
.LBB0_1912:
	ds_read_b128 v[144:147], v151
	ds_read_b128 v[154:157], v151 offset:1024
	ds_read_b128 v[158:161], v151 offset:2048
	ds_read_b128 v[162:165], v151 offset:3072
	ds_read_b128 v[166:169], v152
	ds_read_b128 v[170:173], v152 offset:1024
	ds_read_b128 v[174:177], v152 offset:2048
	ds_read_b128 v[178:181], v152 offset:3072
	s_add_u32 s24, s22, 0xfffc0080
	s_addc_u32 s25, s23, -1
	s_cmp_eq_u32 s46, 12
	s_cselect_b32 s27, s15, s25
	s_cselect_b32 s26, s42, s24
	s_cselect_b32 s25, s13, s45
	s_cselect_b32 s24, s43, s44
	v_lshl_add_u64 v[206:207], s[22:23], 0, v[136:137]
	s_add_i32 m0, s21, 0xc000
	ds_read_b128 v[182:185], v153
	ds_read_b128 v[186:189], v153 offset:1024
	ds_read_b128 v[190:193], v153 offset:2048
	ds_read_b128 v[194:197], v153 offset:3072
	ds_read_b128 v[198:201], v153 offset:4096
	ds_read_b128 v[202:205], v153 offset:5120
	ds_read_b128 v[210:213], v153 offset:6144
	ds_read_b128 v[214:217], v153 offset:7168
	global_load_lds_dwordx4 v[206:207], off
	v_lshl_add_u64 v[206:207], s[22:23], 0, v[138:139]
	s_add_i32 m0, s21, 0xe000
	s_nop 0
	global_load_lds_dwordx4 v[206:207], off
	s_waitcnt vmcnt(8)
	s_waitcnt lgkmcnt(0)
	s_barrier
	s_waitcnt lgkmcnt(0)
	v_mfma_f32_16x16x32_bf16 v[124:127], v[144:147], v[182:185], v[124:127]
	v_mfma_f32_16x16x32_bf16 v[116:119], v[158:161], v[182:185], v[116:119]
	v_mfma_f32_16x16x32_bf16 v[108:111], v[144:147], v[190:193], v[108:111]
	v_mfma_f32_16x16x32_bf16 v[100:103], v[158:161], v[190:193], v[100:103]
	v_mfma_f32_16x16x32_bf16 v[92:95], v[144:147], v[198:201], v[92:95]
	v_mfma_f32_16x16x32_bf16 v[84:87], v[158:161], v[198:201], v[84:87]
	v_mfma_f32_16x16x32_bf16 v[76:79], v[144:147], v[210:213], v[76:79]
	v_mfma_f32_16x16x32_bf16 v[68:71], v[158:161], v[210:213], v[68:71]
	v_mfma_f32_16x16x32_bf16 v[124:127], v[154:157], v[186:189], v[124:127]
	v_mfma_f32_16x16x32_bf16 v[116:119], v[162:165], v[186:189], v[116:119]
	v_mfma_f32_16x16x32_bf16 v[108:111], v[154:157], v[194:197], v[108:111]
	v_mfma_f32_16x16x32_bf16 v[100:103], v[162:165], v[194:197], v[100:103]
	v_mfma_f32_16x16x32_bf16 v[92:95], v[154:157], v[202:205], v[92:95]
	v_mfma_f32_16x16x32_bf16 v[84:87], v[162:165], v[202:205], v[84:87]
	v_mfma_f32_16x16x32_bf16 v[76:79], v[154:157], v[214:217], v[76:79]
	v_mfma_f32_16x16x32_bf16 v[68:71], v[162:165], v[214:217], v[68:71]
	v_mfma_f32_16x16x32_bf16 v[120:123], v[166:169], v[182:185], v[120:123]
	v_mfma_f32_16x16x32_bf16 v[112:115], v[174:177], v[182:185], v[112:115]
	v_mfma_f32_16x16x32_bf16 v[104:107], v[166:169], v[190:193], v[104:107]
	v_mfma_f32_16x16x32_bf16 v[96:99], v[174:177], v[190:193], v[96:99]
	v_mfma_f32_16x16x32_bf16 v[88:91], v[166:169], v[198:201], v[88:91]
	v_mfma_f32_16x16x32_bf16 v[80:83], v[174:177], v[198:201], v[80:83]
	v_mfma_f32_16x16x32_bf16 v[72:75], v[166:169], v[210:213], v[72:75]
	v_mfma_f32_16x16x32_bf16 v[64:67], v[174:177], v[210:213], v[64:67]
	v_mfma_f32_16x16x32_bf16 v[120:123], v[170:173], v[186:189], v[120:123]
	v_mfma_f32_16x16x32_bf16 v[112:115], v[178:181], v[186:189], v[112:115]
	v_mfma_f32_16x16x32_bf16 v[104:107], v[170:173], v[194:197], v[104:107]
	v_mfma_f32_16x16x32_bf16 v[96:99], v[178:181], v[194:197], v[96:99]
	v_mfma_f32_16x16x32_bf16 v[88:91], v[170:173], v[202:205], v[88:91]
	v_mfma_f32_16x16x32_bf16 v[80:83], v[178:181], v[202:205], v[80:83]
	v_mfma_f32_16x16x32_bf16 v[72:75], v[170:173], v[214:217], v[72:75]
	v_mfma_f32_16x16x32_bf16 v[64:67], v[178:181], v[214:217], v[64:67]
	s_barrier
; #define PG8_STAGE(bufoff, gbase, voff) do { _Pragma("unroll") for (int _i = 0; _i < 2; ++_i) \
;         __builtin_amdgcn_global_load_lds((const unsigned*)((const char*)(gbase) + (voff)[_i]), (PG8_LAS unsigned*)(lds + (bufoff) + ldsw + _i * 8192), 16, 0, 0); } while (0)
; #define PG8_LDA(dst, b, h) do { _Pragma("unroll") for (int m = 0; m < 4; ++m) _Pragma("unroll") for (int k = 0; k < 2; ++k) dst[m][k] = *(const PG8_LAS bf16x8*)(lds + PG8_SA(b, h) + aoff + m * 2048 + k * 1024); } while (0)
; #define PG8_LDB(dst, b, h) do { _Pragma("unroll") for (int n = 0; n < 2; ++n) _Pragma("unroll") for (int k = 0; k < 2; ++k) dst[n][k] = *(const PG8_LAS bf16x8*)(lds + PG8_SB(b, h) + boff + n * 2048 + k * 1024); } while (0)
; #define PG8_MMA(ai, bj, At, Bt) do { __builtin_amdgcn_s_setprio(1); _Pragma("unroll") for (int m = 0; m < 4; ++m) _Pragma("unroll") for (int n = 0; n < 2; ++n) _Pragma("unroll") for (int k = 0; k < 2; ++k) \
;         acc[ai][bj][m][n] = __builtin_amdgcn_mfma_f32_16x16x32_bf16(Bt[n][k], At[m][k], acc[ai][bj][m][n], 0, 0, 0); __builtin_amdgcn_s_setprio(0); } while (0)
; #define PG8_WAIT_V(n) asm volatile("s_waitcnt vmcnt(" #n ")" ::: "memory")
; #define PG8_WAIT_L(n) asm volatile("s_waitcnt lgkmcnt(" #n ")" ::: "memory")
; #define PG8_BAR __builtin_amdgcn_s_barrier()
; #define PG8_SCHED __builtin_amdgcn_sched_barrier(0)
; template <class Epi, class Sched, bool ALIGN_EPI = false, bool SP2 = false>
; __device__ __forceinline__ void gemm_phase(PG8_LAS unsigned char* lds, const Gemm g, const Sched& S, const Epi& E, const int wid) {
;     ...
;             PG8_LDB(B0, 0, 0); PG8_LDB(B1, 0, 1); PG8_SCHED; PG8_LDA(At, 0, 0); PG8_STAGE(PG8_SA(1, 1), a1 + hstep, voffA);
;             PG8_WAIT_V(8); PG8_WAIT_L(0); PG8_BAR; PG8_MMA(0, 0, At, B0); PG8_MMA(0, 1, At, B1); PG8_BAR; PG8_SCHED;
;             PG8_LDA(At, 0, 1); PG8_STAGE(PG8_SB(0, 0), b2, voffB); PG8_STAGE(PG8_SB(0, 1), b2 + hstep, voffB); PG8_STAGE(PG8_SA(0, 0), a2, voffA);
;             PG8_WAIT_V(8); PG8_WAIT_L(0); PG8_BAR; PG8_MMA(1, 0, At, B0); PG8_MMA(1, 1, At, B1); PG8_BAR; PG8_SCHED;
;             PG8_LDB(B0, 1, 0); PG8_LDB(B1, 1, 1); PG8_SCHED; PG8_LDA(At, 1, 0); PG8_STAGE(PG8_SA(0, 1), a2 + hstep, voffA);
;             PG8_WAIT_V(8); PG8_WAIT_L(0); PG8_BAR; PG8_MMA(0, 0, At, B0); PG8_MMA(0, 1, At, B1); PG8_BAR; PG8_SCHED;
	s_add_i32 s47, s38, s9
	v_lshl_add_u64 v[206:207], s[24:25], 0, v[132:133]
	s_mov_b32 m0, s47
	ds_read_b128 v[182:185], v153 offset:16384
	ds_read_b128 v[186:189], v153 offset:17408
	ds_read_b128 v[190:193], v153 offset:18432
	ds_read_b128 v[194:197], v153 offset:19456
	ds_read_b128 v[198:201], v153 offset:20480
	ds_read_b128 v[202:205], v153 offset:21504
	ds_read_b128 v[210:213], v153 offset:22528
	ds_read_b128 v[214:217], v153 offset:23552
	global_load_lds_dwordx4 v[206:207], off
	s_add_i32 m0, s47, 0x2000
	s_add_u32 s48, s24, 0x40000
	v_lshl_add_u64 v[218:219], s[24:25], 0, v[128:129]
	s_addc_u32 s49, s25, 0
	s_add_i32 s47, s39, s9
	global_load_lds_dwordx4 v[218:219], off
	v_lshl_add_u64 v[220:221], s[48:49], 0, v[132:133]
	s_mov_b32 m0, s47
	v_lshl_add_u64 v[222:223], s[26:27], 0, v[130:131]
	global_load_lds_dwordx4 v[220:221], off
	v_lshl_add_u64 v[220:221], s[48:49], 0, v[128:129]
	s_add_i32 m0, s47, 0x2000
	s_nop 0
	global_load_lds_dwordx4 v[220:221], off
	v_lshl_add_u64 v[220:221], s[26:27], 0, v[134:135]
	s_mov_b32 m0, s21
	s_nop 0
	global_load_lds_dwordx4 v[220:221], off
	s_mov_b32 m0, s30
	s_nop 0
	global_load_lds_dwordx4 v[222:223], off
	s_waitcnt vmcnt(8)
	s_waitcnt lgkmcnt(0)
	s_barrier
	s_waitcnt lgkmcnt(0)
	v_mfma_f32_16x16x32_bf16 v[60:63], v[144:147], v[182:185], v[60:63]
	v_mfma_f32_16x16x32_bf16 v[52:55], v[158:161], v[182:185], v[52:55]
	v_mfma_f32_16x16x32_bf16 v[44:47], v[144:147], v[190:193], v[44:47]
	v_mfma_f32_16x16x32_bf16 v[36:39], v[158:161], v[190:193], v[36:39]
	v_mfma_f32_16x16x32_bf16 v[28:31], v[144:147], v[198:201], v[28:31]
	v_mfma_f32_16x16x32_bf16 v[20:23], v[158:161], v[198:201], v[20:23]
	v_mfma_f32_16x16x32_bf16 v[12:15], v[144:147], v[210:213], v[12:15]
	v_mfma_f32_16x16x32_bf16 v[4:7], v[158:161], v[210:213], v[4:7]
	v_mfma_f32_16x16x32_bf16 v[60:63], v[154:157], v[186:189], v[60:63]
	v_mfma_f32_16x16x32_bf16 v[52:55], v[162:165], v[186:189], v[52:55]
	v_mfma_f32_16x16x32_bf16 v[44:47], v[154:157], v[194:197], v[44:47]
	v_mfma_f32_16x16x32_bf16 v[36:39], v[162:165], v[194:197], v[36:39]
	v_mfma_f32_16x16x32_bf16 v[28:31], v[154:157], v[202:205], v[28:31]
	v_mfma_f32_16x16x32_bf16 v[20:23], v[162:165], v[202:205], v[20:23]
	v_mfma_f32_16x16x32_bf16 v[12:15], v[154:157], v[214:217], v[12:15]
	v_mfma_f32_16x16x32_bf16 v[4:7], v[162:165], v[214:217], v[4:7]
	v_mfma_f32_16x16x32_bf16 v[56:59], v[166:169], v[182:185], v[56:59]
	v_mfma_f32_16x16x32_bf16 v[48:51], v[174:177], v[182:185], v[48:51]
	v_mfma_f32_16x16x32_bf16 v[40:43], v[166:169], v[190:193], v[40:43]
	v_mfma_f32_16x16x32_bf16 v[32:35], v[174:177], v[190:193], v[32:35]
	v_mfma_f32_16x16x32_bf16 v[24:27], v[166:169], v[198:201], v[24:27]
	v_mfma_f32_16x16x32_bf16 v[16:19], v[174:177], v[198:201], v[16:19]
	v_mfma_f32_16x16x32_bf16 v[8:11], v[166:169], v[210:213], v[8:11]
	v_mfma_f32_16x16x32_bf16 v[0:3], v[174:177], v[210:213], v[0:3]
	v_mfma_f32_16x16x32_bf16 v[56:59], v[170:173], v[186:189], v[56:59]
	v_mfma_f32_16x16x32_bf16 v[48:51], v[178:181], v[186:189], v[48:51]
	v_mfma_f32_16x16x32_bf16 v[40:43], v[170:173], v[194:197], v[40:43]
	v_mfma_f32_16x16x32_bf16 v[32:35], v[178:181], v[194:197], v[32:35]
	v_mfma_f32_16x16x32_bf16 v[24:27], v[170:173], v[202:205], v[24:27]
	v_mfma_f32_16x16x32_bf16 v[16:19], v[178:181], v[202:205], v[16:19]
	v_mfma_f32_16x16x32_bf16 v[8:11], v[170:173], v[214:217], v[8:11]
	v_mfma_f32_16x16x32_bf16 v[0:3], v[178:181], v[214:217], v[0:3]
	s_barrier
	s_add_i32 s47, 0, 0x18000
	s_add_i32 s48, 0, 0x1c000
	v_add_u32_e32 v162, s47, v149
	v_add_u32_e32 v178, s48, v149
	ds_read_b128 v[144:147], v162
	ds_read_b128 v[154:157], v162 offset:1024
	ds_read_b128 v[158:161], v162 offset:2048
	ds_read_b128 v[162:165], v162 offset:3072
	ds_read_b128 v[166:169], v178
	ds_read_b128 v[170:173], v178 offset:1024
	ds_read_b128 v[174:177], v178 offset:2048
	ds_read_b128 v[178:181], v178 offset:3072
	s_add_u32 s26, s26, 0x40000
	s_addc_u32 s27, s27, 0
	s_mov_b32 m0, s31
	v_lshl_add_u64 v[224:225], s[26:27], 0, v[134:135]
	ds_read_b128 v[182:185], v153 offset:32768
	ds_read_b128 v[186:189], v153 offset:33792
	ds_read_b128 v[190:193], v153 offset:34816
	ds_read_b128 v[194:197], v153 offset:35840
	ds_read_b128 v[198:201], v153 offset:36864
	ds_read_b128 v[202:205], v153 offset:37888
	ds_read_b128 v[210:213], v153 offset:38912
	ds_read_b128 v[214:217], v153 offset:39936
	global_load_lds_dwordx4 v[224:225], off
	v_lshl_add_u64 v[224:225], s[26:27], 0, v[130:131]
	s_mov_b32 m0, s33
	s_nop 0
	global_load_lds_dwordx4 v[224:225], off
	s_waitcnt vmcnt(8)
	s_waitcnt lgkmcnt(0)
	s_barrier
; #define PG8_STAGE(bufoff, gbase, voff) do { _Pragma("unroll") for (int _i = 0; _i < 2; ++_i) \
;         __builtin_amdgcn_global_load_lds((const unsigned*)((const char*)(gbase) + (voff)[_i]), (PG8_LAS unsigned*)(lds + (bufoff) + ldsw + _i * 8192), 16, 0, 0); } while (0)
; #define PG8_LDA(dst, b, h) do { _Pragma("unroll") for (int m = 0; m < 4; ++m) _Pragma("unroll") for (int k = 0; k < 2; ++k) dst[m][k] = *(const PG8_LAS bf16x8*)(lds + PG8_SA(b, h) + aoff + m * 2048 + k * 1024); } while (0)
; #define PG8_WAIT_V(n) asm volatile("s_waitcnt vmcnt(" #n ")" ::: "memory")
; #define PG8_WAIT_L(n) asm volatile("s_waitcnt lgkmcnt(" #n ")" ::: "memory")
; #define PG8_BAR __builtin_amdgcn_s_barrier()
; template <class Epi, class Sched, bool ALIGN_EPI = false, bool SP2 = false>
; __device__ __forceinline__ void gemm_phase(PG8_LAS unsigned char* lds, const Gemm g, const Sched& S, const Epi& E, const int wid) {
;     ...
;         for (int t = 0; t < nt; t += 2) {
;             const bool last = (t == nt - 2);
;             const char* a1 = cA + (size_t)(t + 1) * kstep;
;             const char* a2 = last ? nA : cA + (size_t)(t + 2) * kstep; const char* b2 = last ? nB : cB + (size_t)(t + 2) * kstep;
;             const char* a3 = a2 + kstep; const char* b3 = b2 + kstep;
;             if (last && has_next) S.a_ready(nxt);
;             if constexpr (SP2) {
;             PG8_LDB(B0, 0, 0); PG8_LDB(B1, 0, 1); PG8_SCHED; PG8_LDA(At, 0, 0); PG8_STAGE(PG8_SA(1, 1), a1 + hstep, voffA);
;             PG8_WAIT_V(8); PG8_WAIT_L(0); PG8_BAR; PG8_MMA(0, 0, At, B0); PG8_MMA(0, 1, At, B1); PG8_BAR; PG8_SCHED;
;             PG8_LDA(At, 0, 1); PG8_STAGE(PG8_SB(0, 0), b2, voffB); PG8_STAGE(PG8_SB(0, 1), b2 + hstep, voffB); PG8_STAGE(PG8_SA(0, 0), a2, voffA);
;             PG8_WAIT_V(8); PG8_WAIT_L(0); PG8_BAR; PG8_MMA(1, 0, At, B0); PG8_MMA(1, 1, At, B1); PG8_BAR; PG8_SCHED;
;             PG8_LDB(B0, 1, 0); PG8_LDB(B1, 1, 1); PG8_SCHED; PG8_LDA(At, 1, 0); PG8_STAGE(PG8_SA(0, 1), a2 + hstep, voffA);
;             PG8_WAIT_V(8); PG8_WAIT_L(0); PG8_BAR; PG8_MMA(0, 0, At, B0); PG8_MMA(0, 1, At, B1); PG8_BAR; PG8_SCHED;
;             PG8_LDA(At, 1, 1); PG8_STAGE(PG8_SB(1, 0), b3, voffB); PG8_STAGE(PG8_SB(1, 1), b3 + hstep, voffB); PG8_STAGE(PG8_SA(1, 0), a3, voffA);
;             PG8_WAIT_V(8); PG8_WAIT_L(0); PG8_BAR; PG8_MMA(1, 0, At, B0); PG8_MMA(1, 1, At, B1); PG8_BAR; PG8_SCHED;
	s_waitcnt lgkmcnt(0)
	v_mfma_f32_16x16x32_bf16 v[124:127], v[144:147], v[182:185], v[124:127]
	v_mfma_f32_16x16x32_bf16 v[116:119], v[158:161], v[182:185], v[116:119]
	v_mfma_f32_16x16x32_bf16 v[108:111], v[144:147], v[190:193], v[108:111]
	v_mfma_f32_16x16x32_bf16 v[100:103], v[158:161], v[190:193], v[100:103]
	v_mfma_f32_16x16x32_bf16 v[92:95], v[144:147], v[198:201], v[92:95]
	v_mfma_f32_16x16x32_bf16 v[84:87], v[158:161], v[198:201], v[84:87]
	v_mfma_f32_16x16x32_bf16 v[76:79], v[144:147], v[210:213], v[76:79]
	v_mfma_f32_16x16x32_bf16 v[68:71], v[158:161], v[210:213], v[68:71]
	v_mfma_f32_16x16x32_bf16 v[124:127], v[154:157], v[186:189], v[124:127]
	v_mfma_f32_16x16x32_bf16 v[116:119], v[162:165], v[186:189], v[116:119]
	v_mfma_f32_16x16x32_bf16 v[108:111], v[154:157], v[194:197], v[108:111]
	v_mfma_f32_16x16x32_bf16 v[100:103], v[162:165], v[194:197], v[100:103]
	v_mfma_f32_16x16x32_bf16 v[92:95], v[154:157], v[202:205], v[92:95]
	v_mfma_f32_16x16x32_bf16 v[84:87], v[162:165], v[202:205], v[84:87]
	v_mfma_f32_16x16x32_bf16 v[76:79], v[154:157], v[214:217], v[76:79]
	v_mfma_f32_16x16x32_bf16 v[68:71], v[162:165], v[214:217], v[68:71]
	v_mfma_f32_16x16x32_bf16 v[120:123], v[166:169], v[182:185], v[120:123]
	v_mfma_f32_16x16x32_bf16 v[112:115], v[174:177], v[182:185], v[112:115]
	v_mfma_f32_16x16x32_bf16 v[104:107], v[166:169], v[190:193], v[104:107]
	v_mfma_f32_16x16x32_bf16 v[96:99], v[174:177], v[190:193], v[96:99]
	v_mfma_f32_16x16x32_bf16 v[88:91], v[166:169], v[198:201], v[88:91]
	v_mfma_f32_16x16x32_bf16 v[80:83], v[174:177], v[198:201], v[80:83]
	v_mfma_f32_16x16x32_bf16 v[72:75], v[166:169], v[210:213], v[72:75]
	v_mfma_f32_16x16x32_bf16 v[64:67], v[174:177], v[210:213], v[64:67]
	v_mfma_f32_16x16x32_bf16 v[120:123], v[170:173], v[186:189], v[120:123]
	v_mfma_f32_16x16x32_bf16 v[112:115], v[178:181], v[186:189], v[112:115]
	v_mfma_f32_16x16x32_bf16 v[104:107], v[170:173], v[194:197], v[104:107]
	v_mfma_f32_16x16x32_bf16 v[96:99], v[178:181], v[194:197], v[96:99]
	v_mfma_f32_16x16x32_bf16 v[88:91], v[170:173], v[202:205], v[88:91]
	v_mfma_f32_16x16x32_bf16 v[80:83], v[178:181], v[202:205], v[80:83]
	v_mfma_f32_16x16x32_bf16 v[72:75], v[170:173], v[214:217], v[72:75]
	v_mfma_f32_16x16x32_bf16 v[64:67], v[178:181], v[214:217], v[64:67]
	s_barrier
	s_add_i32 s26, s47, s9
	v_lshl_add_u64 v[206:207], v[206:207], 0, s[2:3]
	s_mov_b32 m0, s26
	ds_read_b128 v[182:185], v153 offset:49152
	ds_read_b128 v[186:189], v153 offset:50176
	ds_read_b128 v[190:193], v153 offset:51200
	ds_read_b128 v[194:197], v153 offset:52224
	ds_read_b128 v[198:201], v153 offset:53248
	ds_read_b128 v[202:205], v153 offset:54272
	ds_read_b128 v[210:213], v153 offset:55296
	ds_read_b128 v[214:217], v153 offset:56320
	global_load_lds_dwordx4 v[206:207], off
	s_add_i32 m0, s26, 0x2000
	s_add_u32 s24, s24, 0x40080
	v_lshl_add_u64 v[206:207], v[218:219], 0, s[2:3]
	s_addc_u32 s25, s25, 0
	s_add_i32 s26, s48, s9
	global_load_lds_dwordx4 v[206:207], off
	v_lshl_add_u64 v[206:207], s[24:25], 0, v[132:133]
	s_mov_b32 m0, s26
	s_nop 0
	global_load_lds_dwordx4 v[206:207], off
	v_lshl_add_u64 v[206:207], s[24:25], 0, v[128:129]
	s_add_i32 m0, s26, 0x2000
	s_nop 0
	global_load_lds_dwordx4 v[206:207], off
	v_lshl_add_u64 v[206:207], v[220:221], 0, s[2:3]
	s_mov_b32 m0, s35
	s_nop 0
	global_load_lds_dwordx4 v[206:207], off
	v_lshl_add_u64 v[206:207], v[222:223], 0, s[2:3]
	s_mov_b32 m0, s36
	s_nop 0
	global_load_lds_dwordx4 v[206:207], off
	s_waitcnt vmcnt(8)
	s_waitcnt lgkmcnt(0)
	s_barrier
	s_waitcnt lgkmcnt(0)
	v_mfma_f32_16x16x32_bf16 v[60:63], v[144:147], v[182:185], v[60:63]
	v_mfma_f32_16x16x32_bf16 v[52:55], v[158:161], v[182:185], v[52:55]
	v_mfma_f32_16x16x32_bf16 v[44:47], v[144:147], v[190:193], v[44:47]
	v_mfma_f32_16x16x32_bf16 v[36:39], v[158:161], v[190:193], v[36:39]
	v_mfma_f32_16x16x32_bf16 v[28:31], v[144:147], v[198:201], v[28:31]
	v_mfma_f32_16x16x32_bf16 v[20:23], v[158:161], v[198:201], v[20:23]
	v_mfma_f32_16x16x32_bf16 v[12:15], v[144:147], v[210:213], v[12:15]
	v_mfma_f32_16x16x32_bf16 v[4:7], v[158:161], v[210:213], v[4:7]
	v_mfma_f32_16x16x32_bf16 v[60:63], v[154:157], v[186:189], v[60:63]
	v_mfma_f32_16x16x32_bf16 v[52:55], v[162:165], v[186:189], v[52:55]
	v_mfma_f32_16x16x32_bf16 v[44:47], v[154:157], v[194:197], v[44:47]
	v_mfma_f32_16x16x32_bf16 v[36:39], v[162:165], v[194:197], v[36:39]
	v_mfma_f32_16x16x32_bf16 v[28:31], v[154:157], v[202:205], v[28:31]
	v_mfma_f32_16x16x32_bf16 v[20:23], v[162:165], v[202:205], v[20:23]
	v_mfma_f32_16x16x32_bf16 v[12:15], v[154:157], v[214:217], v[12:15]
	v_mfma_f32_16x16x32_bf16 v[4:7], v[162:165], v[214:217], v[4:7]
	v_mfma_f32_16x16x32_bf16 v[56:59], v[166:169], v[182:185], v[56:59]
	v_mfma_f32_16x16x32_bf16 v[48:51], v[174:177], v[182:185], v[48:51]
	v_mfma_f32_16x16x32_bf16 v[40:43], v[166:169], v[190:193], v[40:43]
	v_mfma_f32_16x16x32_bf16 v[32:35], v[174:177], v[190:193], v[32:35]
	v_mfma_f32_16x16x32_bf16 v[24:27], v[166:169], v[198:201], v[24:27]
	v_mfma_f32_16x16x32_bf16 v[16:19], v[174:177], v[198:201], v[16:19]
	v_mfma_f32_16x16x32_bf16 v[8:11], v[166:169], v[210:213], v[8:11]
	v_mfma_f32_16x16x32_bf16 v[0:3], v[174:177], v[210:213], v[0:3]
	v_mfma_f32_16x16x32_bf16 v[56:59], v[170:173], v[186:189], v[56:59]
	v_mfma_f32_16x16x32_bf16 v[48:51], v[178:181], v[186:189], v[48:51]
	v_mfma_f32_16x16x32_bf16 v[40:43], v[170:173], v[194:197], v[40:43]
	v_mfma_f32_16x16x32_bf16 v[32:35], v[178:181], v[194:197], v[32:35]
	v_mfma_f32_16x16x32_bf16 v[24:27], v[170:173], v[202:205], v[24:27]
	v_mfma_f32_16x16x32_bf16 v[16:19], v[178:181], v[202:205], v[16:19]
	v_mfma_f32_16x16x32_bf16 v[8:11], v[170:173], v[214:217], v[8:11]
	v_mfma_f32_16x16x32_bf16 v[0:3], v[178:181], v[214:217], v[0:3]
	s_barrier
	s_add_i32 s46, s46, 2
	s_add_u32 s22, s22, 0x100
	s_addc_u32 s23, s23, 0
	s_add_u32 s44, s44, 0x100
	s_addc_u32 s45, s45, 0
	s_cmp_gt_u32 s46, 13
	s_cbranch_scc0 .LBB0_1912

; #define PG8_STAGE(bufoff, gbase, voff) do { _Pragma("unroll") for (int _i = 0; _i < 2; ++_i) \
;         __builtin_amdgcn_global_load_lds((const unsigned*)((const char*)(gbase) + (voff)[_i]), (PG8_LAS unsigned*)(lds + (bufoff) + ldsw + _i * 8192), 16, 0, 0); } while (0)
; #define PG8_LDA(dst, b, h) do { _Pragma("unroll") for (int m = 0; m < 4; ++m) _Pragma("unroll") for (int k = 0; k < 2; ++k) dst[m][k] = *(const PG8_LAS bf16x8*)(lds + PG8_SA(b, h) + aoff + m * 2048 + k * 1024); } while (0)
; #define PG8_LDB(dst, b, h) do { _Pragma("unroll") for (int n = 0; n < 2; ++n) _Pragma("unroll") for (int k = 0; k < 2; ++k) dst[n][k] = *(const PG8_LAS bf16x8*)(lds + PG8_SB(b, h) + boff + n * 2048 + k * 1024); } while (0)
; #define PG8_MMA(ai, bj, At, Bt) do { __builtin_amdgcn_s_setprio(1); _Pragma("unroll") for (int m = 0; m < 4; ++m) _Pragma("unroll") for (int n = 0; n < 2; ++n) _Pragma("unroll") for (int k = 0; k < 2; ++k) \
;         acc[ai][bj][m][n] = __builtin_amdgcn_mfma_f32_16x16x32_bf16(Bt[n][k], At[m][k], acc[ai][bj][m][n], 0, 0, 0); __builtin_amdgcn_s_setprio(0); } while (0)
; #define PG8_WAIT_V(n) asm volatile("s_waitcnt vmcnt(" #n ")" ::: "memory")
; #define PG8_WAIT_L(n) asm volatile("s_waitcnt lgkmcnt(" #n ")" ::: "memory")
; #define PG8_BAR __builtin_amdgcn_s_barrier()
; #define PG8_SCHED __builtin_amdgcn_sched_barrier(0)
; template <class Epi, class Sched, bool ALIGN_EPI = false, bool SP2 = false>
; __device__ __forceinline__ void gemm_phase(PG8_LAS unsigned char* lds, const Gemm g, const Sched& S, const Epi& E, const int wid) {
;     ...
;             PG8_LDB(B0, 0, 0); PG8_LDB(B1, 0, 1); PG8_SCHED; PG8_LDA(At, 0, 0); PG8_STAGE(PG8_SA(1, 1), a1 + hstep, voffA);
;             PG8_WAIT_V(8); PG8_WAIT_L(0); PG8_BAR; PG8_MMA(0, 0, At, B0); PG8_MMA(0, 1, At, B1); PG8_BAR; PG8_SCHED;
;             PG8_LDA(At, 0, 1); PG8_STAGE(PG8_SB(0, 0), b2, voffB); PG8_STAGE(PG8_SB(0, 1), b2 + hstep, voffB); PG8_STAGE(PG8_SA(0, 0), a2, voffA);
;             PG8_WAIT_V(8); PG8_WAIT_L(0); PG8_BAR; PG8_MMA(1, 0, At, B0); PG8_MMA(1, 1, At, B1); PG8_BAR; PG8_SCHED;
.LBB0_2460:
	v_add_u32_e32 v151, s35, v149
	ds_read_b128 v[152:155], v151
	ds_read_b128 v[156:159], v151 offset:1024
	ds_read_b128 v[160:163], v151 offset:2048
	ds_read_b128 v[168:171], v151 offset:3072
	v_add_u32_e32 v151, s36, v149
	s_add_u32 s16, s8, s14
	ds_read_b128 v[172:175], v151
	ds_read_b128 v[178:181], v151 offset:1024
	ds_read_b128 v[182:185], v151 offset:2048
	ds_read_b128 v[186:189], v151 offset:3072
	s_addc_u32 s17, s9, s15
	s_add_u32 s16, s16, 0x100
	s_addc_u32 s17, s17, 0
	s_add_u32 s43, s40, s14
	s_addc_u32 s44, s41, s15
	s_cmpk_eq_i32 s14, 0x1500
	s_cselect_b32 s19, s13, s17
	s_cselect_b32 s18, s12, s16
	s_cselect_b32 s17, s5, s44
	s_cselect_b32 s16, s4, s43
	v_lshl_add_u64 v[222:223], v[144:145], 0, s[14:15]
	s_add_i32 m0, s26, 0xc000
	ds_read_b128 v[190:193], v150
	ds_read_b128 v[194:197], v150 offset:1024
	ds_read_b128 v[198:201], v150 offset:2048
	ds_read_b128 v[202:205], v150 offset:3072
	ds_read_b128 v[206:209], v150 offset:4096
	ds_read_b128 v[210:213], v150 offset:5120
	ds_read_b128 v[214:217], v150 offset:6144
	ds_read_b128 v[218:221], v150 offset:7168
	global_load_lds_dwordx4 v[222:223], off
	v_lshl_add_u64 v[222:223], v[146:147], 0, s[14:15]
	s_add_i32 m0, s26, 0xe000
	s_nop 0
	global_load_lds_dwordx4 v[222:223], off
	s_waitcnt vmcnt(8)
	s_waitcnt lgkmcnt(0)
	s_barrier
	s_waitcnt lgkmcnt(0)
	v_mfma_f32_16x16x32_bf16 v[124:127], v[152:155], v[190:193], v[124:127]
	v_mfma_f32_16x16x32_bf16 v[120:123], v[160:163], v[190:193], v[120:123]
	v_mfma_f32_16x16x32_bf16 v[112:115], v[152:155], v[198:201], v[112:115]
	v_mfma_f32_16x16x32_bf16 v[104:107], v[160:163], v[198:201], v[104:107]
	v_mfma_f32_16x16x32_bf16 v[96:99], v[152:155], v[206:209], v[96:99]
	v_mfma_f32_16x16x32_bf16 v[88:91], v[160:163], v[206:209], v[88:91]
	v_mfma_f32_16x16x32_bf16 v[80:83], v[152:155], v[214:217], v[80:83]
	v_mfma_f32_16x16x32_bf16 v[72:75], v[160:163], v[214:217], v[72:75]
	v_mfma_f32_16x16x32_bf16 v[124:127], v[156:159], v[194:197], v[124:127]
	v_mfma_f32_16x16x32_bf16 v[120:123], v[168:171], v[194:197], v[120:123]
	v_mfma_f32_16x16x32_bf16 v[112:115], v[156:159], v[202:205], v[112:115]
	v_mfma_f32_16x16x32_bf16 v[104:107], v[168:171], v[202:205], v[104:107]
	v_mfma_f32_16x16x32_bf16 v[96:99], v[156:159], v[210:213], v[96:99]
	v_mfma_f32_16x16x32_bf16 v[88:91], v[168:171], v[210:213], v[88:91]
	v_mfma_f32_16x16x32_bf16 v[80:83], v[156:159], v[218:221], v[80:83]
	v_mfma_f32_16x16x32_bf16 v[72:75], v[168:171], v[218:221], v[72:75]
	v_mfma_f32_16x16x32_bf16 v[116:119], v[172:175], v[190:193], v[116:119]
	v_mfma_f32_16x16x32_bf16 v[108:111], v[182:185], v[190:193], v[108:111]
	v_mfma_f32_16x16x32_bf16 v[100:103], v[172:175], v[198:201], v[100:103]
	v_mfma_f32_16x16x32_bf16 v[92:95], v[182:185], v[198:201], v[92:95]
	v_mfma_f32_16x16x32_bf16 v[84:87], v[172:175], v[206:209], v[84:87]
	v_mfma_f32_16x16x32_bf16 v[76:79], v[182:185], v[206:209], v[76:79]
	v_mfma_f32_16x16x32_bf16 v[68:71], v[172:175], v[214:217], v[68:71]
	v_mfma_f32_16x16x32_bf16 v[64:67], v[182:185], v[214:217], v[64:67]
	v_mfma_f32_16x16x32_bf16 v[116:119], v[178:181], v[194:197], v[116:119]
	v_mfma_f32_16x16x32_bf16 v[108:111], v[186:189], v[194:197], v[108:111]
	v_mfma_f32_16x16x32_bf16 v[100:103], v[178:181], v[202:205], v[100:103]
	v_mfma_f32_16x16x32_bf16 v[92:95], v[186:189], v[202:205], v[92:95]
	v_mfma_f32_16x16x32_bf16 v[84:87], v[178:181], v[210:213], v[84:87]
	v_mfma_f32_16x16x32_bf16 v[76:79], v[186:189], v[210:213], v[76:79]
	v_mfma_f32_16x16x32_bf16 v[68:71], v[178:181], v[218:221], v[68:71]
	v_mfma_f32_16x16x32_bf16 v[64:67], v[186:189], v[218:221], v[64:67]
	s_barrier
	s_add_i32 s43, s35, s24
	v_lshl_add_u64 v[222:223], s[16:17], 0, v[130:131]
	s_mov_b32 m0, s43
	ds_read_b128 v[190:193], v150 offset:16384
	ds_read_b128 v[194:197], v150 offset:17408
	ds_read_b128 v[198:201], v150 offset:18432
	ds_read_b128 v[202:205], v150 offset:19456
	ds_read_b128 v[206:209], v150 offset:20480
	ds_read_b128 v[210:213], v150 offset:21504
	ds_read_b128 v[214:217], v150 offset:22528
	ds_read_b128 v[218:221], v150 offset:23552
	global_load_lds_dwordx4 v[222:223], off
	s_add_i32 m0, s43, 0x2000
	s_add_u32 s44, s16, 0xb0000
	v_lshl_add_u64 v[224:225], s[16:17], 0, v[134:135]
	s_addc_u32 s45, s17, 0
	s_add_i32 s43, s36, s24
	global_load_lds_dwordx4 v[224:225], off
	v_lshl_add_u64 v[226:227], s[44:45], 0, v[130:131]
	s_mov_b32 m0, s43
	v_lshl_add_u64 v[228:229], s[18:19], 0, v[132:133]
	global_load_lds_dwordx4 v[226:227], off
	v_lshl_add_u64 v[226:227], s[44:45], 0, v[134:135]
	s_add_i32 m0, s43, 0x2000
	s_nop 0
	global_load_lds_dwordx4 v[226:227], off
	v_lshl_add_u64 v[226:227], s[18:19], 0, v[128:129]
	s_mov_b32 m0, s26
	s_nop 0
	global_load_lds_dwordx4 v[226:227], off
	s_mov_b32 m0, s27
	s_nop 0
	global_load_lds_dwordx4 v[228:229], off
	s_waitcnt vmcnt(8)
	s_waitcnt lgkmcnt(0)
	s_barrier
; #define PG8_STAGE(bufoff, gbase, voff) do { _Pragma("unroll") for (int _i = 0; _i < 2; ++_i) \
;         __builtin_amdgcn_global_load_lds((const unsigned*)((const char*)(gbase) + (voff)[_i]), (PG8_LAS unsigned*)(lds + (bufoff) + ldsw + _i * 8192), 16, 0, 0); } while (0)
; #define PG8_LDA(dst, b, h) do { _Pragma("unroll") for (int m = 0; m < 4; ++m) _Pragma("unroll") for (int k = 0; k < 2; ++k) dst[m][k] = *(const PG8_LAS bf16x8*)(lds + PG8_SA(b, h) + aoff + m * 2048 + k * 1024); } while (0)
; #define PG8_LDB(dst, b, h) do { _Pragma("unroll") for (int n = 0; n < 2; ++n) _Pragma("unroll") for (int k = 0; k < 2; ++k) dst[n][k] = *(const PG8_LAS bf16x8*)(lds + PG8_SB(b, h) + boff + n * 2048 + k * 1024); } while (0)
; #define PG8_MMA(ai, bj, At, Bt) do { __builtin_amdgcn_s_setprio(1); _Pragma("unroll") for (int m = 0; m < 4; ++m) _Pragma("unroll") for (int n = 0; n < 2; ++n) _Pragma("unroll") for (int k = 0; k < 2; ++k) \
;         acc[ai][bj][m][n] = __builtin_amdgcn_mfma_f32_16x16x32_bf16(Bt[n][k], At[m][k], acc[ai][bj][m][n], 0, 0, 0); __builtin_amdgcn_s_setprio(0); } while (0)
; #define PG8_WAIT_V(n) asm volatile("s_waitcnt vmcnt(" #n ")" ::: "memory")
; #define PG8_WAIT_L(n) asm volatile("s_waitcnt lgkmcnt(" #n ")" ::: "memory")
; #define PG8_BAR __builtin_amdgcn_s_barrier()
; #define PG8_SCHED __builtin_amdgcn_sched_barrier(0)
; template <class Epi, class Sched, bool ALIGN_EPI = false, bool SP2 = false>
; __device__ __forceinline__ void gemm_phase(PG8_LAS unsigned char* lds, const Gemm g, const Sched& S, const Epi& E, const int wid) {
;     ...
;             PG8_LDA(At, 0, 1); PG8_STAGE(PG8_SB(0, 0), b2, voffB); PG8_STAGE(PG8_SB(0, 1), b2 + hstep, voffB); PG8_STAGE(PG8_SA(0, 0), a2, voffA);
;             PG8_WAIT_V(8); PG8_WAIT_L(0); PG8_BAR; PG8_MMA(1, 0, At, B0); PG8_MMA(1, 1, At, B1); PG8_BAR; PG8_SCHED;
;             PG8_LDB(B0, 1, 0); PG8_LDB(B1, 1, 1); PG8_SCHED; PG8_LDA(At, 1, 0); PG8_STAGE(PG8_SA(0, 1), a2 + hstep, voffA);
;             PG8_WAIT_V(8); PG8_WAIT_L(0); PG8_BAR; PG8_MMA(0, 0, At, B0); PG8_MMA(0, 1, At, B1); PG8_BAR; PG8_SCHED;
;             PG8_LDA(At, 1, 1); PG8_STAGE(PG8_SB(1, 0), b3, voffB); PG8_STAGE(PG8_SB(1, 1), b3 + hstep, voffB); PG8_STAGE(PG8_SA(1, 0), a3, voffA);
	s_waitcnt lgkmcnt(0)
	v_mfma_f32_16x16x32_bf16 v[60:63], v[152:155], v[190:193], v[60:63]
	v_mfma_f32_16x16x32_bf16 v[56:59], v[160:163], v[190:193], v[56:59]
	v_mfma_f32_16x16x32_bf16 v[44:47], v[152:155], v[198:201], v[44:47]
	v_mfma_f32_16x16x32_bf16 v[40:43], v[160:163], v[198:201], v[40:43]
	v_mfma_f32_16x16x32_bf16 v[28:31], v[152:155], v[206:209], v[28:31]
	v_mfma_f32_16x16x32_bf16 v[24:27], v[160:163], v[206:209], v[24:27]
	v_mfma_f32_16x16x32_bf16 v[12:15], v[152:155], v[214:217], v[12:15]
	v_mfma_f32_16x16x32_bf16 v[8:11], v[160:163], v[214:217], v[8:11]
	v_mfma_f32_16x16x32_bf16 v[60:63], v[156:159], v[194:197], v[60:63]
	v_mfma_f32_16x16x32_bf16 v[56:59], v[168:171], v[194:197], v[56:59]
	v_mfma_f32_16x16x32_bf16 v[44:47], v[156:159], v[202:205], v[44:47]
	v_mfma_f32_16x16x32_bf16 v[40:43], v[168:171], v[202:205], v[40:43]
	v_mfma_f32_16x16x32_bf16 v[28:31], v[156:159], v[210:213], v[28:31]
	v_mfma_f32_16x16x32_bf16 v[24:27], v[168:171], v[210:213], v[24:27]
	v_mfma_f32_16x16x32_bf16 v[12:15], v[156:159], v[218:221], v[12:15]
	v_mfma_f32_16x16x32_bf16 v[8:11], v[168:171], v[218:221], v[8:11]
	v_mfma_f32_16x16x32_bf16 v[52:55], v[172:175], v[190:193], v[52:55]
	v_mfma_f32_16x16x32_bf16 v[48:51], v[182:185], v[190:193], v[48:51]
	v_mfma_f32_16x16x32_bf16 v[36:39], v[172:175], v[198:201], v[36:39]
	v_mfma_f32_16x16x32_bf16 v[32:35], v[182:185], v[198:201], v[32:35]
	v_mfma_f32_16x16x32_bf16 v[20:23], v[172:175], v[206:209], v[20:23]
	v_mfma_f32_16x16x32_bf16 v[16:19], v[182:185], v[206:209], v[16:19]
	v_mfma_f32_16x16x32_bf16 v[4:7], v[172:175], v[214:217], v[4:7]
	v_mfma_f32_16x16x32_bf16 v[0:3], v[182:185], v[214:217], v[0:3]
	v_mfma_f32_16x16x32_bf16 v[52:55], v[178:181], v[194:197], v[52:55]
	v_mfma_f32_16x16x32_bf16 v[48:51], v[186:189], v[194:197], v[48:51]
	v_mfma_f32_16x16x32_bf16 v[36:39], v[178:181], v[202:205], v[36:39]
	v_mfma_f32_16x16x32_bf16 v[32:35], v[186:189], v[202:205], v[32:35]
	v_mfma_f32_16x16x32_bf16 v[20:23], v[178:181], v[210:213], v[20:23]
	v_mfma_f32_16x16x32_bf16 v[16:19], v[186:189], v[210:213], v[16:19]
	v_mfma_f32_16x16x32_bf16 v[4:7], v[178:181], v[218:221], v[4:7]
	v_mfma_f32_16x16x32_bf16 v[0:3], v[186:189], v[218:221], v[0:3]
	s_barrier
	s_add_i32 s43, 0, 0x18000
	v_add_u32_e32 v151, s43, v149
	s_add_i32 s44, 0, 0x1c000
	ds_read_b128 v[152:155], v151
	ds_read_b128 v[156:159], v151 offset:1024
	ds_read_b128 v[160:163], v151 offset:2048
	ds_read_b128 v[168:171], v151 offset:3072
	v_add_u32_e32 v151, s44, v149
	ds_read_b128 v[172:175], v151
	ds_read_b128 v[178:181], v151 offset:1024
	ds_read_b128 v[182:185], v151 offset:2048
	ds_read_b128 v[186:189], v151 offset:3072
	s_add_u32 s18, s18, 0xb0000
	s_addc_u32 s19, s19, 0
	s_mov_b32 m0, s28
	v_lshl_add_u64 v[230:231], s[18:19], 0, v[128:129]
	ds_read_b128 v[190:193], v150 offset:32768
	ds_read_b128 v[194:197], v150 offset:33792
	ds_read_b128 v[198:201], v150 offset:34816
	ds_read_b128 v[202:205], v150 offset:35840
	ds_read_b128 v[206:209], v150 offset:36864
	ds_read_b128 v[210:213], v150 offset:37888
	ds_read_b128 v[214:217], v150 offset:38912
	ds_read_b128 v[218:221], v150 offset:39936
	global_load_lds_dwordx4 v[230:231], off
	v_lshl_add_u64 v[230:231], s[18:19], 0, v[132:133]
	s_mov_b32 m0, s29
	s_nop 0
	global_load_lds_dwordx4 v[230:231], off
	s_waitcnt vmcnt(8)
	s_waitcnt lgkmcnt(0)
	s_barrier
	s_waitcnt lgkmcnt(0)
	v_mfma_f32_16x16x32_bf16 v[124:127], v[152:155], v[190:193], v[124:127]
	v_mfma_f32_16x16x32_bf16 v[120:123], v[160:163], v[190:193], v[120:123]
	v_mfma_f32_16x16x32_bf16 v[112:115], v[152:155], v[198:201], v[112:115]
	v_mfma_f32_16x16x32_bf16 v[104:107], v[160:163], v[198:201], v[104:107]
	v_mfma_f32_16x16x32_bf16 v[96:99], v[152:155], v[206:209], v[96:99]
	v_mfma_f32_16x16x32_bf16 v[88:91], v[160:163], v[206:209], v[88:91]
	v_mfma_f32_16x16x32_bf16 v[80:83], v[152:155], v[214:217], v[80:83]
	v_mfma_f32_16x16x32_bf16 v[72:75], v[160:163], v[214:217], v[72:75]
	v_mfma_f32_16x16x32_bf16 v[124:127], v[156:159], v[194:197], v[124:127]
	v_mfma_f32_16x16x32_bf16 v[120:123], v[168:171], v[194:197], v[120:123]
	v_mfma_f32_16x16x32_bf16 v[112:115], v[156:159], v[202:205], v[112:115]
	v_mfma_f32_16x16x32_bf16 v[104:107], v[168:171], v[202:205], v[104:107]
	v_mfma_f32_16x16x32_bf16 v[96:99], v[156:159], v[210:213], v[96:99]
	v_mfma_f32_16x16x32_bf16 v[88:91], v[168:171], v[210:213], v[88:91]
	v_mfma_f32_16x16x32_bf16 v[80:83], v[156:159], v[218:221], v[80:83]
	v_mfma_f32_16x16x32_bf16 v[72:75], v[168:171], v[218:221], v[72:75]
	v_mfma_f32_16x16x32_bf16 v[116:119], v[172:175], v[190:193], v[116:119]
	v_mfma_f32_16x16x32_bf16 v[108:111], v[182:185], v[190:193], v[108:111]
	v_mfma_f32_16x16x32_bf16 v[100:103], v[172:175], v[198:201], v[100:103]
	v_mfma_f32_16x16x32_bf16 v[92:95], v[182:185], v[198:201], v[92:95]
	v_mfma_f32_16x16x32_bf16 v[84:87], v[172:175], v[206:209], v[84:87]
	v_mfma_f32_16x16x32_bf16 v[76:79], v[182:185], v[206:209], v[76:79]
	v_mfma_f32_16x16x32_bf16 v[68:71], v[172:175], v[214:217], v[68:71]
	v_mfma_f32_16x16x32_bf16 v[64:67], v[182:185], v[214:217], v[64:67]
	v_mfma_f32_16x16x32_bf16 v[116:119], v[178:181], v[194:197], v[116:119]
	v_mfma_f32_16x16x32_bf16 v[108:111], v[186:189], v[194:197], v[108:111]
	v_mfma_f32_16x16x32_bf16 v[100:103], v[178:181], v[202:205], v[100:103]
	v_mfma_f32_16x16x32_bf16 v[92:95], v[186:189], v[202:205], v[92:95]
	v_mfma_f32_16x16x32_bf16 v[84:87], v[178:181], v[210:213], v[84:87]
	v_mfma_f32_16x16x32_bf16 v[76:79], v[186:189], v[210:213], v[76:79]
	v_mfma_f32_16x16x32_bf16 v[68:71], v[178:181], v[218:221], v[68:71]
	v_mfma_f32_16x16x32_bf16 v[64:67], v[186:189], v[218:221], v[64:67]
	s_barrier
; #define PG8_STAGE(bufoff, gbase, voff) do { _Pragma("unroll") for (int _i = 0; _i < 2; ++_i) \
;         __builtin_amdgcn_global_load_lds((const unsigned*)((const char*)(gbase) + (voff)[_i]), (PG8_LAS unsigned*)(lds + (bufoff) + ldsw + _i * 8192), 16, 0, 0); } while (0)
; #define PG8_LDA(dst, b, h) do { _Pragma("unroll") for (int m = 0; m < 4; ++m) _Pragma("unroll") for (int k = 0; k < 2; ++k) dst[m][k] = *(const PG8_LAS bf16x8*)(lds + PG8_SA(b, h) + aoff + m * 2048 + k * 1024); } while (0)
; #define PG8_MMA(ai, bj, At, Bt) do { __builtin_amdgcn_s_setprio(1); _Pragma("unroll") for (int m = 0; m < 4; ++m) _Pragma("unroll") for (int n = 0; n < 2; ++n) _Pragma("unroll") for (int k = 0; k < 2; ++k) \
;         acc[ai][bj][m][n] = __builtin_amdgcn_mfma_f32_16x16x32_bf16(Bt[n][k], At[m][k], acc[ai][bj][m][n], 0, 0, 0); __builtin_amdgcn_s_setprio(0); } while (0)
; #define PG8_WAIT_V(n) asm volatile("s_waitcnt vmcnt(" #n ")" ::: "memory")
; #define PG8_WAIT_L(n) asm volatile("s_waitcnt lgkmcnt(" #n ")" ::: "memory")
; #define PG8_BAR __builtin_amdgcn_s_barrier()
; #define PG8_SCHED __builtin_amdgcn_sched_barrier(0)
; template <class Epi, class Sched, bool ALIGN_EPI = false, bool SP2 = false>
; __device__ __forceinline__ void gemm_phase(PG8_LAS unsigned char* lds, const Gemm g, const Sched& S, const Epi& E, const int wid) {
;     ...
;             PG8_LDA(At, 1, 1); PG8_STAGE(PG8_SB(1, 0), b3, voffB); PG8_STAGE(PG8_SB(1, 1), b3 + hstep, voffB); PG8_STAGE(PG8_SA(1, 0), a3, voffA);
;             PG8_WAIT_V(8); PG8_WAIT_L(0); PG8_BAR; PG8_MMA(1, 0, At, B0); PG8_MMA(1, 1, At, B1); PG8_BAR; PG8_SCHED;
;     ...
;         if (!has_next) break;
; #pragma unroll
;         for (int a = 0; a < 2; ++a)
; #pragma unroll
;             for (int b = 0; b < 2; ++b)
; #pragma unroll
;                 for (int m = 0; m < 4; ++m)
; #pragma unroll
;                     for (int n = 0; n < 2; ++n) acc[a][b][m][n] = (f32x4){0.f, 0.f, 0.f, 0.f};
;         cur = nxt; cA = nA; cB = nB; ++ui;
	s_add_i32 s18, s43, s24
	v_lshl_add_u64 v[222:223], v[222:223], 0, s[10:11]
	s_mov_b32 m0, s18
	ds_read_b128 v[190:193], v150 offset:49152
	ds_read_b128 v[194:197], v150 offset:50176
	ds_read_b128 v[198:201], v150 offset:51200
	ds_read_b128 v[202:205], v150 offset:52224
	ds_read_b128 v[206:209], v150 offset:53248
	ds_read_b128 v[210:213], v150 offset:54272
	ds_read_b128 v[214:217], v150 offset:55296
	ds_read_b128 v[218:221], v150 offset:56320
	global_load_lds_dwordx4 v[222:223], off
	s_add_i32 m0, s18, 0x2000
	s_add_u32 s16, s16, 0xb0080
	v_lshl_add_u64 v[222:223], v[224:225], 0, s[10:11]
	s_addc_u32 s17, s17, 0
	s_add_i32 s18, s44, s24
	global_load_lds_dwordx4 v[222:223], off
	v_lshl_add_u64 v[222:223], s[16:17], 0, v[130:131]
	s_mov_b32 m0, s18
	s_nop 0
	global_load_lds_dwordx4 v[222:223], off
	v_lshl_add_u64 v[222:223], s[16:17], 0, v[134:135]
	s_add_i32 m0, s18, 0x2000
	s_nop 0
	global_load_lds_dwordx4 v[222:223], off
	v_lshl_add_u64 v[222:223], v[226:227], 0, s[10:11]
	s_mov_b32 m0, s31
	s_nop 0
	global_load_lds_dwordx4 v[222:223], off
	v_lshl_add_u64 v[222:223], v[228:229], 0, s[10:11]
	s_mov_b32 m0, s33
	s_nop 0
	global_load_lds_dwordx4 v[222:223], off
	s_waitcnt vmcnt(8)
	s_waitcnt lgkmcnt(0)
	s_barrier
	s_waitcnt lgkmcnt(0)
	v_mfma_f32_16x16x32_bf16 v[60:63], v[152:155], v[190:193], v[60:63]
	v_mfma_f32_16x16x32_bf16 v[56:59], v[160:163], v[190:193], v[56:59]
	v_mfma_f32_16x16x32_bf16 v[44:47], v[152:155], v[198:201], v[44:47]
	v_mfma_f32_16x16x32_bf16 v[40:43], v[160:163], v[198:201], v[40:43]
	v_mfma_f32_16x16x32_bf16 v[28:31], v[152:155], v[206:209], v[28:31]
	v_mfma_f32_16x16x32_bf16 v[24:27], v[160:163], v[206:209], v[24:27]
	v_mfma_f32_16x16x32_bf16 v[12:15], v[152:155], v[214:217], v[12:15]
	v_mfma_f32_16x16x32_bf16 v[8:11], v[160:163], v[214:217], v[8:11]
	v_mfma_f32_16x16x32_bf16 v[60:63], v[156:159], v[194:197], v[60:63]
	v_mfma_f32_16x16x32_bf16 v[56:59], v[168:171], v[194:197], v[56:59]
	v_mfma_f32_16x16x32_bf16 v[44:47], v[156:159], v[202:205], v[44:47]
	v_mfma_f32_16x16x32_bf16 v[40:43], v[168:171], v[202:205], v[40:43]
	v_mfma_f32_16x16x32_bf16 v[28:31], v[156:159], v[210:213], v[28:31]
	v_mfma_f32_16x16x32_bf16 v[24:27], v[168:171], v[210:213], v[24:27]
	v_mfma_f32_16x16x32_bf16 v[12:15], v[156:159], v[218:221], v[12:15]
	v_mfma_f32_16x16x32_bf16 v[8:11], v[168:171], v[218:221], v[8:11]
	v_mfma_f32_16x16x32_bf16 v[52:55], v[172:175], v[190:193], v[52:55]
	v_mfma_f32_16x16x32_bf16 v[48:51], v[182:185], v[190:193], v[48:51]
	v_mfma_f32_16x16x32_bf16 v[36:39], v[172:175], v[198:201], v[36:39]
	v_mfma_f32_16x16x32_bf16 v[32:35], v[182:185], v[198:201], v[32:35]
	v_mfma_f32_16x16x32_bf16 v[20:23], v[172:175], v[206:209], v[20:23]
	v_mfma_f32_16x16x32_bf16 v[16:19], v[182:185], v[206:209], v[16:19]
	v_mfma_f32_16x16x32_bf16 v[4:7], v[172:175], v[214:217], v[4:7]
	v_mfma_f32_16x16x32_bf16 v[0:3], v[182:185], v[214:217], v[0:3]
	v_mfma_f32_16x16x32_bf16 v[52:55], v[178:181], v[194:197], v[52:55]
	v_mfma_f32_16x16x32_bf16 v[48:51], v[186:189], v[194:197], v[48:51]
	v_mfma_f32_16x16x32_bf16 v[36:39], v[178:181], v[202:205], v[36:39]
	v_mfma_f32_16x16x32_bf16 v[32:35], v[186:189], v[202:205], v[32:35]
	v_mfma_f32_16x16x32_bf16 v[20:23], v[178:181], v[210:213], v[20:23]
	v_mfma_f32_16x16x32_bf16 v[16:19], v[186:189], v[210:213], v[16:19]
	v_mfma_f32_16x16x32_bf16 v[4:7], v[178:181], v[218:221], v[4:7]
	v_mfma_f32_16x16x32_bf16 v[0:3], v[186:189], v[218:221], v[0:3]
	s_barrier
	s_add_i32 s42, s42, 2
	s_add_u32 s14, s14, 0x100
	s_addc_u32 s15, s15, 0
	s_cmp_gt_u32 s42, 41
	s_cbranch_scc0 .LBB0_2460
	s_add_u32 s14, s40, 0xffffff00
	s_addc_u32 s15, s41, -1
	s_and_b64 vcc, exec, s[6:7]
	s_cbranch_vccnz .LBB0_2447
	v_mov_b32_e32 v0, 0
	s_mov_b32 s2, s37
	s_mov_b32 s20, s38
	s_mov_b64 s[8:9], s[12:13]
	s_mov_b32 s34, s39
	v_mov_b32_e32 v1, v0
	v_mov_b32_e32 v2, v0
	v_mov_b32_e32 v3, v0
	v_mov_b32_e32 v4, v0
	v_mov_b32_e32 v5, v0
	v_mov_b32_e32 v6, v0
	v_mov_b32_e32 v7, v0
	v_mov_b32_e32 v16, v0
	v_mov_b32_e32 v17, v0
	v_mov_b32_e32 v18, v0
	v_mov_b32_e32 v19, v0
	v_mov_b32_e32 v20, v0
	v_mov_b32_e32 v21, v0
	v_mov_b32_e32 v22, v0
	v_mov_b32_e32 v23, v0
	v_mov_b32_e32 v32, v0
	v_mov_b32_e32 v33, v0
	v_mov_b32_e32 v34, v0
	v_mov_b32_e32 v35, v0
	v_mov_b32_e32 v36, v0
	v_mov_b32_e32 v37, v0
	v_mov_b32_e32 v38, v0
	v_mov_b32_e32 v39, v0
	v_mov_b32_e32 v48, v0
	v_mov_b32_e32 v49, v0
	v_mov_b32_e32 v50, v0
	v_mov_b32_e32 v51, v0
	v_mov_b32_e32 v52, v0
	v_mov_b32_e32 v53, v0
	v_mov_b32_e32 v54, v0
	v_mov_b32_e32 v55, v0
	v_mov_b32_e32 v8, v0
	v_mov_b32_e32 v9, v0
	v_mov_b32_e32 v10, v0
	v_mov_b32_e32 v11, v0
	v_mov_b32_e32 v12, v0
	v_mov_b32_e32 v13, v0
	v_mov_b32_e32 v14, v0
	v_mov_b32_e32 v15, v0
	v_mov_b32_e32 v24, v0
	v_mov_b32_e32 v25, v0
	v_mov_b32_e32 v26, v0
	v_mov_b32_e32 v27, v0
	v_mov_b32_e32 v28, v0
	v_mov_b32_e32 v29, v0
	v_mov_b32_e32 v30, v0
	v_mov_b32_e32 v31, v0
	v_mov_b32_e32 v40, v0
	v_mov_b32_e32 v41, v0
	v_mov_b32_e32 v42, v0
	v_mov_b32_e32 v43, v0
	v_mov_b32_e32 v44, v0
	v_mov_b32_e32 v45, v0
	v_mov_b32_e32 v46, v0
	v_mov_b32_e32 v47, v0
	v_mov_b32_e32 v56, v0
	v_mov_b32_e32 v57, v0
	v_mov_b32_e32 v58, v0
	v_mov_b32_e32 v59, v0
	v_mov_b32_e32 v60, v0
	v_mov_b32_e32 v61, v0
	v_mov_b32_e32 v62, v0
	v_mov_b32_e32 v63, v0
	v_mov_b32_e32 v64, v0
	v_mov_b32_e32 v65, v0
	v_mov_b32_e32 v66, v0
	v_mov_b32_e32 v67, v0
	v_mov_b32_e32 v68, v0
	v_mov_b32_e32 v69, v0
	v_mov_b32_e32 v70, v0
	v_mov_b32_e32 v71, v0
	v_mov_b32_e32 v76, v0
	v_mov_b32_e32 v77, v0
	v_mov_b32_e32 v78, v0
	v_mov_b32_e32 v79, v0
	v_mov_b32_e32 v84, v0
	v_mov_b32_e32 v85, v0
	v_mov_b32_e32 v86, v0
	v_mov_b32_e32 v87, v0
	v_mov_b32_e32 v92, v0
	v_mov_b32_e32 v93, v0
	v_mov_b32_e32 v94, v0
	v_mov_b32_e32 v95, v0
	v_mov_b32_e32 v100, v0
	v_mov_b32_e32 v101, v0
	v_mov_b32_e32 v102, v0
	v_mov_b32_e32 v103, v0
	v_mov_b32_e32 v108, v0
	v_mov_b32_e32 v109, v0
	v_mov_b32_e32 v110, v0
	v_mov_b32_e32 v111, v0
	v_mov_b32_e32 v116, v0
	v_mov_b32_e32 v117, v0
	v_mov_b32_e32 v118, v0
	v_mov_b32_e32 v119, v0
	v_mov_b32_e32 v72, v0
	v_mov_b32_e32 v73, v0
	v_mov_b32_e32 v74, v0
	v_mov_b32_e32 v75, v0
	v_mov_b32_e32 v80, v0
	v_mov_b32_e32 v81, v0
	v_mov_b32_e32 v82, v0
	v_mov_b32_e32 v83, v0
	v_mov_b32_e32 v88, v0
	v_mov_b32_e32 v89, v0
	v_mov_b32_e32 v90, v0
	v_mov_b32_e32 v91, v0
	v_mov_b32_e32 v96, v0
	v_mov_b32_e32 v97, v0
	v_mov_b32_e32 v98, v0
	v_mov_b32_e32 v99, v0
	v_mov_b32_e32 v104, v0
	v_mov_b32_e32 v105, v0
	v_mov_b32_e32 v106, v0
	v_mov_b32_e32 v107, v0
	v_mov_b32_e32 v112, v0
	v_mov_b32_e32 v113, v0
	v_mov_b32_e32 v114, v0
	v_mov_b32_e32 v115, v0
	v_mov_b32_e32 v120, v0
	v_mov_b32_e32 v121, v0
	v_mov_b32_e32 v122, v0
	v_mov_b32_e32 v123, v0
	v_mov_b32_e32 v124, v0
	v_mov_b32_e32 v125, v0
	v_mov_b32_e32 v126, v0
	v_mov_b32_e32 v127, v0
	s_andn2_b64 vcc, exec, s[0:1]
	s_cbranch_vccnz .LBB0_2448
